# GEMM loops: 64-bit VALU address adds replaced by SGPR-base saddr-form global_load_lds (16 VALU per K-loop body removed)
# speedup vs baseline: 1.0043x; 1.0043x over previous
; #define PG8_STAGE(bufoff, gbase, voff) do { _Pragma("unroll") for (int _i = 0; _i < 2; ++_i) \
;         __builtin_amdgcn_global_load_lds((const unsigned*)((const char*)(gbase) + (voff)[_i]), (LAS unsigned*)(lds + (bufoff) + ldsw + _i * 8192), 16, 0, ((voff) == voffA ? AUXA : 0)); } while (0)
; #define PG8_LDA(dst, b, h) do { _Pragma("unroll") for (int m = 0; m < 4; ++m) _Pragma("unroll") for (int k = 0; k < 2; ++k) dst[m][k] = *(const LAS bf16x8*)(lds + PG8_SA(b, h) + aoff + m * 2048 + k * 1024); } while (0)
; #define PG8_LDB(dst, b, h) do { _Pragma("unroll") for (int n = 0; n < 2; ++n) _Pragma("unroll") for (int k = 0; k < 2; ++k) dst[n][k] = *(const LAS bf16x8*)(lds + PG8_SB(b, h) + boff + n * 2048 + k * 1024); } while (0)
; #define PG8_MMA(ai, bj, At, Bt) do { __builtin_amdgcn_s_setprio(1); _Pragma("unroll") for (int m = 0; m < 4; ++m) _Pragma("unroll") for (int n = 0; n < 2; ++n) _Pragma("unroll") for (int k = 0; k < 2; ++k) \
;         acc[ai][bj][m][n] = __builtin_amdgcn_mfma_f32_16x16x32_bf16(Bt[n][k], At[m][k], acc[ai][bj][m][n], 0, 0, 0); __builtin_amdgcn_s_setprio(0); } while (0)
; #define PG8_WAIT_V(n) asm volatile("s_waitcnt vmcnt(" #n ")" ::: "memory")
; #define PG8_WAIT_L(n) asm volatile("s_waitcnt lgkmcnt(" #n ")" ::: "memory")
; #define PG8_BAR __builtin_amdgcn_s_barrier()
; #define PG8_SCHED __builtin_amdgcn_sched_barrier(0)
;     ...
;             PG8_WAIT_L(0); PG8_BAR; PG8_MMA(1, 0, At, B0); PG8_MMA(1, 1, At, B1); PG8_BAR; PG8_SCHED;
;             PG8_LDB(B0, 1, 0); PG8_LDB(B1, 1, 1); PG8_SCHED; PG8_LDA(At, 1, 0); PG8_STAGE(PG8_SA(0, 1), a2 + hsA, voffA);
;             PG8_WAIT_V(8); PG8_WAIT_L(0); PG8_BAR; PG8_MMA(0, 0, At, B0); PG8_MMA(0, 1, At, B1); PG8_BAR; PG8_SCHED;
.LBB0_148:
	s_waitcnt lgkmcnt(0)
	s_add_i32 s61, s61, 2
	s_barrier
	s_setprio 1
	s_waitcnt lgkmcnt(0)
	v_mfma_f32_16x16x32_bf16 v[60:63], v[144:147], v[184:187], v[60:63]
	v_mfma_f32_16x16x32_bf16 v[52:55], v[152:155], v[184:187], v[52:55]
	v_mfma_f32_16x16x32_bf16 v[44:47], v[144:147], v[176:179], v[44:47]
	v_mfma_f32_16x16x32_bf16 v[36:39], v[152:155], v[176:179], v[36:39]
	v_mfma_f32_16x16x32_bf16 v[28:31], v[144:147], v[168:171], v[28:31]
	v_mfma_f32_16x16x32_bf16 v[20:23], v[152:155], v[168:171], v[20:23]
	v_mfma_f32_16x16x32_bf16 v[12:15], v[144:147], v[160:163], v[12:15]
	v_mfma_f32_16x16x32_bf16 v[4:7], v[152:155], v[160:163], v[4:7]
	v_mfma_f32_16x16x32_bf16 v[60:63], v[148:151], v[188:191], v[60:63]
	v_mfma_f32_16x16x32_bf16 v[52:55], v[156:159], v[188:191], v[52:55]
	v_mfma_f32_16x16x32_bf16 v[44:47], v[148:151], v[180:183], v[44:47]
	v_mfma_f32_16x16x32_bf16 v[36:39], v[156:159], v[180:183], v[36:39]
	v_mfma_f32_16x16x32_bf16 v[28:31], v[148:151], v[172:175], v[28:31]
	v_mfma_f32_16x16x32_bf16 v[20:23], v[156:159], v[172:175], v[20:23]
	v_mfma_f32_16x16x32_bf16 v[12:15], v[148:151], v[164:167], v[12:15]
	v_mfma_f32_16x16x32_bf16 v[4:7], v[156:159], v[164:167], v[4:7]
	s_setprio 0
	s_setprio 1
	v_mfma_f32_16x16x32_bf16 v[56:59], v[128:131], v[184:187], v[56:59]
	v_mfma_f32_16x16x32_bf16 v[48:51], v[136:139], v[184:187], v[48:51]
	v_mfma_f32_16x16x32_bf16 v[40:43], v[128:131], v[176:179], v[40:43]
	v_mfma_f32_16x16x32_bf16 v[32:35], v[136:139], v[176:179], v[32:35]
	v_mfma_f32_16x16x32_bf16 v[24:27], v[128:131], v[168:171], v[24:27]
	v_mfma_f32_16x16x32_bf16 v[16:19], v[136:139], v[168:171], v[16:19]
	v_mfma_f32_16x16x32_bf16 v[8:11], v[128:131], v[160:163], v[8:11]
	v_mfma_f32_16x16x32_bf16 v[0:3], v[136:139], v[160:163], v[0:3]
	v_mfma_f32_16x16x32_bf16 v[56:59], v[132:135], v[188:191], v[56:59]
	v_mfma_f32_16x16x32_bf16 v[48:51], v[140:143], v[188:191], v[48:51]
	v_mfma_f32_16x16x32_bf16 v[40:43], v[132:135], v[180:183], v[40:43]
	v_mfma_f32_16x16x32_bf16 v[32:35], v[140:143], v[180:183], v[32:35]
	v_mfma_f32_16x16x32_bf16 v[24:27], v[132:135], v[172:175], v[24:27]
	v_mfma_f32_16x16x32_bf16 v[16:19], v[140:143], v[172:175], v[16:19]
	v_mfma_f32_16x16x32_bf16 v[8:11], v[132:135], v[164:167], v[8:11]
	v_mfma_f32_16x16x32_bf16 v[0:3], v[140:143], v[164:167], v[0:3]
	s_setprio 0
	s_barrier
	s_add_i32 s36, 0, 0x18000
	s_add_i32 s37, 0, 0x1c000
	v_add_u32_e32 v140, s36, v222
	v_add_u32_e32 v156, s37, v222
	ds_read_b128 v[128:131], v140
	ds_read_b128 v[132:135], v140 offset:1024
	ds_read_b128 v[136:139], v140 offset:2048
	ds_read_b128 v[140:143], v140 offset:3072
	ds_read_b128 v[144:147], v156
	ds_read_b128 v[148:151], v156 offset:1024
	ds_read_b128 v[152:155], v156 offset:2048
	ds_read_b128 v[156:159], v156 offset:3072
	s_add_u32 s34, s34, 0x80000
	s_addc_u32 s35, s35, 0
	s_mov_b32 m0, s46
	ds_read_b128 v[160:163], v226 offset:32768
	ds_read_b128 v[164:167], v226 offset:33792
	ds_read_b128 v[168:171], v226 offset:34816
	ds_read_b128 v[172:175], v226 offset:35840
	ds_read_b128 v[176:179], v226 offset:36864
	ds_read_b128 v[180:183], v226 offset:37888
	ds_read_b128 v[184:187], v226 offset:38912
	ds_read_b128 v[188:191], v226 offset:39936
	global_load_lds_dwordx4 v200, s[34:35]
	s_mov_b32 m0, s47
	s_nop 0
	global_load_lds_dwordx4 v196, s[34:35]
	s_waitcnt vmcnt(8)
	s_waitcnt lgkmcnt(0)
	s_barrier
	s_setprio 1
	s_waitcnt lgkmcnt(0)
	v_mfma_f32_16x16x32_bf16 v[124:127], v[128:131], v[160:163], v[124:127]
	v_mfma_f32_16x16x32_bf16 v[116:119], v[136:139], v[160:163], v[116:119]
	v_mfma_f32_16x16x32_bf16 v[108:111], v[128:131], v[168:171], v[108:111]
	v_mfma_f32_16x16x32_bf16 v[100:103], v[136:139], v[168:171], v[100:103]
	v_mfma_f32_16x16x32_bf16 v[92:95], v[128:131], v[176:179], v[92:95]
	v_mfma_f32_16x16x32_bf16 v[84:87], v[136:139], v[176:179], v[84:87]
	v_mfma_f32_16x16x32_bf16 v[76:79], v[128:131], v[184:187], v[76:79]
	v_mfma_f32_16x16x32_bf16 v[68:71], v[136:139], v[184:187], v[68:71]
	v_mfma_f32_16x16x32_bf16 v[124:127], v[132:135], v[164:167], v[124:127]
	v_mfma_f32_16x16x32_bf16 v[116:119], v[140:143], v[164:167], v[116:119]
	v_mfma_f32_16x16x32_bf16 v[108:111], v[132:135], v[172:175], v[108:111]
	v_mfma_f32_16x16x32_bf16 v[100:103], v[140:143], v[172:175], v[100:103]
	v_mfma_f32_16x16x32_bf16 v[92:95], v[132:135], v[180:183], v[92:95]
	v_mfma_f32_16x16x32_bf16 v[84:87], v[140:143], v[180:183], v[84:87]
	v_mfma_f32_16x16x32_bf16 v[76:79], v[132:135], v[188:191], v[76:79]
	v_mfma_f32_16x16x32_bf16 v[68:71], v[140:143], v[188:191], v[68:71]
	s_setprio 0
	s_setprio 1
	v_mfma_f32_16x16x32_bf16 v[120:123], v[144:147], v[160:163], v[120:123]
	v_mfma_f32_16x16x32_bf16 v[112:115], v[152:155], v[160:163], v[112:115]
	v_mfma_f32_16x16x32_bf16 v[104:107], v[144:147], v[168:171], v[104:107]
	v_mfma_f32_16x16x32_bf16 v[96:99], v[152:155], v[168:171], v[96:99]
	v_mfma_f32_16x16x32_bf16 v[88:91], v[144:147], v[176:179], v[88:91]
	v_mfma_f32_16x16x32_bf16 v[80:83], v[152:155], v[176:179], v[80:83]
	v_mfma_f32_16x16x32_bf16 v[72:75], v[144:147], v[184:187], v[72:75]
	v_mfma_f32_16x16x32_bf16 v[64:67], v[152:155], v[184:187], v[64:67]
	v_mfma_f32_16x16x32_bf16 v[120:123], v[148:151], v[164:167], v[120:123]
	v_mfma_f32_16x16x32_bf16 v[112:115], v[156:159], v[164:167], v[112:115]
	v_mfma_f32_16x16x32_bf16 v[104:107], v[148:151], v[172:175], v[104:107]
	v_mfma_f32_16x16x32_bf16 v[96:99], v[156:159], v[172:175], v[96:99]
	v_mfma_f32_16x16x32_bf16 v[88:91], v[148:151], v[180:183], v[88:91]
	v_mfma_f32_16x16x32_bf16 v[80:83], v[156:159], v[180:183], v[80:83]
	v_mfma_f32_16x16x32_bf16 v[72:75], v[148:151], v[188:191], v[72:75]
	v_mfma_f32_16x16x32_bf16 v[64:67], v[156:159], v[188:191], v[64:67]
	s_setprio 0
	s_barrier
; #define PG8_STAGE(bufoff, gbase, voff) do { _Pragma("unroll") for (int _i = 0; _i < 2; ++_i) \
;         __builtin_amdgcn_global_load_lds((const unsigned*)((const char*)(gbase) + (voff)[_i]), (LAS unsigned*)(lds + (bufoff) + ldsw + _i * 8192), 16, 0, ((voff) == voffA ? AUXA : 0)); } while (0)
; #define PG8_LDA(dst, b, h) do { _Pragma("unroll") for (int m = 0; m < 4; ++m) _Pragma("unroll") for (int k = 0; k < 2; ++k) dst[m][k] = *(const LAS bf16x8*)(lds + PG8_SA(b, h) + aoff + m * 2048 + k * 1024); } while (0)
; #define PG8_LDB(dst, b, h) do { _Pragma("unroll") for (int n = 0; n < 2; ++n) _Pragma("unroll") for (int k = 0; k < 2; ++k) dst[n][k] = *(const LAS bf16x8*)(lds + PG8_SB(b, h) + boff + n * 2048 + k * 1024); } while (0)
; #define PG8_MMA(ai, bj, At, Bt) do { __builtin_amdgcn_s_setprio(1); _Pragma("unroll") for (int m = 0; m < 4; ++m) _Pragma("unroll") for (int n = 0; n < 2; ++n) _Pragma("unroll") for (int k = 0; k < 2; ++k) \
;         acc[ai][bj][m][n] = __builtin_amdgcn_mfma_f32_16x16x32_bf16(Bt[n][k], At[m][k], acc[ai][bj][m][n], 0, 0, 0); __builtin_amdgcn_s_setprio(0); } while (0)
; #define PG8_WAIT_V(n) asm volatile("s_waitcnt vmcnt(" #n ")" ::: "memory")
; #define PG8_WAIT_L(n) asm volatile("s_waitcnt lgkmcnt(" #n ")" ::: "memory")
; #define PG8_BAR __builtin_amdgcn_s_barrier()
; #define PG8_SCHED __builtin_amdgcn_sched_barrier(0)
;     ...
;             PG8_LDB(B0, 0, 0); PG8_LDB(B1, 0, 1); PG8_SCHED; PG8_LDA(At, 0, 0); PG8_STAGE(PG8_SA(1, 1), a1 + hsA, voffA);
;             if (Epi::NPRE != 0 && last) { E.pre(sv, cur, wr, fr); PG8_WAIT_V(16); } else { PG8_WAIT_V(8); }
;     ...
;             PG8_LDA(At, 1, 1); PG8_STAGE(PG8_SB(1, 0), b3, voffB); PG8_STAGE(PG8_SB(1, 1), b3 + hsB, voffB); PG8_STAGE(PG8_SA(1, 0), a3, voffA);
;             PG8_WAIT_V(8); PG8_WAIT_L(0); PG8_BAR; PG8_MMA(1, 0, At, B0); PG8_MMA(1, 1, At, B1); PG8_BAR; PG8_SCHED;
	s_add_i32 s34, s36, s3
	s_mov_b32 m0, s34
	ds_read_b128 v[160:163], v226 offset:49152
	ds_read_b128 v[164:167], v226 offset:50176
	ds_read_b128 v[168:171], v226 offset:51200
	ds_read_b128 v[172:175], v226 offset:52224
	ds_read_b128 v[176:179], v226 offset:53248
	ds_read_b128 v[180:183], v226 offset:54272
	ds_read_b128 v[184:187], v226 offset:55296
	ds_read_b128 v[188:191], v226 offset:56320
	global_load_lds_dwordx4 v198, s[98:99]
	s_add_i32 m0, s34, 0x2000
	s_add_u32 s30, s30, 0x80080
	s_addc_u32 s31, s31, 0
	s_add_i32 s34, s37, s3
	global_load_lds_dwordx4 v194, s[98:99]
	s_mov_b32 m0, s34
	s_nop 0
	global_load_lds_dwordx4 v198, s[30:31]
	s_add_i32 m0, s34, 0x2000
	s_nop 0
	global_load_lds_dwordx4 v194, s[30:31]
	s_mov_b32 m0, s50
	s_nop 0
	global_load_lds_dwordx4 v200, s[100:101]
	s_mov_b32 m0, s51
	s_nop 0
	global_load_lds_dwordx4 v196, s[100:101]
	s_waitcnt vmcnt(8)
	s_waitcnt lgkmcnt(0)
	s_barrier
	s_setprio 1
	s_waitcnt lgkmcnt(0)
	v_mfma_f32_16x16x32_bf16 v[60:63], v[128:131], v[160:163], v[60:63]
	v_mfma_f32_16x16x32_bf16 v[52:55], v[136:139], v[160:163], v[52:55]
	v_mfma_f32_16x16x32_bf16 v[44:47], v[128:131], v[168:171], v[44:47]
	v_mfma_f32_16x16x32_bf16 v[36:39], v[136:139], v[168:171], v[36:39]
	v_mfma_f32_16x16x32_bf16 v[28:31], v[128:131], v[176:179], v[28:31]
	v_mfma_f32_16x16x32_bf16 v[20:23], v[136:139], v[176:179], v[20:23]
	v_mfma_f32_16x16x32_bf16 v[12:15], v[128:131], v[184:187], v[12:15]
	v_mfma_f32_16x16x32_bf16 v[4:7], v[136:139], v[184:187], v[4:7]
	v_mfma_f32_16x16x32_bf16 v[60:63], v[132:135], v[164:167], v[60:63]
	v_mfma_f32_16x16x32_bf16 v[52:55], v[140:143], v[164:167], v[52:55]
	v_mfma_f32_16x16x32_bf16 v[44:47], v[132:135], v[172:175], v[44:47]
	v_mfma_f32_16x16x32_bf16 v[36:39], v[140:143], v[172:175], v[36:39]
	v_mfma_f32_16x16x32_bf16 v[28:31], v[132:135], v[180:183], v[28:31]
	v_mfma_f32_16x16x32_bf16 v[20:23], v[140:143], v[180:183], v[20:23]
	v_mfma_f32_16x16x32_bf16 v[12:15], v[132:135], v[188:191], v[12:15]
	v_mfma_f32_16x16x32_bf16 v[4:7], v[140:143], v[188:191], v[4:7]
	s_setprio 0
	s_setprio 1
	v_mfma_f32_16x16x32_bf16 v[56:59], v[144:147], v[160:163], v[56:59]
	v_mfma_f32_16x16x32_bf16 v[48:51], v[152:155], v[160:163], v[48:51]
	v_mfma_f32_16x16x32_bf16 v[40:43], v[144:147], v[168:171], v[40:43]
	v_mfma_f32_16x16x32_bf16 v[32:35], v[152:155], v[168:171], v[32:35]
	v_mfma_f32_16x16x32_bf16 v[24:27], v[144:147], v[176:179], v[24:27]
	v_mfma_f32_16x16x32_bf16 v[16:19], v[152:155], v[176:179], v[16:19]
	v_mfma_f32_16x16x32_bf16 v[8:11], v[144:147], v[184:187], v[8:11]
	v_mfma_f32_16x16x32_bf16 v[0:3], v[152:155], v[184:187], v[0:3]
	v_mfma_f32_16x16x32_bf16 v[56:59], v[148:151], v[164:167], v[56:59]
	v_mfma_f32_16x16x32_bf16 v[48:51], v[156:159], v[164:167], v[48:51]
	v_mfma_f32_16x16x32_bf16 v[40:43], v[148:151], v[172:175], v[40:43]
	v_mfma_f32_16x16x32_bf16 v[32:35], v[156:159], v[172:175], v[32:35]
	v_mfma_f32_16x16x32_bf16 v[24:27], v[148:151], v[180:183], v[24:27]
	v_mfma_f32_16x16x32_bf16 v[16:19], v[156:159], v[180:183], v[16:19]
	v_mfma_f32_16x16x32_bf16 v[8:11], v[148:151], v[188:191], v[8:11]
	v_mfma_f32_16x16x32_bf16 v[0:3], v[156:159], v[188:191], v[0:3]
	s_setprio 0
	s_barrier
	s_add_u32 s28, s28, 0x100
	s_addc_u32 s29, s29, 0
	s_add_u32 s59, s59, 0x100
	s_addc_u32 s60, s60, 0
	s_cmp_ge_i32 s61, s49
	s_cbranch_scc1 .LBB0_158
.LBB0_149:
	ds_read_b128 v[144:147], v224
	ds_read_b128 v[148:151], v224 offset:1024
	ds_read_b128 v[152:155], v224 offset:2048
	ds_read_b128 v[156:159], v224 offset:3072
	ds_read_b128 v[128:131], v225
	ds_read_b128 v[132:135], v225 offset:1024
	ds_read_b128 v[136:139], v225 offset:2048
	ds_read_b128 v[140:143], v225 offset:3072
	s_cmp_eq_u32 s52, s61
	s_cselect_b64 s[30:31], -1, 0
	s_cmp_lg_u32 s52, s61
	s_cselect_b64 s[36:37], -1, 0
	s_add_i32 m0, s40, 0xc000
	ds_read_b128 v[184:187], v226
	ds_read_b128 v[188:191], v226 offset:1024
	ds_read_b128 v[176:179], v226 offset:2048
	ds_read_b128 v[180:183], v226 offset:3072
	ds_read_b128 v[168:171], v226 offset:4096
	ds_read_b128 v[172:175], v226 offset:5120
	ds_read_b128 v[160:163], v226 offset:6144
	ds_read_b128 v[164:167], v226 offset:7168
	global_load_lds_dwordx4 v202, s[28:29]
	s_add_i32 m0, s40, 0xe000
	s_mov_b64 s[34:35], -1
	global_load_lds_dwordx4 v204, s[28:29]
	s_and_b64 vcc, exec, s[36:37]
	s_cbranch_vccz .LBB0_151
	s_waitcnt vmcnt(8)
	s_mov_b64 s[34:35], 0

; #define PG8_STAGE(bufoff, gbase, voff) do { _Pragma("unroll") for (int _i = 0; _i < 2; ++_i) \
;         __builtin_amdgcn_global_load_lds((const unsigned*)((const char*)(gbase) + (voff)[_i]), (LAS unsigned*)(lds + (bufoff) + ldsw + _i * 8192), 16, 0, ((voff) == voffA ? AUXA : 0)); } while (0)
; #define PG8_LDA(dst, b, h) do { _Pragma("unroll") for (int m = 0; m < 4; ++m) _Pragma("unroll") for (int k = 0; k < 2; ++k) dst[m][k] = *(const LAS bf16x8*)(lds + PG8_SA(b, h) + aoff + m * 2048 + k * 1024); } while (0)
; #define PG8_LDB(dst, b, h) do { _Pragma("unroll") for (int n = 0; n < 2; ++n) _Pragma("unroll") for (int k = 0; k < 2; ++k) dst[n][k] = *(const LAS bf16x8*)(lds + PG8_SB(b, h) + boff + n * 2048 + k * 1024); } while (0)
; #define PG8_MMA(ai, bj, At, Bt) do { __builtin_amdgcn_s_setprio(1); _Pragma("unroll") for (int m = 0; m < 4; ++m) _Pragma("unroll") for (int n = 0; n < 2; ++n) _Pragma("unroll") for (int k = 0; k < 2; ++k) \
;         acc[ai][bj][m][n] = __builtin_amdgcn_mfma_f32_16x16x32_bf16(Bt[n][k], At[m][k], acc[ai][bj][m][n], 0, 0, 0); __builtin_amdgcn_s_setprio(0); } while (0)
; #define PG8_WAIT_V(n) asm volatile("s_waitcnt vmcnt(" #n ")" ::: "memory")
; #define PG8_WAIT_L(n) asm volatile("s_waitcnt lgkmcnt(" #n ")" ::: "memory")
; #define PG8_BAR __builtin_amdgcn_s_barrier()
; #define PG8_SCHED __builtin_amdgcn_sched_barrier(0)
;     ...
;             const char* a2 = last ? nA : cA + (size_t)(t + 2) * kstep; const char* b2 = last ? nB : cB + (size_t)(t + 2) * kstep;
;             const char* a3 = a2 + kstep; const char* b3 = b2 + kstep;
;             PG8_LDB(B0, 0, 0); PG8_LDB(B1, 0, 1); PG8_SCHED; PG8_LDA(At, 0, 0); PG8_STAGE(PG8_SA(1, 1), a1 + hsA, voffA);
;             if (Epi::NPRE != 0 && last) { E.pre(sv, cur, wr, fr); PG8_WAIT_V(16); } else { PG8_WAIT_V(8); }
;             PG8_WAIT_L(0); PG8_BAR; PG8_MMA(0, 0, At, B0); PG8_MMA(0, 1, At, B1); PG8_BAR; PG8_SCHED;
;             PG8_LDA(At, 0, 1); PG8_STAGE(PG8_SB(0, 0), b2, voffB); PG8_STAGE(PG8_SB(0, 1), b2 + hsB, voffB); PG8_STAGE(PG8_SA(0, 0), a2, voffA);
;             if (Epi::NPRE != 0 && last) { PG8_WAIT_V(16); } else { PG8_WAIT_V(8); }
.LBB0_153:
	s_add_u32 s34, s28, 0xfff80080
	s_addc_u32 s35, s29, -1
	s_waitcnt lgkmcnt(0)
	s_and_b64 s[30:31], s[30:31], exec
	s_cselect_b32 s35, s21, s35
	s_cselect_b32 s34, s23, s34
	s_cselect_b32 s31, s57, s60
	s_cselect_b32 s30, s58, s59
	s_barrier
	s_setprio 1
	s_waitcnt lgkmcnt(0)
	v_mfma_f32_16x16x32_bf16 v[124:127], v[144:147], v[184:187], v[124:127]
	v_mfma_f32_16x16x32_bf16 v[116:119], v[152:155], v[184:187], v[116:119]
	v_mfma_f32_16x16x32_bf16 v[108:111], v[144:147], v[176:179], v[108:111]
	v_mfma_f32_16x16x32_bf16 v[100:103], v[152:155], v[176:179], v[100:103]
	v_mfma_f32_16x16x32_bf16 v[92:95], v[144:147], v[168:171], v[92:95]
	v_mfma_f32_16x16x32_bf16 v[84:87], v[152:155], v[168:171], v[84:87]
	v_mfma_f32_16x16x32_bf16 v[76:79], v[144:147], v[160:163], v[76:79]
	v_mfma_f32_16x16x32_bf16 v[68:71], v[152:155], v[160:163], v[68:71]
	v_mfma_f32_16x16x32_bf16 v[124:127], v[148:151], v[188:191], v[124:127]
	v_mfma_f32_16x16x32_bf16 v[116:119], v[156:159], v[188:191], v[116:119]
	v_mfma_f32_16x16x32_bf16 v[108:111], v[148:151], v[180:183], v[108:111]
	v_mfma_f32_16x16x32_bf16 v[100:103], v[156:159], v[180:183], v[100:103]
	v_mfma_f32_16x16x32_bf16 v[92:95], v[148:151], v[172:175], v[92:95]
	v_mfma_f32_16x16x32_bf16 v[84:87], v[156:159], v[172:175], v[84:87]
	v_mfma_f32_16x16x32_bf16 v[76:79], v[148:151], v[164:167], v[76:79]
	v_mfma_f32_16x16x32_bf16 v[68:71], v[156:159], v[164:167], v[68:71]
	s_setprio 0
	s_setprio 1
	v_mfma_f32_16x16x32_bf16 v[120:123], v[128:131], v[184:187], v[120:123]
	v_mfma_f32_16x16x32_bf16 v[112:115], v[136:139], v[184:187], v[112:115]
	v_mfma_f32_16x16x32_bf16 v[104:107], v[128:131], v[176:179], v[104:107]
	v_mfma_f32_16x16x32_bf16 v[96:99], v[136:139], v[176:179], v[96:99]
	v_mfma_f32_16x16x32_bf16 v[88:91], v[128:131], v[168:171], v[88:91]
	v_mfma_f32_16x16x32_bf16 v[80:83], v[136:139], v[168:171], v[80:83]
	v_mfma_f32_16x16x32_bf16 v[72:75], v[128:131], v[160:163], v[72:75]
	v_mfma_f32_16x16x32_bf16 v[64:67], v[136:139], v[160:163], v[64:67]
	v_mfma_f32_16x16x32_bf16 v[120:123], v[132:135], v[188:191], v[120:123]
	v_mfma_f32_16x16x32_bf16 v[112:115], v[140:143], v[188:191], v[112:115]
	v_mfma_f32_16x16x32_bf16 v[104:107], v[132:135], v[180:183], v[104:107]
	v_mfma_f32_16x16x32_bf16 v[96:99], v[140:143], v[180:183], v[96:99]
	v_mfma_f32_16x16x32_bf16 v[88:91], v[132:135], v[172:175], v[88:91]
	v_mfma_f32_16x16x32_bf16 v[80:83], v[140:143], v[172:175], v[80:83]
	v_mfma_f32_16x16x32_bf16 v[72:75], v[132:135], v[164:167], v[72:75]
	v_mfma_f32_16x16x32_bf16 v[64:67], v[140:143], v[164:167], v[64:67]
	s_setprio 0
	s_barrier
	s_add_u32 s98, s30, s16
	s_addc_u32 s99, s31, s17
	s_add_u32 s100, s34, s16
	s_addc_u32 s101, s35, s17
	s_mov_b32 m0, s41
	s_add_u32 s38, s30, 0x80000
	ds_read_b128 v[184:187], v226 offset:16384
	ds_read_b128 v[188:191], v226 offset:17408
	ds_read_b128 v[176:179], v226 offset:18432
	ds_read_b128 v[180:183], v226 offset:19456
	ds_read_b128 v[168:171], v226 offset:20480
	ds_read_b128 v[172:175], v226 offset:21504
	ds_read_b128 v[160:163], v226 offset:22528
	ds_read_b128 v[164:167], v226 offset:23552
	global_load_lds_dwordx4 v198, s[30:31]
	s_mov_b32 m0, s42
	s_addc_u32 s39, s31, 0
	global_load_lds_dwordx4 v194, s[30:31]
	s_mov_b32 m0, s43
	s_nop 0
	global_load_lds_dwordx4 v198, s[38:39]
	s_mov_b32 m0, s44
	s_nop 0
	global_load_lds_dwordx4 v194, s[38:39]
	s_mov_b64 s[38:39], -1
	s_mov_b32 m0, s40
	s_and_b64 vcc, exec, s[36:37]
	global_load_lds_dwordx4 v200, s[34:35]
	s_mov_b32 m0, s45
	s_nop 0
	global_load_lds_dwordx4 v196, s[34:35]
	s_cbranch_vccz .LBB0_155
	s_waitcnt vmcnt(8)
	s_mov_b64 s[38:39], 0

; #define PG8_STAGE(bufoff, gbase, voff) do { _Pragma("unroll") for (int _i = 0; _i < 2; ++_i) \
;         __builtin_amdgcn_global_load_lds((const unsigned*)((const char*)(gbase) + (voff)[_i]), (LAS unsigned*)(lds + (bufoff) + ldsw + _i * 8192), 16, 0, ((voff) == voffA ? AUXA : 0)); } while (0)
; #define PG8_LDA(dst, b, h) do { _Pragma("unroll") for (int m = 0; m < 4; ++m) _Pragma("unroll") for (int k = 0; k < 2; ++k) dst[m][k] = *(const LAS bf16x8*)(lds + PG8_SA(b, h) + aoff + m * 2048 + k * 1024); } while (0)
; #define PG8_LDB(dst, b, h) do { _Pragma("unroll") for (int n = 0; n < 2; ++n) _Pragma("unroll") for (int k = 0; k < 2; ++k) dst[n][k] = *(const LAS bf16x8*)(lds + PG8_SB(b, h) + boff + n * 2048 + k * 1024); } while (0)
; #define PG8_MMA(ai, bj, At, Bt) do { __builtin_amdgcn_s_setprio(1); _Pragma("unroll") for (int m = 0; m < 4; ++m) _Pragma("unroll") for (int n = 0; n < 2; ++n) _Pragma("unroll") for (int k = 0; k < 2; ++k) \
;         acc[ai][bj][m][n] = __builtin_amdgcn_mfma_f32_16x16x32_bf16(Bt[n][k], At[m][k], acc[ai][bj][m][n], 0, 0, 0); __builtin_amdgcn_s_setprio(0); } while (0)
; #define PG8_WAIT_V(n) asm volatile("s_waitcnt vmcnt(" #n ")" ::: "memory")
; #define PG8_WAIT_L(n) asm volatile("s_waitcnt lgkmcnt(" #n ")" ::: "memory")
; #define PG8_BAR __builtin_amdgcn_s_barrier()
; #define PG8_SCHED __builtin_amdgcn_sched_barrier(0)
;     ...
;             const bool last = (t == nt - 2);
;             const char* a1 = cA + (size_t)(t + 1) * kstep;
;             const char* a2 = last ? nA : cA + (size_t)(t + 2) * kstep; const char* b2 = last ? nB : cB + (size_t)(t + 2) * kstep;
;             const char* a3 = a2 + kstep; const char* b3 = b2 + kstep;
;             PG8_LDB(B0, 0, 0); PG8_LDB(B1, 0, 1); PG8_SCHED; PG8_LDA(At, 0, 0); PG8_STAGE(PG8_SA(1, 1), a1 + hsA, voffA);
;             if (Epi::NPRE != 0 && last) { E.pre(sv, cur, wr, fr); PG8_WAIT_V(16); } else { PG8_WAIT_V(8); }
;             PG8_WAIT_L(0); PG8_BAR; PG8_MMA(0, 0, At, B0); PG8_MMA(0, 1, At, B1); PG8_BAR; PG8_SCHED;
;             PG8_LDA(At, 0, 1); PG8_STAGE(PG8_SB(0, 0), b2, voffB); PG8_STAGE(PG8_SB(0, 1), b2 + hsB, voffB); PG8_STAGE(PG8_SA(0, 0), a2, voffA);
;             if (Epi::NPRE != 0 && last) { PG8_WAIT_V(16); } else { PG8_WAIT_V(8); }
;             PG8_WAIT_L(0); PG8_BAR; PG8_MMA(1, 0, At, B0); PG8_MMA(1, 1, At, B1); PG8_BAR; PG8_SCHED;
.LBB0_246:
	ds_read_b128 v[144:147], v208
	ds_read_b128 v[148:151], v208 offset:1024
	ds_read_b128 v[152:155], v208 offset:2048
	ds_read_b128 v[156:159], v208 offset:3072
	ds_read_b128 v[160:163], v209
	ds_read_b128 v[164:167], v209 offset:1024
	ds_read_b128 v[168:171], v209 offset:2048
	ds_read_b128 v[172:175], v209 offset:3072
	s_add_i32 s52, s26, 2
	s_add_u32 s27, s24, 0xffea0080
	s_addc_u32 s28, s25, -1
	s_cmp_eq_u32 s41, s26
	s_cselect_b32 s26, s22, s50
	s_cselect_b32 s29, s11, s28
	s_cselect_b32 s28, s10, s27
	s_cselect_b32 s27, s23, s51
	s_add_i32 m0, s30, 0xc000
	ds_read_b128 v[176:179], v210
	ds_read_b128 v[180:183], v210 offset:1024
	ds_read_b128 v[184:187], v210 offset:2048
	ds_read_b128 v[188:191], v210 offset:3072
	ds_read_b128 v[194:197], v210 offset:4096
	ds_read_b128 v[198:201], v210 offset:5120
	ds_read_b128 v[202:205], v210 offset:6144
	ds_read_b128 v[212:215], v210 offset:7168
	global_load_lds_dwordx4 v136, s[24:25]
	s_add_i32 m0, s30, 0xe000
	s_nop 0
	global_load_lds_dwordx4 v138, s[24:25]
	s_waitcnt vmcnt(8)
	s_waitcnt lgkmcnt(0)
	s_barrier
	s_setprio 1
	s_waitcnt lgkmcnt(0)
	v_mfma_f32_16x16x32_bf16 v[124:127], v[144:147], v[176:179], v[124:127]
	v_mfma_f32_16x16x32_bf16 v[120:123], v[152:155], v[176:179], v[120:123]
	v_mfma_f32_16x16x32_bf16 v[116:119], v[144:147], v[184:187], v[116:119]
	v_mfma_f32_16x16x32_bf16 v[112:115], v[152:155], v[184:187], v[112:115]
	v_mfma_f32_16x16x32_bf16 v[104:107], v[144:147], v[194:197], v[104:107]
	v_mfma_f32_16x16x32_bf16 v[96:99], v[152:155], v[194:197], v[96:99]
	v_mfma_f32_16x16x32_bf16 v[88:91], v[144:147], v[202:205], v[88:91]
	v_mfma_f32_16x16x32_bf16 v[80:83], v[152:155], v[202:205], v[80:83]
	v_mfma_f32_16x16x32_bf16 v[124:127], v[148:151], v[180:183], v[124:127]
	v_mfma_f32_16x16x32_bf16 v[120:123], v[156:159], v[180:183], v[120:123]
	v_mfma_f32_16x16x32_bf16 v[116:119], v[148:151], v[188:191], v[116:119]
	v_mfma_f32_16x16x32_bf16 v[112:115], v[156:159], v[188:191], v[112:115]
	v_mfma_f32_16x16x32_bf16 v[104:107], v[148:151], v[198:201], v[104:107]
	v_mfma_f32_16x16x32_bf16 v[96:99], v[156:159], v[198:201], v[96:99]
	v_mfma_f32_16x16x32_bf16 v[88:91], v[148:151], v[212:215], v[88:91]
	v_mfma_f32_16x16x32_bf16 v[80:83], v[156:159], v[212:215], v[80:83]
	s_setprio 0
	s_setprio 1
	v_mfma_f32_16x16x32_bf16 v[108:111], v[160:163], v[176:179], v[108:111]
	v_mfma_f32_16x16x32_bf16 v[100:103], v[168:171], v[176:179], v[100:103]
	v_mfma_f32_16x16x32_bf16 v[92:95], v[160:163], v[184:187], v[92:95]
	v_mfma_f32_16x16x32_bf16 v[84:87], v[168:171], v[184:187], v[84:87]
	v_mfma_f32_16x16x32_bf16 v[76:79], v[160:163], v[194:197], v[76:79]
	v_mfma_f32_16x16x32_bf16 v[72:75], v[168:171], v[194:197], v[72:75]
	v_mfma_f32_16x16x32_bf16 v[68:71], v[160:163], v[202:205], v[68:71]
	v_mfma_f32_16x16x32_bf16 v[64:67], v[168:171], v[202:205], v[64:67]
	v_mfma_f32_16x16x32_bf16 v[108:111], v[164:167], v[180:183], v[108:111]
	v_mfma_f32_16x16x32_bf16 v[100:103], v[172:175], v[180:183], v[100:103]
	v_mfma_f32_16x16x32_bf16 v[92:95], v[164:167], v[188:191], v[92:95]
	v_mfma_f32_16x16x32_bf16 v[84:87], v[172:175], v[188:191], v[84:87]
	v_mfma_f32_16x16x32_bf16 v[76:79], v[164:167], v[198:201], v[76:79]
	v_mfma_f32_16x16x32_bf16 v[72:75], v[172:175], v[198:201], v[72:75]
	v_mfma_f32_16x16x32_bf16 v[68:71], v[164:167], v[212:215], v[68:71]
	v_mfma_f32_16x16x32_bf16 v[64:67], v[172:175], v[212:215], v[64:67]
	s_setprio 0
	s_barrier
	s_add_u32 s98, s26, s16
	s_addc_u32 s99, s27, s17
	s_add_u32 s100, s28, s16
	s_addc_u32 s101, s29, s17
	s_add_i32 s53, s44, s5
	s_mov_b32 m0, s53
	ds_read_b128 v[176:179], v210 offset:16384
	ds_read_b128 v[180:183], v210 offset:17408
	ds_read_b128 v[184:187], v210 offset:18432
	ds_read_b128 v[188:191], v210 offset:19456
	ds_read_b128 v[194:197], v210 offset:20480
	ds_read_b128 v[198:201], v210 offset:21504
	ds_read_b128 v[202:205], v210 offset:22528
	ds_read_b128 v[212:215], v210 offset:23552
	global_load_lds_dwordx4 v130, s[26:27]
	s_add_i32 m0, s53, 0x2000
	s_add_u32 s54, s26, 0x160000
	s_addc_u32 s55, s27, 0
	s_add_i32 s53, s45, s5
	global_load_lds_dwordx4 v134, s[26:27]
	s_mov_b32 m0, s53
	s_nop 0
	global_load_lds_dwordx4 v130, s[54:55]
	s_add_i32 m0, s53, 0x2000
	s_nop 0
	global_load_lds_dwordx4 v134, s[54:55]
	s_mov_b32 m0, s30
	s_nop 0
	global_load_lds_dwordx4 v128, s[28:29]
	s_mov_b32 m0, s31
	s_nop 0
	global_load_lds_dwordx4 v132, s[28:29]
	s_waitcnt vmcnt(8)
	s_waitcnt lgkmcnt(0)
	s_barrier
	s_setprio 1
	s_waitcnt lgkmcnt(0)
	v_mfma_f32_16x16x32_bf16 v[60:63], v[144:147], v[176:179], v[60:63]
	v_mfma_f32_16x16x32_bf16 v[56:59], v[152:155], v[176:179], v[56:59]
	v_mfma_f32_16x16x32_bf16 v[52:55], v[144:147], v[184:187], v[52:55]
	v_mfma_f32_16x16x32_bf16 v[48:51], v[152:155], v[184:187], v[48:51]
	v_mfma_f32_16x16x32_bf16 v[40:43], v[144:147], v[194:197], v[40:43]
	v_mfma_f32_16x16x32_bf16 v[32:35], v[152:155], v[194:197], v[32:35]
	v_mfma_f32_16x16x32_bf16 v[24:27], v[144:147], v[202:205], v[24:27]
	v_mfma_f32_16x16x32_bf16 v[16:19], v[152:155], v[202:205], v[16:19]
	v_mfma_f32_16x16x32_bf16 v[60:63], v[148:151], v[180:183], v[60:63]
	v_mfma_f32_16x16x32_bf16 v[56:59], v[156:159], v[180:183], v[56:59]
	v_mfma_f32_16x16x32_bf16 v[52:55], v[148:151], v[188:191], v[52:55]
	v_mfma_f32_16x16x32_bf16 v[48:51], v[156:159], v[188:191], v[48:51]
	v_mfma_f32_16x16x32_bf16 v[40:43], v[148:151], v[198:201], v[40:43]
	v_mfma_f32_16x16x32_bf16 v[32:35], v[156:159], v[198:201], v[32:35]
	v_mfma_f32_16x16x32_bf16 v[24:27], v[148:151], v[212:215], v[24:27]
	v_mfma_f32_16x16x32_bf16 v[16:19], v[156:159], v[212:215], v[16:19]
	s_setprio 0
	s_setprio 1
	v_mfma_f32_16x16x32_bf16 v[44:47], v[160:163], v[176:179], v[44:47]
	v_mfma_f32_16x16x32_bf16 v[36:39], v[168:171], v[176:179], v[36:39]
	v_mfma_f32_16x16x32_bf16 v[28:31], v[160:163], v[184:187], v[28:31]
	v_mfma_f32_16x16x32_bf16 v[20:23], v[168:171], v[184:187], v[20:23]
	v_mfma_f32_16x16x32_bf16 v[12:15], v[160:163], v[194:197], v[12:15]
	v_mfma_f32_16x16x32_bf16 v[8:11], v[168:171], v[194:197], v[8:11]
	v_mfma_f32_16x16x32_bf16 v[4:7], v[160:163], v[202:205], v[4:7]
	v_mfma_f32_16x16x32_bf16 v[0:3], v[168:171], v[202:205], v[0:3]
	v_mfma_f32_16x16x32_bf16 v[44:47], v[164:167], v[180:183], v[44:47]
	v_mfma_f32_16x16x32_bf16 v[36:39], v[172:175], v[180:183], v[36:39]
	v_mfma_f32_16x16x32_bf16 v[28:31], v[164:167], v[188:191], v[28:31]
	v_mfma_f32_16x16x32_bf16 v[20:23], v[172:175], v[188:191], v[20:23]
	v_mfma_f32_16x16x32_bf16 v[12:15], v[164:167], v[198:201], v[12:15]
	v_mfma_f32_16x16x32_bf16 v[8:11], v[172:175], v[198:201], v[8:11]
	v_mfma_f32_16x16x32_bf16 v[4:7], v[164:167], v[212:215], v[4:7]
	v_mfma_f32_16x16x32_bf16 v[0:3], v[172:175], v[212:215], v[0:3]
	s_setprio 0
	s_barrier
; #define PG8_STAGE(bufoff, gbase, voff) do { _Pragma("unroll") for (int _i = 0; _i < 2; ++_i) \
;         __builtin_amdgcn_global_load_lds((const unsigned*)((const char*)(gbase) + (voff)[_i]), (LAS unsigned*)(lds + (bufoff) + ldsw + _i * 8192), 16, 0, ((voff) == voffA ? AUXA : 0)); } while (0)
; #define PG8_LDA(dst, b, h) do { _Pragma("unroll") for (int m = 0; m < 4; ++m) _Pragma("unroll") for (int k = 0; k < 2; ++k) dst[m][k] = *(const LAS bf16x8*)(lds + PG8_SA(b, h) + aoff + m * 2048 + k * 1024); } while (0)
; #define PG8_LDB(dst, b, h) do { _Pragma("unroll") for (int n = 0; n < 2; ++n) _Pragma("unroll") for (int k = 0; k < 2; ++k) dst[n][k] = *(const LAS bf16x8*)(lds + PG8_SB(b, h) + boff + n * 2048 + k * 1024); } while (0)
; #define PG8_MMA(ai, bj, At, Bt) do { __builtin_amdgcn_s_setprio(1); _Pragma("unroll") for (int m = 0; m < 4; ++m) _Pragma("unroll") for (int n = 0; n < 2; ++n) _Pragma("unroll") for (int k = 0; k < 2; ++k) \
;         acc[ai][bj][m][n] = __builtin_amdgcn_mfma_f32_16x16x32_bf16(Bt[n][k], At[m][k], acc[ai][bj][m][n], 0, 0, 0); __builtin_amdgcn_s_setprio(0); } while (0)
; #define PG8_WAIT_V(n) asm volatile("s_waitcnt vmcnt(" #n ")" ::: "memory")
; #define PG8_WAIT_L(n) asm volatile("s_waitcnt lgkmcnt(" #n ")" ::: "memory")
; #define PG8_BAR __builtin_amdgcn_s_barrier()
; #define PG8_SCHED __builtin_amdgcn_sched_barrier(0)
;     ...
;             PG8_LDB(B0, 1, 0); PG8_LDB(B1, 1, 1); PG8_SCHED; PG8_LDA(At, 1, 0); PG8_STAGE(PG8_SA(0, 1), a2 + hsA, voffA);
;             PG8_WAIT_V(8); PG8_WAIT_L(0); PG8_BAR; PG8_MMA(0, 0, At, B0); PG8_MMA(0, 1, At, B1); PG8_BAR; PG8_SCHED;
;             PG8_LDA(At, 1, 1); PG8_STAGE(PG8_SB(1, 0), b3, voffB); PG8_STAGE(PG8_SB(1, 1), b3 + hsB, voffB); PG8_STAGE(PG8_SA(1, 0), a3, voffA);
;             PG8_WAIT_V(8); PG8_WAIT_L(0); PG8_BAR; PG8_MMA(1, 0, At, B0); PG8_MMA(1, 1, At, B1); PG8_BAR; PG8_SCHED;
	s_add_i32 s53, 0, 0x18000
	s_add_i32 s54, 0, 0x1c000
	v_add_u32_e32 v156, s53, v206
	v_add_u32_e32 v172, s54, v206
	ds_read_b128 v[144:147], v156
	ds_read_b128 v[148:151], v156 offset:1024
	ds_read_b128 v[152:155], v156 offset:2048
	ds_read_b128 v[156:159], v156 offset:3072
	ds_read_b128 v[160:163], v172
	ds_read_b128 v[164:167], v172 offset:1024
	ds_read_b128 v[168:171], v172 offset:2048
	ds_read_b128 v[172:175], v172 offset:3072
	s_add_u32 s28, s28, 0x160000
	s_addc_u32 s29, s29, 0
	s_mov_b32 m0, s34
	ds_read_b128 v[176:179], v210 offset:32768
	ds_read_b128 v[180:183], v210 offset:33792
	ds_read_b128 v[184:187], v210 offset:34816
	ds_read_b128 v[188:191], v210 offset:35840
	ds_read_b128 v[194:197], v210 offset:36864
	ds_read_b128 v[198:201], v210 offset:37888
	ds_read_b128 v[202:205], v210 offset:38912
	ds_read_b128 v[212:215], v210 offset:39936
	global_load_lds_dwordx4 v128, s[28:29]
	s_mov_b32 m0, s35
	s_nop 0
	global_load_lds_dwordx4 v132, s[28:29]
	s_waitcnt vmcnt(8)
	s_waitcnt lgkmcnt(0)
	s_barrier
	s_setprio 1
	s_waitcnt lgkmcnt(0)
	v_mfma_f32_16x16x32_bf16 v[124:127], v[144:147], v[176:179], v[124:127]
	v_mfma_f32_16x16x32_bf16 v[120:123], v[152:155], v[176:179], v[120:123]
	v_mfma_f32_16x16x32_bf16 v[116:119], v[144:147], v[184:187], v[116:119]
	v_mfma_f32_16x16x32_bf16 v[112:115], v[152:155], v[184:187], v[112:115]
	v_mfma_f32_16x16x32_bf16 v[104:107], v[144:147], v[194:197], v[104:107]
	v_mfma_f32_16x16x32_bf16 v[96:99], v[152:155], v[194:197], v[96:99]
	v_mfma_f32_16x16x32_bf16 v[88:91], v[144:147], v[202:205], v[88:91]
	v_mfma_f32_16x16x32_bf16 v[80:83], v[152:155], v[202:205], v[80:83]
	v_mfma_f32_16x16x32_bf16 v[124:127], v[148:151], v[180:183], v[124:127]
	v_mfma_f32_16x16x32_bf16 v[120:123], v[156:159], v[180:183], v[120:123]
	v_mfma_f32_16x16x32_bf16 v[116:119], v[148:151], v[188:191], v[116:119]
	v_mfma_f32_16x16x32_bf16 v[112:115], v[156:159], v[188:191], v[112:115]
	v_mfma_f32_16x16x32_bf16 v[104:107], v[148:151], v[198:201], v[104:107]
	v_mfma_f32_16x16x32_bf16 v[96:99], v[156:159], v[198:201], v[96:99]
	v_mfma_f32_16x16x32_bf16 v[88:91], v[148:151], v[212:215], v[88:91]
	v_mfma_f32_16x16x32_bf16 v[80:83], v[156:159], v[212:215], v[80:83]
	s_setprio 0
	s_setprio 1
	v_mfma_f32_16x16x32_bf16 v[108:111], v[160:163], v[176:179], v[108:111]
	v_mfma_f32_16x16x32_bf16 v[100:103], v[168:171], v[176:179], v[100:103]
	v_mfma_f32_16x16x32_bf16 v[92:95], v[160:163], v[184:187], v[92:95]
	v_mfma_f32_16x16x32_bf16 v[84:87], v[168:171], v[184:187], v[84:87]
	v_mfma_f32_16x16x32_bf16 v[76:79], v[160:163], v[194:197], v[76:79]
	v_mfma_f32_16x16x32_bf16 v[72:75], v[168:171], v[194:197], v[72:75]
	v_mfma_f32_16x16x32_bf16 v[68:71], v[160:163], v[202:205], v[68:71]
	v_mfma_f32_16x16x32_bf16 v[64:67], v[168:171], v[202:205], v[64:67]
	v_mfma_f32_16x16x32_bf16 v[108:111], v[164:167], v[180:183], v[108:111]
	v_mfma_f32_16x16x32_bf16 v[100:103], v[172:175], v[180:183], v[100:103]
	v_mfma_f32_16x16x32_bf16 v[92:95], v[164:167], v[188:191], v[92:95]
	v_mfma_f32_16x16x32_bf16 v[84:87], v[172:175], v[188:191], v[84:87]
	v_mfma_f32_16x16x32_bf16 v[76:79], v[164:167], v[198:201], v[76:79]
	v_mfma_f32_16x16x32_bf16 v[72:75], v[172:175], v[198:201], v[72:75]
	v_mfma_f32_16x16x32_bf16 v[68:71], v[164:167], v[212:215], v[68:71]
	v_mfma_f32_16x16x32_bf16 v[64:67], v[172:175], v[212:215], v[64:67]
	s_setprio 0
	s_barrier
	s_add_i32 s28, s53, s5
	s_mov_b32 m0, s28
	ds_read_b128 v[176:179], v210 offset:49152
	ds_read_b128 v[180:183], v210 offset:50176
	ds_read_b128 v[184:187], v210 offset:51200
	ds_read_b128 v[188:191], v210 offset:52224
	ds_read_b128 v[194:197], v210 offset:53248
	ds_read_b128 v[198:201], v210 offset:54272
	ds_read_b128 v[202:205], v210 offset:55296
	ds_read_b128 v[212:215], v210 offset:56320
	global_load_lds_dwordx4 v130, s[98:99]
	s_add_i32 m0, s28, 0x2000
	s_add_u32 s26, s26, 0x160080
	s_addc_u32 s27, s27, 0
	s_add_i32 s28, s54, s5
	global_load_lds_dwordx4 v134, s[98:99]
	s_mov_b32 m0, s28
	s_nop 0
	global_load_lds_dwordx4 v130, s[26:27]
	s_add_i32 m0, s28, 0x2000
	s_nop 0
	global_load_lds_dwordx4 v134, s[26:27]
	s_mov_b32 m0, s39
	s_nop 0
	global_load_lds_dwordx4 v128, s[100:101]
	s_mov_b32 m0, s40
	s_nop 0
	global_load_lds_dwordx4 v132, s[100:101]
	s_waitcnt vmcnt(8)
	s_waitcnt lgkmcnt(0)
	s_barrier
; #define PG8_MMA(ai, bj, At, Bt) do { __builtin_amdgcn_s_setprio(1); _Pragma("unroll") for (int m = 0; m < 4; ++m) _Pragma("unroll") for (int n = 0; n < 2; ++n) _Pragma("unroll") for (int k = 0; k < 2; ++k) \
;         acc[ai][bj][m][n] = __builtin_amdgcn_mfma_f32_16x16x32_bf16(Bt[n][k], At[m][k], acc[ai][bj][m][n], 0, 0, 0); __builtin_amdgcn_s_setprio(0); } while (0)
; #define PG8_WAIT_V(n) asm volatile("s_waitcnt vmcnt(" #n ")" ::: "memory")
; #define PG8_WAIT_L(n) asm volatile("s_waitcnt lgkmcnt(" #n ")" ::: "memory")
; #define PG8_BAR __builtin_amdgcn_s_barrier()
; #define PG8_SCHED __builtin_amdgcn_sched_barrier(0)
;     ...
;             PG8_WAIT_V(8); PG8_WAIT_L(0); PG8_BAR; PG8_MMA(1, 0, At, B0); PG8_MMA(1, 1, At, B1); PG8_BAR; PG8_SCHED;
;         }
;     __device__ __forceinline__ void operator()(const Acc& acc, const Unit& u, int wr, int wc, int fr, int fq, const float (&sv8)[8]) const {
;     ...
;                     const f32x4 y0 = xr[m][bj][0] + acc[ai][bj][m][0] * scale, y1 = xr[m][bj][1] + acc[ai][bj][m][1] * scale;
	s_setprio 1
	s_waitcnt lgkmcnt(0)
	v_mfma_f32_16x16x32_bf16 v[60:63], v[144:147], v[176:179], v[60:63]
	v_mfma_f32_16x16x32_bf16 v[56:59], v[152:155], v[176:179], v[56:59]
	v_mfma_f32_16x16x32_bf16 v[52:55], v[144:147], v[184:187], v[52:55]
	v_mfma_f32_16x16x32_bf16 v[48:51], v[152:155], v[184:187], v[48:51]
	v_mfma_f32_16x16x32_bf16 v[40:43], v[144:147], v[194:197], v[40:43]
	v_mfma_f32_16x16x32_bf16 v[32:35], v[152:155], v[194:197], v[32:35]
	v_mfma_f32_16x16x32_bf16 v[24:27], v[144:147], v[202:205], v[24:27]
	v_mfma_f32_16x16x32_bf16 v[16:19], v[152:155], v[202:205], v[16:19]
	v_mfma_f32_16x16x32_bf16 v[60:63], v[148:151], v[180:183], v[60:63]
	v_mfma_f32_16x16x32_bf16 v[56:59], v[156:159], v[180:183], v[56:59]
	v_mfma_f32_16x16x32_bf16 v[52:55], v[148:151], v[188:191], v[52:55]
	v_mfma_f32_16x16x32_bf16 v[48:51], v[156:159], v[188:191], v[48:51]
	v_mfma_f32_16x16x32_bf16 v[40:43], v[148:151], v[198:201], v[40:43]
	v_mfma_f32_16x16x32_bf16 v[32:35], v[156:159], v[198:201], v[32:35]
	v_mfma_f32_16x16x32_bf16 v[24:27], v[148:151], v[212:215], v[24:27]
	v_mfma_f32_16x16x32_bf16 v[16:19], v[156:159], v[212:215], v[16:19]
	s_setprio 0
	s_setprio 1
	v_mfma_f32_16x16x32_bf16 v[44:47], v[160:163], v[176:179], v[44:47]
	v_mfma_f32_16x16x32_bf16 v[36:39], v[168:171], v[176:179], v[36:39]
	v_mfma_f32_16x16x32_bf16 v[28:31], v[160:163], v[184:187], v[28:31]
	v_mfma_f32_16x16x32_bf16 v[20:23], v[168:171], v[184:187], v[20:23]
	v_mfma_f32_16x16x32_bf16 v[12:15], v[160:163], v[194:197], v[12:15]
	v_mfma_f32_16x16x32_bf16 v[8:11], v[168:171], v[194:197], v[8:11]
	v_mfma_f32_16x16x32_bf16 v[4:7], v[160:163], v[202:205], v[4:7]
	v_mfma_f32_16x16x32_bf16 v[0:3], v[168:171], v[202:205], v[0:3]
	v_mfma_f32_16x16x32_bf16 v[44:47], v[164:167], v[180:183], v[44:47]
	v_mfma_f32_16x16x32_bf16 v[36:39], v[172:175], v[180:183], v[36:39]
	v_mfma_f32_16x16x32_bf16 v[28:31], v[164:167], v[188:191], v[28:31]
	v_mfma_f32_16x16x32_bf16 v[20:23], v[172:175], v[188:191], v[20:23]
	v_mfma_f32_16x16x32_bf16 v[12:15], v[164:167], v[198:201], v[12:15]
	v_mfma_f32_16x16x32_bf16 v[8:11], v[172:175], v[198:201], v[8:11]
	v_mfma_f32_16x16x32_bf16 v[4:7], v[164:167], v[212:215], v[4:7]
	v_mfma_f32_16x16x32_bf16 v[0:3], v[172:175], v[212:215], v[0:3]
	s_setprio 0
	s_barrier
	s_add_u32 s24, s24, 0x100
	s_addc_u32 s25, s25, 0
	s_add_u32 s50, s50, 0x100
	s_addc_u32 s51, s51, 0
	s_cmp_ge_i32 s52, s38
	s_mov_b32 s26, s52
	s_cbranch_scc0 .LBB0_246
	v_pk_mul_f32 v[178:179], v[126:127], 0.5 op_sel_hi:[1,0]
	v_pk_mul_f32 v[184:185], v[124:125], 0.5 op_sel_hi:[1,0]
	v_pk_mul_f32 v[182:183], v[122:123], 0.5 op_sel_hi:[1,0]
	v_pk_mul_f32 v[180:181], v[120:121], 0.5 op_sel_hi:[1,0]
	v_pk_mul_f32 v[194:195], v[110:111], 0.5 op_sel_hi:[1,0]
	v_pk_mul_f32 v[190:191], v[108:109], 0.5 op_sel_hi:[1,0]
	v_pk_mul_f32 v[188:189], v[102:103], 0.5 op_sel_hi:[1,0]
	v_pk_mul_f32 v[186:187], v[100:101], 0.5 op_sel_hi:[1,0]
	v_pk_mul_f32 v[168:169], v[118:119], 0.5 op_sel_hi:[1,0]
	v_pk_mul_f32 v[166:167], v[116:117], 0.5 op_sel_hi:[1,0]
	v_pk_mul_f32 v[164:165], v[114:115], 0.5 op_sel_hi:[1,0]
	v_pk_mul_f32 v[162:163], v[112:113], 0.5 op_sel_hi:[1,0]
	v_pk_mul_f32 v[176:177], v[94:95], 0.5 op_sel_hi:[1,0]
	v_pk_mul_f32 v[174:175], v[92:93], 0.5 op_sel_hi:[1,0]
	v_pk_mul_f32 v[172:173], v[86:87], 0.5 op_sel_hi:[1,0]
	v_pk_mul_f32 v[170:171], v[84:85], 0.5 op_sel_hi:[1,0]
	v_pk_mul_f32 v[152:153], v[106:107], 0.5 op_sel_hi:[1,0]
	v_pk_mul_f32 v[150:151], v[104:105], 0.5 op_sel_hi:[1,0]
	v_pk_mul_f32 v[148:149], v[98:99], 0.5 op_sel_hi:[1,0]
	v_pk_mul_f32 v[146:147], v[96:97], 0.5 op_sel_hi:[1,0]
	v_pk_mul_f32 v[160:161], v[78:79], 0.5 op_sel_hi:[1,0]
	v_pk_mul_f32 v[158:159], v[76:77], 0.5 op_sel_hi:[1,0]
	v_pk_mul_f32 v[156:157], v[74:75], 0.5 op_sel_hi:[1,0]
	v_pk_mul_f32 v[154:155], v[72:73], 0.5 op_sel_hi:[1,0]
	v_pk_mul_f32 v[120:121], v[90:91], 0.5 op_sel_hi:[1,0]
	v_pk_mul_f32 v[118:119], v[88:89], 0.5 op_sel_hi:[1,0]
	v_pk_mul_f32 v[116:117], v[82:83], 0.5 op_sel_hi:[1,0]
	v_pk_mul_f32 v[114:115], v[80:81], 0.5 op_sel_hi:[1,0]
	v_pk_mul_f32 v[144:145], v[70:71], 0.5 op_sel_hi:[1,0]
	v_pk_mul_f32 v[126:127], v[68:69], 0.5 op_sel_hi:[1,0]
	v_pk_mul_f32 v[124:125], v[66:67], 0.5 op_sel_hi:[1,0]
	v_pk_mul_f32 v[122:123], v[64:65], 0.5 op_sel_hi:[1,0]
	v_pk_mul_f32 v[102:103], v[62:63], 0.5 op_sel_hi:[1,0]
	v_pk_mul_f32 v[100:101], v[60:61], 0.5 op_sel_hi:[1,0]
	v_pk_mul_f32 v[98:99], v[58:59], 0.5 op_sel_hi:[1,0]
	v_pk_mul_f32 v[96:97], v[56:57], 0.5 op_sel_hi:[1,0]
	v_pk_mul_f32 v[110:111], v[46:47], 0.5 op_sel_hi:[1,0]
	v_pk_mul_f32 v[108:109], v[44:45], 0.5 op_sel_hi:[1,0]
	v_pk_mul_f32 v[106:107], v[38:39], 0.5 op_sel_hi:[1,0]
	v_pk_mul_f32 v[104:105], v[36:37], 0.5 op_sel_hi:[1,0]
	v_pk_mul_f32 v[86:87], v[54:55], 0.5 op_sel_hi:[1,0]
	v_pk_mul_f32 v[84:85], v[52:53], 0.5 op_sel_hi:[1,0]
	v_pk_mul_f32 v[82:83], v[50:51], 0.5 op_sel_hi:[1,0]
	v_pk_mul_f32 v[80:81], v[48:49], 0.5 op_sel_hi:[1,0]
	v_pk_mul_f32 v[94:95], v[30:31], 0.5 op_sel_hi:[1,0]
	v_pk_mul_f32 v[92:93], v[28:29], 0.5 op_sel_hi:[1,0]
	v_pk_mul_f32 v[90:91], v[22:23], 0.5 op_sel_hi:[1,0]
	v_pk_mul_f32 v[88:89], v[20:21], 0.5 op_sel_hi:[1,0]
	v_pk_mul_f32 v[70:71], v[42:43], 0.5 op_sel_hi:[1,0]
	v_pk_mul_f32 v[68:69], v[40:41], 0.5 op_sel_hi:[1,0]
	v_pk_mul_f32 v[66:67], v[34:35], 0.5 op_sel_hi:[1,0]
	v_pk_mul_f32 v[64:65], v[32:33], 0.5 op_sel_hi:[1,0]
	v_pk_mul_f32 v[78:79], v[14:15], 0.5 op_sel_hi:[1,0]
	v_pk_mul_f32 v[76:77], v[12:13], 0.5 op_sel_hi:[1,0]
	v_pk_mul_f32 v[74:75], v[10:11], 0.5 op_sel_hi:[1,0]
	v_pk_mul_f32 v[72:73], v[8:9], 0.5 op_sel_hi:[1,0]
	v_pk_mul_f32 v[54:55], v[26:27], 0.5 op_sel_hi:[1,0]
	v_pk_mul_f32 v[52:53], v[24:25], 0.5 op_sel_hi:[1,0]
	v_pk_mul_f32 v[50:51], v[18:19], 0.5 op_sel_hi:[1,0]
	v_pk_mul_f32 v[48:49], v[16:17], 0.5 op_sel_hi:[1,0]
	v_pk_mul_f32 v[62:63], v[6:7], 0.5 op_sel_hi:[1,0]
	v_pk_mul_f32 v[60:61], v[4:5], 0.5 op_sel_hi:[1,0]
	v_pk_mul_f32 v[58:59], v[2:3], 0.5 op_sel_hi:[1,0]
	v_pk_mul_f32 v[56:57], v[0:1], 0.5 op_sel_hi:[1,0]

; #define PG8_STAGE(bufoff, gbase, voff) do { _Pragma("unroll") for (int _i = 0; _i < 2; ++_i) \
;         __builtin_amdgcn_global_load_lds((const unsigned*)((const char*)(gbase) + (voff)[_i]), (LAS unsigned*)(lds + (bufoff) + ldsw + _i * 8192), 16, 0, ((voff) == voffA ? AUXA : 0)); } while (0)
; #define PG8_LDA(dst, b, h) do { _Pragma("unroll") for (int m = 0; m < 4; ++m) _Pragma("unroll") for (int k = 0; k < 2; ++k) dst[m][k] = *(const LAS bf16x8*)(lds + PG8_SA(b, h) + aoff + m * 2048 + k * 1024); } while (0)
; #define PG8_LDB(dst, b, h) do { _Pragma("unroll") for (int n = 0; n < 2; ++n) _Pragma("unroll") for (int k = 0; k < 2; ++k) dst[n][k] = *(const LAS bf16x8*)(lds + PG8_SB(b, h) + boff + n * 2048 + k * 1024); } while (0)
; #define PG8_MMA(ai, bj, At, Bt) do { __builtin_amdgcn_s_setprio(1); _Pragma("unroll") for (int m = 0; m < 4; ++m) _Pragma("unroll") for (int n = 0; n < 2; ++n) _Pragma("unroll") for (int k = 0; k < 2; ++k) \
;         acc[ai][bj][m][n] = __builtin_amdgcn_mfma_f32_16x16x32_bf16(Bt[n][k], At[m][k], acc[ai][bj][m][n], 0, 0, 0); __builtin_amdgcn_s_setprio(0); } while (0)
; #define PG8_WAIT_V(n) asm volatile("s_waitcnt vmcnt(" #n ")" ::: "memory")
; #define PG8_WAIT_L(n) asm volatile("s_waitcnt lgkmcnt(" #n ")" ::: "memory")
; #define PG8_BAR __builtin_amdgcn_s_barrier()
; #define PG8_SCHED __builtin_amdgcn_sched_barrier(0)
;     ...
;             PG8_WAIT_L(0); PG8_BAR; PG8_MMA(1, 0, At, B0); PG8_MMA(1, 1, At, B1); PG8_BAR; PG8_SCHED;
;             PG8_LDB(B0, 1, 0); PG8_LDB(B1, 1, 1); PG8_SCHED; PG8_LDA(At, 1, 0); PG8_STAGE(PG8_SA(0, 1), a2 + hsA, voffA);
;             PG8_WAIT_V(8); PG8_WAIT_L(0); PG8_BAR; PG8_MMA(0, 0, At, B0); PG8_MMA(0, 1, At, B1); PG8_BAR; PG8_SCHED;
.LBB0_370:
	s_waitcnt lgkmcnt(0)
	s_add_i32 s71, s71, 2
	s_barrier
	s_setprio 1
	s_waitcnt lgkmcnt(0)
	v_mfma_f32_16x16x32_bf16 v[60:63], v[144:147], v[184:187], v[60:63]
	v_mfma_f32_16x16x32_bf16 v[56:59], v[152:155], v[184:187], v[56:59]
	v_mfma_f32_16x16x32_bf16 v[44:47], v[144:147], v[176:179], v[44:47]
	v_mfma_f32_16x16x32_bf16 v[40:43], v[152:155], v[176:179], v[40:43]
	v_mfma_f32_16x16x32_bf16 v[28:31], v[144:147], v[168:171], v[28:31]
	v_mfma_f32_16x16x32_bf16 v[24:27], v[152:155], v[168:171], v[24:27]
	v_mfma_f32_16x16x32_bf16 v[12:15], v[144:147], v[160:163], v[12:15]
	v_mfma_f32_16x16x32_bf16 v[8:11], v[152:155], v[160:163], v[8:11]
	v_mfma_f32_16x16x32_bf16 v[60:63], v[148:151], v[188:191], v[60:63]
	v_mfma_f32_16x16x32_bf16 v[56:59], v[156:159], v[188:191], v[56:59]
	v_mfma_f32_16x16x32_bf16 v[44:47], v[148:151], v[180:183], v[44:47]
	v_mfma_f32_16x16x32_bf16 v[40:43], v[156:159], v[180:183], v[40:43]
	v_mfma_f32_16x16x32_bf16 v[28:31], v[148:151], v[172:175], v[28:31]
	v_mfma_f32_16x16x32_bf16 v[24:27], v[156:159], v[172:175], v[24:27]
	v_mfma_f32_16x16x32_bf16 v[12:15], v[148:151], v[164:167], v[12:15]
	v_mfma_f32_16x16x32_bf16 v[8:11], v[156:159], v[164:167], v[8:11]
	s_setprio 0
	s_setprio 1
	v_mfma_f32_16x16x32_bf16 v[52:55], v[128:131], v[184:187], v[52:55]
	v_mfma_f32_16x16x32_bf16 v[48:51], v[136:139], v[184:187], v[48:51]
	v_mfma_f32_16x16x32_bf16 v[36:39], v[128:131], v[176:179], v[36:39]
	v_mfma_f32_16x16x32_bf16 v[32:35], v[136:139], v[176:179], v[32:35]
	v_mfma_f32_16x16x32_bf16 v[20:23], v[128:131], v[168:171], v[20:23]
	v_mfma_f32_16x16x32_bf16 v[16:19], v[136:139], v[168:171], v[16:19]
	v_mfma_f32_16x16x32_bf16 v[4:7], v[128:131], v[160:163], v[4:7]
	v_mfma_f32_16x16x32_bf16 v[0:3], v[136:139], v[160:163], v[0:3]
	v_mfma_f32_16x16x32_bf16 v[52:55], v[132:135], v[188:191], v[52:55]
	v_mfma_f32_16x16x32_bf16 v[48:51], v[140:143], v[188:191], v[48:51]
	v_mfma_f32_16x16x32_bf16 v[36:39], v[132:135], v[180:183], v[36:39]
	v_mfma_f32_16x16x32_bf16 v[32:35], v[140:143], v[180:183], v[32:35]
	v_mfma_f32_16x16x32_bf16 v[20:23], v[132:135], v[172:175], v[20:23]
	v_mfma_f32_16x16x32_bf16 v[16:19], v[140:143], v[172:175], v[16:19]
	v_mfma_f32_16x16x32_bf16 v[4:7], v[132:135], v[164:167], v[4:7]
	v_mfma_f32_16x16x32_bf16 v[0:3], v[140:143], v[164:167], v[0:3]
	s_setprio 0
	s_barrier
	s_add_i32 s36, 0, 0x18000
	s_add_i32 s37, 0, 0x1c000
	v_add_u32_e32 v140, s36, v235
	v_add_u32_e32 v156, s37, v235
	ds_read_b128 v[128:131], v140
	ds_read_b128 v[132:135], v140 offset:1024
	ds_read_b128 v[136:139], v140 offset:2048
	ds_read_b128 v[140:143], v140 offset:3072
	ds_read_b128 v[144:147], v156
	ds_read_b128 v[148:151], v156 offset:1024
	ds_read_b128 v[152:155], v156 offset:2048
	ds_read_b128 v[156:159], v156 offset:3072
	s_add_u32 s34, s34, 0x80000
	s_addc_u32 s35, s35, 0
	s_mov_b32 m0, s45
	ds_read_b128 v[160:163], v239 offset:32768
	ds_read_b128 v[164:167], v239 offset:33792
	ds_read_b128 v[168:171], v239 offset:34816
	ds_read_b128 v[172:175], v239 offset:35840
	ds_read_b128 v[176:179], v239 offset:36864
	ds_read_b128 v[180:183], v239 offset:37888
	ds_read_b128 v[184:187], v239 offset:38912
	ds_read_b128 v[188:191], v239 offset:39936
	global_load_lds_dwordx4 v194, s[34:35]
	s_mov_b32 m0, s46
	s_nop 0
	global_load_lds_dwordx4 v198, s[34:35]
	s_waitcnt vmcnt(8)
	s_waitcnt lgkmcnt(0)
	s_barrier
	s_setprio 1
	s_waitcnt lgkmcnt(0)
	v_mfma_f32_16x16x32_bf16 v[124:127], v[128:131], v[160:163], v[124:127]
	v_mfma_f32_16x16x32_bf16 v[120:123], v[136:139], v[160:163], v[120:123]
	v_mfma_f32_16x16x32_bf16 v[108:111], v[128:131], v[168:171], v[108:111]
	v_mfma_f32_16x16x32_bf16 v[104:107], v[136:139], v[168:171], v[104:107]
	v_mfma_f32_16x16x32_bf16 v[92:95], v[128:131], v[176:179], v[92:95]
	v_mfma_f32_16x16x32_bf16 v[88:91], v[136:139], v[176:179], v[88:91]
	v_mfma_f32_16x16x32_bf16 v[76:79], v[128:131], v[184:187], v[76:79]
	v_mfma_f32_16x16x32_bf16 v[72:75], v[136:139], v[184:187], v[72:75]
	v_mfma_f32_16x16x32_bf16 v[124:127], v[132:135], v[164:167], v[124:127]
	v_mfma_f32_16x16x32_bf16 v[120:123], v[140:143], v[164:167], v[120:123]
	v_mfma_f32_16x16x32_bf16 v[108:111], v[132:135], v[172:175], v[108:111]
	v_mfma_f32_16x16x32_bf16 v[104:107], v[140:143], v[172:175], v[104:107]
	v_mfma_f32_16x16x32_bf16 v[92:95], v[132:135], v[180:183], v[92:95]
	v_mfma_f32_16x16x32_bf16 v[88:91], v[140:143], v[180:183], v[88:91]
	v_mfma_f32_16x16x32_bf16 v[76:79], v[132:135], v[188:191], v[76:79]
	v_mfma_f32_16x16x32_bf16 v[72:75], v[140:143], v[188:191], v[72:75]
	s_setprio 0
	s_setprio 1
	v_mfma_f32_16x16x32_bf16 v[116:119], v[144:147], v[160:163], v[116:119]
	v_mfma_f32_16x16x32_bf16 v[112:115], v[152:155], v[160:163], v[112:115]
	v_mfma_f32_16x16x32_bf16 v[100:103], v[144:147], v[168:171], v[100:103]
	v_mfma_f32_16x16x32_bf16 v[96:99], v[152:155], v[168:171], v[96:99]
	v_mfma_f32_16x16x32_bf16 v[84:87], v[144:147], v[176:179], v[84:87]
	v_mfma_f32_16x16x32_bf16 v[80:83], v[152:155], v[176:179], v[80:83]
	v_mfma_f32_16x16x32_bf16 v[68:71], v[144:147], v[184:187], v[68:71]
	v_mfma_f32_16x16x32_bf16 v[64:67], v[152:155], v[184:187], v[64:67]
	v_mfma_f32_16x16x32_bf16 v[116:119], v[148:151], v[164:167], v[116:119]
	v_mfma_f32_16x16x32_bf16 v[112:115], v[156:159], v[164:167], v[112:115]
	v_mfma_f32_16x16x32_bf16 v[100:103], v[148:151], v[172:175], v[100:103]
	v_mfma_f32_16x16x32_bf16 v[96:99], v[156:159], v[172:175], v[96:99]
	v_mfma_f32_16x16x32_bf16 v[84:87], v[148:151], v[180:183], v[84:87]
	v_mfma_f32_16x16x32_bf16 v[80:83], v[156:159], v[180:183], v[80:83]
	v_mfma_f32_16x16x32_bf16 v[68:71], v[148:151], v[188:191], v[68:71]
	v_mfma_f32_16x16x32_bf16 v[64:67], v[156:159], v[188:191], v[64:67]
	s_setprio 0
	s_barrier
; #define PG8_STAGE(bufoff, gbase, voff) do { _Pragma("unroll") for (int _i = 0; _i < 2; ++_i) \
;         __builtin_amdgcn_global_load_lds((const unsigned*)((const char*)(gbase) + (voff)[_i]), (LAS unsigned*)(lds + (bufoff) + ldsw + _i * 8192), 16, 0, ((voff) == voffA ? AUXA : 0)); } while (0)
; #define PG8_LDA(dst, b, h) do { _Pragma("unroll") for (int m = 0; m < 4; ++m) _Pragma("unroll") for (int k = 0; k < 2; ++k) dst[m][k] = *(const LAS bf16x8*)(lds + PG8_SA(b, h) + aoff + m * 2048 + k * 1024); } while (0)
; #define PG8_LDB(dst, b, h) do { _Pragma("unroll") for (int n = 0; n < 2; ++n) _Pragma("unroll") for (int k = 0; k < 2; ++k) dst[n][k] = *(const LAS bf16x8*)(lds + PG8_SB(b, h) + boff + n * 2048 + k * 1024); } while (0)
; #define PG8_MMA(ai, bj, At, Bt) do { __builtin_amdgcn_s_setprio(1); _Pragma("unroll") for (int m = 0; m < 4; ++m) _Pragma("unroll") for (int n = 0; n < 2; ++n) _Pragma("unroll") for (int k = 0; k < 2; ++k) \
;         acc[ai][bj][m][n] = __builtin_amdgcn_mfma_f32_16x16x32_bf16(Bt[n][k], At[m][k], acc[ai][bj][m][n], 0, 0, 0); __builtin_amdgcn_s_setprio(0); } while (0)
; #define PG8_WAIT_V(n) asm volatile("s_waitcnt vmcnt(" #n ")" ::: "memory")
; #define PG8_WAIT_L(n) asm volatile("s_waitcnt lgkmcnt(" #n ")" ::: "memory")
; #define PG8_BAR __builtin_amdgcn_s_barrier()
; #define PG8_SCHED __builtin_amdgcn_sched_barrier(0)
;     ...
;             PG8_LDB(B0, 0, 0); PG8_LDB(B1, 0, 1); PG8_SCHED; PG8_LDA(At, 0, 0); PG8_STAGE(PG8_SA(1, 1), a1 + hsA, voffA);
;             if (Epi::NPRE != 0 && last) { E.pre(sv, cur, wr, fr); PG8_WAIT_V(16); } else { PG8_WAIT_V(8); }
;     ...
;             PG8_LDA(At, 1, 1); PG8_STAGE(PG8_SB(1, 0), b3, voffB); PG8_STAGE(PG8_SB(1, 1), b3 + hsB, voffB); PG8_STAGE(PG8_SA(1, 0), a3, voffA);
;             PG8_WAIT_V(8); PG8_WAIT_L(0); PG8_BAR; PG8_MMA(1, 0, At, B0); PG8_MMA(1, 1, At, B1); PG8_BAR; PG8_SCHED;
	s_add_i32 s34, s36, s5
	s_mov_b32 m0, s34
	ds_read_b128 v[160:163], v239 offset:49152
	ds_read_b128 v[164:167], v239 offset:50176
	ds_read_b128 v[168:171], v239 offset:51200
	ds_read_b128 v[172:175], v239 offset:52224
	ds_read_b128 v[176:179], v239 offset:53248
	ds_read_b128 v[180:183], v239 offset:54272
	ds_read_b128 v[184:187], v239 offset:55296
	ds_read_b128 v[188:191], v239 offset:56320
	global_load_lds_dwordx4 v196, s[98:99]
	s_add_i32 m0, s34, 0x2000
	s_add_u32 s30, s30, 0x80080
	s_addc_u32 s31, s31, 0
	s_add_i32 s34, s37, s5
	global_load_lds_dwordx4 v200, s[98:99]
	s_mov_b32 m0, s34
	s_nop 0
	global_load_lds_dwordx4 v196, s[30:31]
	s_add_i32 m0, s34, 0x2000
	s_nop 0
	global_load_lds_dwordx4 v200, s[30:31]
	s_mov_b32 m0, s50
	s_nop 0
	global_load_lds_dwordx4 v194, s[100:101]
	s_mov_b32 m0, s51
	s_nop 0
	global_load_lds_dwordx4 v198, s[100:101]
	s_waitcnt vmcnt(8)
	s_waitcnt lgkmcnt(0)
	s_barrier
	s_setprio 1
	s_waitcnt lgkmcnt(0)
	v_mfma_f32_16x16x32_bf16 v[60:63], v[128:131], v[160:163], v[60:63]
	v_mfma_f32_16x16x32_bf16 v[56:59], v[136:139], v[160:163], v[56:59]
	v_mfma_f32_16x16x32_bf16 v[44:47], v[128:131], v[168:171], v[44:47]
	v_mfma_f32_16x16x32_bf16 v[40:43], v[136:139], v[168:171], v[40:43]
	v_mfma_f32_16x16x32_bf16 v[28:31], v[128:131], v[176:179], v[28:31]
	v_mfma_f32_16x16x32_bf16 v[24:27], v[136:139], v[176:179], v[24:27]
	v_mfma_f32_16x16x32_bf16 v[12:15], v[128:131], v[184:187], v[12:15]
	v_mfma_f32_16x16x32_bf16 v[8:11], v[136:139], v[184:187], v[8:11]
	v_mfma_f32_16x16x32_bf16 v[60:63], v[132:135], v[164:167], v[60:63]
	v_mfma_f32_16x16x32_bf16 v[56:59], v[140:143], v[164:167], v[56:59]
	v_mfma_f32_16x16x32_bf16 v[44:47], v[132:135], v[172:175], v[44:47]
	v_mfma_f32_16x16x32_bf16 v[40:43], v[140:143], v[172:175], v[40:43]
	v_mfma_f32_16x16x32_bf16 v[28:31], v[132:135], v[180:183], v[28:31]
	v_mfma_f32_16x16x32_bf16 v[24:27], v[140:143], v[180:183], v[24:27]
	v_mfma_f32_16x16x32_bf16 v[12:15], v[132:135], v[188:191], v[12:15]
	v_mfma_f32_16x16x32_bf16 v[8:11], v[140:143], v[188:191], v[8:11]
	s_setprio 0
	s_setprio 1
	v_mfma_f32_16x16x32_bf16 v[52:55], v[144:147], v[160:163], v[52:55]
	v_mfma_f32_16x16x32_bf16 v[48:51], v[152:155], v[160:163], v[48:51]
	v_mfma_f32_16x16x32_bf16 v[36:39], v[144:147], v[168:171], v[36:39]
	v_mfma_f32_16x16x32_bf16 v[32:35], v[152:155], v[168:171], v[32:35]
	v_mfma_f32_16x16x32_bf16 v[20:23], v[144:147], v[176:179], v[20:23]
	v_mfma_f32_16x16x32_bf16 v[16:19], v[152:155], v[176:179], v[16:19]
	v_mfma_f32_16x16x32_bf16 v[4:7], v[144:147], v[184:187], v[4:7]
	v_mfma_f32_16x16x32_bf16 v[0:3], v[152:155], v[184:187], v[0:3]
	v_mfma_f32_16x16x32_bf16 v[52:55], v[148:151], v[164:167], v[52:55]
	v_mfma_f32_16x16x32_bf16 v[48:51], v[156:159], v[164:167], v[48:51]
	v_mfma_f32_16x16x32_bf16 v[36:39], v[148:151], v[172:175], v[36:39]
	v_mfma_f32_16x16x32_bf16 v[32:35], v[156:159], v[172:175], v[32:35]
	v_mfma_f32_16x16x32_bf16 v[20:23], v[148:151], v[180:183], v[20:23]
	v_mfma_f32_16x16x32_bf16 v[16:19], v[156:159], v[180:183], v[16:19]
	v_mfma_f32_16x16x32_bf16 v[4:7], v[148:151], v[188:191], v[4:7]
	v_mfma_f32_16x16x32_bf16 v[0:3], v[156:159], v[188:191], v[0:3]
	s_setprio 0
	s_barrier
	s_add_u32 s28, s28, 0x100
	s_addc_u32 s29, s29, 0
	s_add_u32 s69, s69, 0x100
	s_addc_u32 s70, s70, 0
	s_cmp_ge_i32 s71, s48
	s_cbranch_scc1 .LBB0_380
.LBB0_371:
	ds_read_b128 v[144:147], v237
	ds_read_b128 v[148:151], v237 offset:1024
	ds_read_b128 v[152:155], v237 offset:2048
	ds_read_b128 v[156:159], v237 offset:3072
	ds_read_b128 v[128:131], v238
	ds_read_b128 v[132:135], v238 offset:1024
	ds_read_b128 v[136:139], v238 offset:2048
	ds_read_b128 v[140:143], v238 offset:3072
	s_cmp_eq_u32 s53, s71
	s_cselect_b64 s[30:31], -1, 0
	s_cmp_lg_u32 s53, s71
	s_cselect_b64 s[36:37], -1, 0
	s_add_i32 m0, s13, 0xc000
	ds_read_b128 v[184:187], v239
	ds_read_b128 v[188:191], v239 offset:1024
	ds_read_b128 v[176:179], v239 offset:2048
	ds_read_b128 v[180:183], v239 offset:3072
	ds_read_b128 v[168:171], v239 offset:4096
	ds_read_b128 v[172:175], v239 offset:5120
	ds_read_b128 v[160:163], v239 offset:6144
	ds_read_b128 v[164:167], v239 offset:7168
	global_load_lds_dwordx4 v216, s[28:29]
	s_add_i32 m0, s13, 0xe000
	s_mov_b64 s[34:35], -1
	global_load_lds_dwordx4 v218, s[28:29]
	s_and_b64 vcc, exec, s[36:37]
	s_cbranch_vccz .LBB0_373
	s_waitcnt vmcnt(8)
	s_mov_b64 s[34:35], 0

; #define PG8_STAGE(bufoff, gbase, voff) do { _Pragma("unroll") for (int _i = 0; _i < 2; ++_i) \
;         __builtin_amdgcn_global_load_lds((const unsigned*)((const char*)(gbase) + (voff)[_i]), (LAS unsigned*)(lds + (bufoff) + ldsw + _i * 8192), 16, 0, ((voff) == voffA ? AUXA : 0)); } while (0)
; #define PG8_LDA(dst, b, h) do { _Pragma("unroll") for (int m = 0; m < 4; ++m) _Pragma("unroll") for (int k = 0; k < 2; ++k) dst[m][k] = *(const LAS bf16x8*)(lds + PG8_SA(b, h) + aoff + m * 2048 + k * 1024); } while (0)
; #define PG8_LDB(dst, b, h) do { _Pragma("unroll") for (int n = 0; n < 2; ++n) _Pragma("unroll") for (int k = 0; k < 2; ++k) dst[n][k] = *(const LAS bf16x8*)(lds + PG8_SB(b, h) + boff + n * 2048 + k * 1024); } while (0)
; #define PG8_MMA(ai, bj, At, Bt) do { __builtin_amdgcn_s_setprio(1); _Pragma("unroll") for (int m = 0; m < 4; ++m) _Pragma("unroll") for (int n = 0; n < 2; ++n) _Pragma("unroll") for (int k = 0; k < 2; ++k) \
;         acc[ai][bj][m][n] = __builtin_amdgcn_mfma_f32_16x16x32_bf16(Bt[n][k], At[m][k], acc[ai][bj][m][n], 0, 0, 0); __builtin_amdgcn_s_setprio(0); } while (0)
; #define PG8_WAIT_V(n) asm volatile("s_waitcnt vmcnt(" #n ")" ::: "memory")
; #define PG8_WAIT_L(n) asm volatile("s_waitcnt lgkmcnt(" #n ")" ::: "memory")
; #define PG8_BAR __builtin_amdgcn_s_barrier()
; #define PG8_SCHED __builtin_amdgcn_sched_barrier(0)
;     ...
;             const char* a2 = last ? nA : cA + (size_t)(t + 2) * kstep; const char* b2 = last ? nB : cB + (size_t)(t + 2) * kstep;
;             const char* a3 = a2 + kstep; const char* b3 = b2 + kstep;
;             PG8_LDB(B0, 0, 0); PG8_LDB(B1, 0, 1); PG8_SCHED; PG8_LDA(At, 0, 0); PG8_STAGE(PG8_SA(1, 1), a1 + hsA, voffA);
;             if (Epi::NPRE != 0 && last) { E.pre(sv, cur, wr, fr); PG8_WAIT_V(16); } else { PG8_WAIT_V(8); }
;             PG8_WAIT_L(0); PG8_BAR; PG8_MMA(0, 0, At, B0); PG8_MMA(0, 1, At, B1); PG8_BAR; PG8_SCHED;
;             PG8_LDA(At, 0, 1); PG8_STAGE(PG8_SB(0, 0), b2, voffB); PG8_STAGE(PG8_SB(0, 1), b2 + hsB, voffB); PG8_STAGE(PG8_SA(0, 0), a2, voffA);
;             if (Epi::NPRE != 0 && last) { PG8_WAIT_V(16); } else { PG8_WAIT_V(8); }
.LBB0_375:
	s_add_u32 s34, s28, 0xfff80080
	s_addc_u32 s35, s29, -1
	s_waitcnt lgkmcnt(0)
	s_and_b64 s[30:31], s[30:31], exec
	s_cselect_b32 s35, s7, s35
	s_cselect_b32 s34, s21, s34
	s_cselect_b32 s31, s23, s70
	s_cselect_b32 s30, s68, s69
	s_barrier
	s_setprio 1
	s_waitcnt lgkmcnt(0)
	v_mfma_f32_16x16x32_bf16 v[124:127], v[144:147], v[184:187], v[124:127]
	v_mfma_f32_16x16x32_bf16 v[120:123], v[152:155], v[184:187], v[120:123]
	v_mfma_f32_16x16x32_bf16 v[108:111], v[144:147], v[176:179], v[108:111]
	v_mfma_f32_16x16x32_bf16 v[104:107], v[152:155], v[176:179], v[104:107]
	v_mfma_f32_16x16x32_bf16 v[92:95], v[144:147], v[168:171], v[92:95]
	v_mfma_f32_16x16x32_bf16 v[88:91], v[152:155], v[168:171], v[88:91]
	v_mfma_f32_16x16x32_bf16 v[76:79], v[144:147], v[160:163], v[76:79]
	v_mfma_f32_16x16x32_bf16 v[72:75], v[152:155], v[160:163], v[72:75]
	v_mfma_f32_16x16x32_bf16 v[124:127], v[148:151], v[188:191], v[124:127]
	v_mfma_f32_16x16x32_bf16 v[120:123], v[156:159], v[188:191], v[120:123]
	v_mfma_f32_16x16x32_bf16 v[108:111], v[148:151], v[180:183], v[108:111]
	v_mfma_f32_16x16x32_bf16 v[104:107], v[156:159], v[180:183], v[104:107]
	v_mfma_f32_16x16x32_bf16 v[92:95], v[148:151], v[172:175], v[92:95]
	v_mfma_f32_16x16x32_bf16 v[88:91], v[156:159], v[172:175], v[88:91]
	v_mfma_f32_16x16x32_bf16 v[76:79], v[148:151], v[164:167], v[76:79]
	v_mfma_f32_16x16x32_bf16 v[72:75], v[156:159], v[164:167], v[72:75]
	s_setprio 0
	s_setprio 1
	v_mfma_f32_16x16x32_bf16 v[116:119], v[128:131], v[184:187], v[116:119]
	v_mfma_f32_16x16x32_bf16 v[112:115], v[136:139], v[184:187], v[112:115]
	v_mfma_f32_16x16x32_bf16 v[100:103], v[128:131], v[176:179], v[100:103]
	v_mfma_f32_16x16x32_bf16 v[96:99], v[136:139], v[176:179], v[96:99]
	v_mfma_f32_16x16x32_bf16 v[84:87], v[128:131], v[168:171], v[84:87]
	v_mfma_f32_16x16x32_bf16 v[80:83], v[136:139], v[168:171], v[80:83]
	v_mfma_f32_16x16x32_bf16 v[68:71], v[128:131], v[160:163], v[68:71]
	v_mfma_f32_16x16x32_bf16 v[64:67], v[136:139], v[160:163], v[64:67]
	v_mfma_f32_16x16x32_bf16 v[116:119], v[132:135], v[188:191], v[116:119]
	v_mfma_f32_16x16x32_bf16 v[112:115], v[140:143], v[188:191], v[112:115]
	v_mfma_f32_16x16x32_bf16 v[100:103], v[132:135], v[180:183], v[100:103]
	v_mfma_f32_16x16x32_bf16 v[96:99], v[140:143], v[180:183], v[96:99]
	v_mfma_f32_16x16x32_bf16 v[84:87], v[132:135], v[172:175], v[84:87]
	v_mfma_f32_16x16x32_bf16 v[80:83], v[140:143], v[172:175], v[80:83]
	v_mfma_f32_16x16x32_bf16 v[68:71], v[132:135], v[164:167], v[68:71]
	v_mfma_f32_16x16x32_bf16 v[64:67], v[140:143], v[164:167], v[64:67]
	s_setprio 0
	s_barrier
	s_add_u32 s98, s30, s10
	s_addc_u32 s99, s31, s11
	s_add_u32 s100, s34, s10
	s_addc_u32 s101, s35, s11
	s_mov_b32 m0, s40
	s_add_u32 s38, s30, 0x80000
	ds_read_b128 v[184:187], v239 offset:16384
	ds_read_b128 v[188:191], v239 offset:17408
	ds_read_b128 v[176:179], v239 offset:18432
	ds_read_b128 v[180:183], v239 offset:19456
	ds_read_b128 v[168:171], v239 offset:20480
	ds_read_b128 v[172:175], v239 offset:21504
	ds_read_b128 v[160:163], v239 offset:22528
	ds_read_b128 v[164:167], v239 offset:23552
	global_load_lds_dwordx4 v196, s[30:31]
	s_mov_b32 m0, s41
	s_addc_u32 s39, s31, 0
	global_load_lds_dwordx4 v200, s[30:31]
	s_mov_b32 m0, s42
	s_nop 0
	global_load_lds_dwordx4 v196, s[38:39]
	s_mov_b32 m0, s43
	s_nop 0
	global_load_lds_dwordx4 v200, s[38:39]
	s_mov_b64 s[38:39], -1
	s_mov_b32 m0, s13
	s_and_b64 vcc, exec, s[36:37]
	global_load_lds_dwordx4 v194, s[34:35]
	s_mov_b32 m0, s44
	s_nop 0
	global_load_lds_dwordx4 v198, s[34:35]
	s_cbranch_vccz .LBB0_377
	s_waitcnt vmcnt(8)
	s_mov_b64 s[38:39], 0

; #define PG8_STAGE(bufoff, gbase, voff) do { _Pragma("unroll") for (int _i = 0; _i < 2; ++_i) \
;         __builtin_amdgcn_global_load_lds((const unsigned*)((const char*)(gbase) + (voff)[_i]), (LAS unsigned*)(lds + (bufoff) + ldsw + _i * 8192), 16, 0, ((voff) == voffA ? AUXA : 0)); } while (0)
; #define PG8_LDA(dst, b, h) do { _Pragma("unroll") for (int m = 0; m < 4; ++m) _Pragma("unroll") for (int k = 0; k < 2; ++k) dst[m][k] = *(const LAS bf16x8*)(lds + PG8_SA(b, h) + aoff + m * 2048 + k * 1024); } while (0)
; #define PG8_LDB(dst, b, h) do { _Pragma("unroll") for (int n = 0; n < 2; ++n) _Pragma("unroll") for (int k = 0; k < 2; ++k) dst[n][k] = *(const LAS bf16x8*)(lds + PG8_SB(b, h) + boff + n * 2048 + k * 1024); } while (0)
; #define PG8_MMA(ai, bj, At, Bt) do { __builtin_amdgcn_s_setprio(1); _Pragma("unroll") for (int m = 0; m < 4; ++m) _Pragma("unroll") for (int n = 0; n < 2; ++n) _Pragma("unroll") for (int k = 0; k < 2; ++k) \
;         acc[ai][bj][m][n] = __builtin_amdgcn_mfma_f32_16x16x32_bf16(Bt[n][k], At[m][k], acc[ai][bj][m][n], 0, 0, 0); __builtin_amdgcn_s_setprio(0); } while (0)
; #define PG8_WAIT_V(n) asm volatile("s_waitcnt vmcnt(" #n ")" ::: "memory")
; #define PG8_WAIT_L(n) asm volatile("s_waitcnt lgkmcnt(" #n ")" ::: "memory")
; #define PG8_BAR __builtin_amdgcn_s_barrier()
; #define PG8_SCHED __builtin_amdgcn_sched_barrier(0)
;     ...
;             const bool last = (t == nt - 2);
;             const char* a1 = cA + (size_t)(t + 1) * kstep;
;             const char* a2 = last ? nA : cA + (size_t)(t + 2) * kstep; const char* b2 = last ? nB : cB + (size_t)(t + 2) * kstep;
;             const char* a3 = a2 + kstep; const char* b3 = b2 + kstep;
;             PG8_LDB(B0, 0, 0); PG8_LDB(B1, 0, 1); PG8_SCHED; PG8_LDA(At, 0, 0); PG8_STAGE(PG8_SA(1, 1), a1 + hsA, voffA);
;             if (Epi::NPRE != 0 && last) { E.pre(sv, cur, wr, fr); PG8_WAIT_V(16); } else { PG8_WAIT_V(8); }
;             PG8_WAIT_L(0); PG8_BAR; PG8_MMA(0, 0, At, B0); PG8_MMA(0, 1, At, B1); PG8_BAR; PG8_SCHED;
;             PG8_LDA(At, 0, 1); PG8_STAGE(PG8_SB(0, 0), b2, voffB); PG8_STAGE(PG8_SB(0, 1), b2 + hsB, voffB); PG8_STAGE(PG8_SA(0, 0), a2, voffA);
;             if (Epi::NPRE != 0 && last) { PG8_WAIT_V(16); } else { PG8_WAIT_V(8); }
;             PG8_WAIT_L(0); PG8_BAR; PG8_MMA(1, 0, At, B0); PG8_MMA(1, 1, At, B1); PG8_BAR; PG8_SCHED;
.LBB0_648:
	ds_read_b128 v[148:151], v143
	ds_read_b128 v[152:155], v143 offset:1024
	ds_read_b128 v[156:159], v143 offset:2048
	ds_read_b128 v[160:163], v143 offset:3072
	ds_read_b128 v[164:167], v144
	ds_read_b128 v[168:171], v144 offset:1024
	ds_read_b128 v[172:175], v144 offset:2048
	ds_read_b128 v[176:179], v144 offset:3072
	s_add_i32 s56, s24, 2
	s_add_u32 s25, s22, 0xfffe0080
	s_addc_u32 s26, s23, -1
	s_cmp_eq_u32 s38, s24
	s_cselect_b32 s24, s53, s54
	s_cselect_b32 s27, s50, s26
	s_cselect_b32 s26, s51, s25
	s_cselect_b32 s25, s52, s55
	s_mov_b32 m0, s39
	ds_read_b128 v[180:183], v145
	ds_read_b128 v[184:187], v145 offset:1024
	ds_read_b128 v[188:191], v145 offset:2048
	ds_read_b128 v[194:197], v145 offset:3072
	ds_read_b128 v[198:201], v145 offset:4096
	ds_read_b128 v[202:205], v145 offset:5120
	ds_read_b128 v[206:209], v145 offset:6144
	ds_read_b128 v[210:213], v145 offset:7168
	global_load_lds_dwordx4 v138, s[22:23]
	s_mov_b32 m0, s40
	s_nop 0
	global_load_lds_dwordx4 v140, s[22:23]
	s_waitcnt vmcnt(8)
	s_waitcnt lgkmcnt(0)
	s_barrier
	s_setprio 1
	s_waitcnt lgkmcnt(0)
	v_mfma_f32_16x16x32_bf16 v[124:127], v[148:151], v[180:183], v[124:127]
	v_mfma_f32_16x16x32_bf16 v[120:123], v[156:159], v[180:183], v[120:123]
	v_mfma_f32_16x16x32_bf16 v[108:111], v[148:151], v[188:191], v[108:111]
	v_mfma_f32_16x16x32_bf16 v[104:107], v[156:159], v[188:191], v[104:107]
	v_mfma_f32_16x16x32_bf16 v[92:95], v[148:151], v[198:201], v[92:95]
	v_mfma_f32_16x16x32_bf16 v[88:91], v[156:159], v[198:201], v[88:91]
	v_mfma_f32_16x16x32_bf16 v[76:79], v[148:151], v[206:209], v[76:79]
	v_mfma_f32_16x16x32_bf16 v[72:75], v[156:159], v[206:209], v[72:75]
	v_mfma_f32_16x16x32_bf16 v[124:127], v[152:155], v[184:187], v[124:127]
	v_mfma_f32_16x16x32_bf16 v[120:123], v[160:163], v[184:187], v[120:123]
	v_mfma_f32_16x16x32_bf16 v[108:111], v[152:155], v[194:197], v[108:111]
	v_mfma_f32_16x16x32_bf16 v[104:107], v[160:163], v[194:197], v[104:107]
	v_mfma_f32_16x16x32_bf16 v[92:95], v[152:155], v[202:205], v[92:95]
	v_mfma_f32_16x16x32_bf16 v[88:91], v[160:163], v[202:205], v[88:91]
	v_mfma_f32_16x16x32_bf16 v[76:79], v[152:155], v[210:213], v[76:79]
	v_mfma_f32_16x16x32_bf16 v[72:75], v[160:163], v[210:213], v[72:75]
	s_setprio 0
	s_setprio 1
	v_mfma_f32_16x16x32_bf16 v[116:119], v[164:167], v[180:183], v[116:119]
	v_mfma_f32_16x16x32_bf16 v[112:115], v[172:175], v[180:183], v[112:115]
	v_mfma_f32_16x16x32_bf16 v[100:103], v[164:167], v[188:191], v[100:103]
	v_mfma_f32_16x16x32_bf16 v[96:99], v[172:175], v[188:191], v[96:99]
	v_mfma_f32_16x16x32_bf16 v[84:87], v[164:167], v[198:201], v[84:87]
	v_mfma_f32_16x16x32_bf16 v[80:83], v[172:175], v[198:201], v[80:83]
	v_mfma_f32_16x16x32_bf16 v[68:71], v[164:167], v[206:209], v[68:71]
	v_mfma_f32_16x16x32_bf16 v[64:67], v[172:175], v[206:209], v[64:67]
	v_mfma_f32_16x16x32_bf16 v[116:119], v[168:171], v[184:187], v[116:119]
	v_mfma_f32_16x16x32_bf16 v[112:115], v[176:179], v[184:187], v[112:115]
	v_mfma_f32_16x16x32_bf16 v[100:103], v[168:171], v[194:197], v[100:103]
	v_mfma_f32_16x16x32_bf16 v[96:99], v[176:179], v[194:197], v[96:99]
	v_mfma_f32_16x16x32_bf16 v[84:87], v[168:171], v[202:205], v[84:87]
	v_mfma_f32_16x16x32_bf16 v[80:83], v[176:179], v[202:205], v[80:83]
	v_mfma_f32_16x16x32_bf16 v[68:71], v[168:171], v[210:213], v[68:71]
	v_mfma_f32_16x16x32_bf16 v[64:67], v[176:179], v[210:213], v[64:67]
	s_setprio 0
	s_barrier
	s_add_u32 s98, s24, s12
	s_addc_u32 s99, s25, s13
	s_add_u32 s100, s26, s12
	s_addc_u32 s101, s27, s13
	s_mov_b32 m0, s41
	s_add_u32 s66, s24, 0x10000
	ds_read_b128 v[180:183], v145 offset:16384
	ds_read_b128 v[184:187], v145 offset:17408
	ds_read_b128 v[188:191], v145 offset:18432
	ds_read_b128 v[194:197], v145 offset:19456
	ds_read_b128 v[198:201], v145 offset:20480
	ds_read_b128 v[202:205], v145 offset:21504
	ds_read_b128 v[206:209], v145 offset:22528
	ds_read_b128 v[210:213], v145 offset:23552
	global_load_lds_dwordx4 v132, s[24:25]
	s_mov_b32 m0, s42
	s_addc_u32 s67, s25, 0
	global_load_lds_dwordx4 v128, s[24:25]
	s_mov_b32 m0, s43
	s_nop 0
	global_load_lds_dwordx4 v132, s[66:67]
	s_mov_b32 m0, s44
	s_nop 0
	global_load_lds_dwordx4 v128, s[66:67]
	s_mov_b32 m0, s3
	s_nop 0
	global_load_lds_dwordx4 v134, s[26:27]
	s_mov_b32 m0, s29
	s_nop 0
	global_load_lds_dwordx4 v130, s[26:27]
	s_waitcnt vmcnt(8)
	s_waitcnt lgkmcnt(0)
	s_barrier
	s_setprio 1
	s_waitcnt lgkmcnt(0)
	v_mfma_f32_16x16x32_bf16 v[60:63], v[148:151], v[180:183], v[60:63]
	v_mfma_f32_16x16x32_bf16 v[56:59], v[156:159], v[180:183], v[56:59]
	v_mfma_f32_16x16x32_bf16 v[44:47], v[148:151], v[188:191], v[44:47]
	v_mfma_f32_16x16x32_bf16 v[40:43], v[156:159], v[188:191], v[40:43]
	v_mfma_f32_16x16x32_bf16 v[28:31], v[148:151], v[198:201], v[28:31]
	v_mfma_f32_16x16x32_bf16 v[24:27], v[156:159], v[198:201], v[24:27]
	v_mfma_f32_16x16x32_bf16 v[12:15], v[148:151], v[206:209], v[12:15]
	v_mfma_f32_16x16x32_bf16 v[8:11], v[156:159], v[206:209], v[8:11]
	v_mfma_f32_16x16x32_bf16 v[60:63], v[152:155], v[184:187], v[60:63]
	v_mfma_f32_16x16x32_bf16 v[56:59], v[160:163], v[184:187], v[56:59]
	v_mfma_f32_16x16x32_bf16 v[44:47], v[152:155], v[194:197], v[44:47]
	v_mfma_f32_16x16x32_bf16 v[40:43], v[160:163], v[194:197], v[40:43]
	v_mfma_f32_16x16x32_bf16 v[28:31], v[152:155], v[202:205], v[28:31]
	v_mfma_f32_16x16x32_bf16 v[24:27], v[160:163], v[202:205], v[24:27]
	v_mfma_f32_16x16x32_bf16 v[12:15], v[152:155], v[210:213], v[12:15]
	v_mfma_f32_16x16x32_bf16 v[8:11], v[160:163], v[210:213], v[8:11]
	s_setprio 0
	s_setprio 1
	v_mfma_f32_16x16x32_bf16 v[52:55], v[164:167], v[180:183], v[52:55]
	v_mfma_f32_16x16x32_bf16 v[48:51], v[172:175], v[180:183], v[48:51]
	v_mfma_f32_16x16x32_bf16 v[36:39], v[164:167], v[188:191], v[36:39]
	v_mfma_f32_16x16x32_bf16 v[32:35], v[172:175], v[188:191], v[32:35]
	v_mfma_f32_16x16x32_bf16 v[20:23], v[164:167], v[198:201], v[20:23]
	v_mfma_f32_16x16x32_bf16 v[16:19], v[172:175], v[198:201], v[16:19]
	v_mfma_f32_16x16x32_bf16 v[4:7], v[164:167], v[206:209], v[4:7]
	v_mfma_f32_16x16x32_bf16 v[0:3], v[172:175], v[206:209], v[0:3]
	v_mfma_f32_16x16x32_bf16 v[52:55], v[168:171], v[184:187], v[52:55]
	v_mfma_f32_16x16x32_bf16 v[48:51], v[176:179], v[184:187], v[48:51]
	v_mfma_f32_16x16x32_bf16 v[36:39], v[168:171], v[194:197], v[36:39]
	v_mfma_f32_16x16x32_bf16 v[32:35], v[176:179], v[194:197], v[32:35]
	v_mfma_f32_16x16x32_bf16 v[20:23], v[168:171], v[202:205], v[20:23]
	v_mfma_f32_16x16x32_bf16 v[16:19], v[176:179], v[202:205], v[16:19]
	v_mfma_f32_16x16x32_bf16 v[4:7], v[168:171], v[210:213], v[4:7]
	v_mfma_f32_16x16x32_bf16 v[0:3], v[176:179], v[210:213], v[0:3]
	s_setprio 0
	s_barrier
; #define PG8_STAGE(bufoff, gbase, voff) do { _Pragma("unroll") for (int _i = 0; _i < 2; ++_i) \
;         __builtin_amdgcn_global_load_lds((const unsigned*)((const char*)(gbase) + (voff)[_i]), (LAS unsigned*)(lds + (bufoff) + ldsw + _i * 8192), 16, 0, ((voff) == voffA ? AUXA : 0)); } while (0)
; #define PG8_LDA(dst, b, h) do { _Pragma("unroll") for (int m = 0; m < 4; ++m) _Pragma("unroll") for (int k = 0; k < 2; ++k) dst[m][k] = *(const LAS bf16x8*)(lds + PG8_SA(b, h) + aoff + m * 2048 + k * 1024); } while (0)
; #define PG8_LDB(dst, b, h) do { _Pragma("unroll") for (int n = 0; n < 2; ++n) _Pragma("unroll") for (int k = 0; k < 2; ++k) dst[n][k] = *(const LAS bf16x8*)(lds + PG8_SB(b, h) + boff + n * 2048 + k * 1024); } while (0)
; #define PG8_MMA(ai, bj, At, Bt) do { __builtin_amdgcn_s_setprio(1); _Pragma("unroll") for (int m = 0; m < 4; ++m) _Pragma("unroll") for (int n = 0; n < 2; ++n) _Pragma("unroll") for (int k = 0; k < 2; ++k) \
;         acc[ai][bj][m][n] = __builtin_amdgcn_mfma_f32_16x16x32_bf16(Bt[n][k], At[m][k], acc[ai][bj][m][n], 0, 0, 0); __builtin_amdgcn_s_setprio(0); } while (0)
; #define PG8_WAIT_V(n) asm volatile("s_waitcnt vmcnt(" #n ")" ::: "memory")
; #define PG8_WAIT_L(n) asm volatile("s_waitcnt lgkmcnt(" #n ")" ::: "memory")
; #define PG8_BAR __builtin_amdgcn_s_barrier()
; #define PG8_SCHED __builtin_amdgcn_sched_barrier(0)
;     ...
;             PG8_LDB(B0, 1, 0); PG8_LDB(B1, 1, 1); PG8_SCHED; PG8_LDA(At, 1, 0); PG8_STAGE(PG8_SA(0, 1), a2 + hsA, voffA);
;             PG8_WAIT_V(8); PG8_WAIT_L(0); PG8_BAR; PG8_MMA(0, 0, At, B0); PG8_MMA(0, 1, At, B1); PG8_BAR; PG8_SCHED;
;             PG8_LDA(At, 1, 1); PG8_STAGE(PG8_SB(1, 0), b3, voffB); PG8_STAGE(PG8_SB(1, 1), b3 + hsB, voffB); PG8_STAGE(PG8_SA(1, 0), a3, voffA);
;             PG8_WAIT_V(8); PG8_WAIT_L(0); PG8_BAR; PG8_MMA(1, 0, At, B0); PG8_MMA(1, 1, At, B1); PG8_BAR; PG8_SCHED;
;         }
	ds_read_b128 v[148:151], v146
	ds_read_b128 v[152:155], v146 offset:1024
	ds_read_b128 v[156:159], v146 offset:2048
	ds_read_b128 v[160:163], v146 offset:3072
	ds_read_b128 v[164:167], v147
	ds_read_b128 v[168:171], v147 offset:1024
	ds_read_b128 v[172:175], v147 offset:2048
	ds_read_b128 v[176:179], v147 offset:3072
	s_add_u32 s26, s26, 0x20000
	s_addc_u32 s27, s27, 0
	s_mov_b32 m0, s30
	ds_read_b128 v[180:183], v145 offset:32768
	ds_read_b128 v[184:187], v145 offset:33792
	ds_read_b128 v[188:191], v145 offset:34816
	ds_read_b128 v[194:197], v145 offset:35840
	ds_read_b128 v[198:201], v145 offset:36864
	ds_read_b128 v[202:205], v145 offset:37888
	ds_read_b128 v[206:209], v145 offset:38912
	ds_read_b128 v[210:213], v145 offset:39936
	global_load_lds_dwordx4 v134, s[26:27]
	s_mov_b32 m0, s31
	s_nop 0
	global_load_lds_dwordx4 v130, s[26:27]
	s_waitcnt vmcnt(8)
	s_waitcnt lgkmcnt(0)
	s_barrier
	s_setprio 1
	s_waitcnt lgkmcnt(0)
	v_mfma_f32_16x16x32_bf16 v[124:127], v[148:151], v[180:183], v[124:127]
	v_mfma_f32_16x16x32_bf16 v[120:123], v[156:159], v[180:183], v[120:123]
	v_mfma_f32_16x16x32_bf16 v[108:111], v[148:151], v[188:191], v[108:111]
	v_mfma_f32_16x16x32_bf16 v[104:107], v[156:159], v[188:191], v[104:107]
	v_mfma_f32_16x16x32_bf16 v[92:95], v[148:151], v[198:201], v[92:95]
	v_mfma_f32_16x16x32_bf16 v[88:91], v[156:159], v[198:201], v[88:91]
	v_mfma_f32_16x16x32_bf16 v[76:79], v[148:151], v[206:209], v[76:79]
	v_mfma_f32_16x16x32_bf16 v[72:75], v[156:159], v[206:209], v[72:75]
	v_mfma_f32_16x16x32_bf16 v[124:127], v[152:155], v[184:187], v[124:127]
	v_mfma_f32_16x16x32_bf16 v[120:123], v[160:163], v[184:187], v[120:123]
	v_mfma_f32_16x16x32_bf16 v[108:111], v[152:155], v[194:197], v[108:111]
	v_mfma_f32_16x16x32_bf16 v[104:107], v[160:163], v[194:197], v[104:107]
	v_mfma_f32_16x16x32_bf16 v[92:95], v[152:155], v[202:205], v[92:95]
	v_mfma_f32_16x16x32_bf16 v[88:91], v[160:163], v[202:205], v[88:91]
	v_mfma_f32_16x16x32_bf16 v[76:79], v[152:155], v[210:213], v[76:79]
	v_mfma_f32_16x16x32_bf16 v[72:75], v[160:163], v[210:213], v[72:75]
	s_setprio 0
	s_setprio 1
	v_mfma_f32_16x16x32_bf16 v[116:119], v[164:167], v[180:183], v[116:119]
	v_mfma_f32_16x16x32_bf16 v[112:115], v[172:175], v[180:183], v[112:115]
	v_mfma_f32_16x16x32_bf16 v[100:103], v[164:167], v[188:191], v[100:103]
	v_mfma_f32_16x16x32_bf16 v[96:99], v[172:175], v[188:191], v[96:99]
	v_mfma_f32_16x16x32_bf16 v[84:87], v[164:167], v[198:201], v[84:87]
	v_mfma_f32_16x16x32_bf16 v[80:83], v[172:175], v[198:201], v[80:83]
	v_mfma_f32_16x16x32_bf16 v[68:71], v[164:167], v[206:209], v[68:71]
	v_mfma_f32_16x16x32_bf16 v[64:67], v[172:175], v[206:209], v[64:67]
	v_mfma_f32_16x16x32_bf16 v[116:119], v[168:171], v[184:187], v[116:119]
	v_mfma_f32_16x16x32_bf16 v[112:115], v[176:179], v[184:187], v[112:115]
	v_mfma_f32_16x16x32_bf16 v[100:103], v[168:171], v[194:197], v[100:103]
	v_mfma_f32_16x16x32_bf16 v[96:99], v[176:179], v[194:197], v[96:99]
	v_mfma_f32_16x16x32_bf16 v[84:87], v[168:171], v[202:205], v[84:87]
	v_mfma_f32_16x16x32_bf16 v[80:83], v[176:179], v[202:205], v[80:83]
	v_mfma_f32_16x16x32_bf16 v[68:71], v[168:171], v[210:213], v[68:71]
	v_mfma_f32_16x16x32_bf16 v[64:67], v[176:179], v[210:213], v[64:67]
	s_setprio 0
	s_barrier
	s_add_i32 s26, s45, s28
	s_mov_b32 m0, s26
	ds_read_b128 v[180:183], v145 offset:49152
	ds_read_b128 v[184:187], v145 offset:50176
	ds_read_b128 v[188:191], v145 offset:51200
	ds_read_b128 v[194:197], v145 offset:52224
	ds_read_b128 v[198:201], v145 offset:53248
	ds_read_b128 v[202:205], v145 offset:54272
	ds_read_b128 v[206:209], v145 offset:55296
	ds_read_b128 v[210:213], v145 offset:56320
	global_load_lds_dwordx4 v132, s[98:99]
	s_add_i32 m0, s26, 0x2000
	s_add_u32 s24, s24, 0x10080
	s_addc_u32 s25, s25, 0
	s_add_i32 s26, s46, s28
	global_load_lds_dwordx4 v128, s[98:99]
	s_mov_b32 m0, s26
	s_nop 0
	global_load_lds_dwordx4 v132, s[24:25]
	s_add_i32 m0, s26, 0x2000
	s_nop 0
	global_load_lds_dwordx4 v128, s[24:25]
	s_mov_b32 m0, s36
	s_nop 0
	global_load_lds_dwordx4 v134, s[100:101]
	s_mov_b32 m0, s37
	s_nop 0
	global_load_lds_dwordx4 v130, s[100:101]
	s_waitcnt vmcnt(8)
	s_waitcnt lgkmcnt(0)
	s_barrier
	s_setprio 1
	s_waitcnt lgkmcnt(0)
	v_mfma_f32_16x16x32_bf16 v[60:63], v[148:151], v[180:183], v[60:63]
	v_mfma_f32_16x16x32_bf16 v[56:59], v[156:159], v[180:183], v[56:59]
	v_mfma_f32_16x16x32_bf16 v[44:47], v[148:151], v[188:191], v[44:47]
	v_mfma_f32_16x16x32_bf16 v[40:43], v[156:159], v[188:191], v[40:43]
	v_mfma_f32_16x16x32_bf16 v[28:31], v[148:151], v[198:201], v[28:31]
	v_mfma_f32_16x16x32_bf16 v[24:27], v[156:159], v[198:201], v[24:27]
	v_mfma_f32_16x16x32_bf16 v[12:15], v[148:151], v[206:209], v[12:15]
	v_mfma_f32_16x16x32_bf16 v[8:11], v[156:159], v[206:209], v[8:11]
	v_mfma_f32_16x16x32_bf16 v[60:63], v[152:155], v[184:187], v[60:63]
	v_mfma_f32_16x16x32_bf16 v[56:59], v[160:163], v[184:187], v[56:59]
	v_mfma_f32_16x16x32_bf16 v[44:47], v[152:155], v[194:197], v[44:47]
	v_mfma_f32_16x16x32_bf16 v[40:43], v[160:163], v[194:197], v[40:43]
	v_mfma_f32_16x16x32_bf16 v[28:31], v[152:155], v[202:205], v[28:31]
	v_mfma_f32_16x16x32_bf16 v[24:27], v[160:163], v[202:205], v[24:27]
	v_mfma_f32_16x16x32_bf16 v[12:15], v[152:155], v[210:213], v[12:15]
	v_mfma_f32_16x16x32_bf16 v[8:11], v[160:163], v[210:213], v[8:11]
	s_setprio 0
	s_setprio 1
	v_mfma_f32_16x16x32_bf16 v[52:55], v[164:167], v[180:183], v[52:55]
	v_mfma_f32_16x16x32_bf16 v[48:51], v[172:175], v[180:183], v[48:51]
	v_mfma_f32_16x16x32_bf16 v[36:39], v[164:167], v[188:191], v[36:39]
	v_mfma_f32_16x16x32_bf16 v[32:35], v[172:175], v[188:191], v[32:35]
	v_mfma_f32_16x16x32_bf16 v[20:23], v[164:167], v[198:201], v[20:23]
	v_mfma_f32_16x16x32_bf16 v[16:19], v[172:175], v[198:201], v[16:19]
	v_mfma_f32_16x16x32_bf16 v[4:7], v[164:167], v[206:209], v[4:7]
	v_mfma_f32_16x16x32_bf16 v[0:3], v[172:175], v[206:209], v[0:3]
	v_mfma_f32_16x16x32_bf16 v[52:55], v[168:171], v[184:187], v[52:55]
	v_mfma_f32_16x16x32_bf16 v[48:51], v[176:179], v[184:187], v[48:51]
	v_mfma_f32_16x16x32_bf16 v[36:39], v[168:171], v[194:197], v[36:39]
	v_mfma_f32_16x16x32_bf16 v[32:35], v[176:179], v[194:197], v[32:35]
	v_mfma_f32_16x16x32_bf16 v[20:23], v[168:171], v[202:205], v[20:23]
	v_mfma_f32_16x16x32_bf16 v[16:19], v[176:179], v[202:205], v[16:19]
	v_mfma_f32_16x16x32_bf16 v[4:7], v[168:171], v[210:213], v[4:7]
	v_mfma_f32_16x16x32_bf16 v[0:3], v[176:179], v[210:213], v[0:3]
	s_setprio 0
	s_barrier
	s_add_u32 s22, s22, 0x100
	s_addc_u32 s23, s23, 0
	s_add_u32 s54, s54, 0x100
	s_addc_u32 s55, s55, 0
	s_cmp_ge_i32 s56, s35
	s_mov_b32 s24, s56
	s_cbranch_scc0 .LBB0_648

; #define PG8_STAGE(bufoff, gbase, voff) do { _Pragma("unroll") for (int _i = 0; _i < 2; ++_i) \
;         __builtin_amdgcn_global_load_lds((const unsigned*)((const char*)(gbase) + (voff)[_i]), (LAS unsigned*)(lds + (bufoff) + ldsw + _i * 8192), 16, 0, ((voff) == voffA ? AUXA : 0)); } while (0)
; #define PG8_LDA(dst, b, h) do { _Pragma("unroll") for (int m = 0; m < 4; ++m) _Pragma("unroll") for (int k = 0; k < 2; ++k) dst[m][k] = *(const LAS bf16x8*)(lds + PG8_SA(b, h) + aoff + m * 2048 + k * 1024); } while (0)
; #define PG8_LDB(dst, b, h) do { _Pragma("unroll") for (int n = 0; n < 2; ++n) _Pragma("unroll") for (int k = 0; k < 2; ++k) dst[n][k] = *(const LAS bf16x8*)(lds + PG8_SB(b, h) + boff + n * 2048 + k * 1024); } while (0)
; #define PG8_MMA(ai, bj, At, Bt) do { __builtin_amdgcn_s_setprio(1); _Pragma("unroll") for (int m = 0; m < 4; ++m) _Pragma("unroll") for (int n = 0; n < 2; ++n) _Pragma("unroll") for (int k = 0; k < 2; ++k) \
;         acc[ai][bj][m][n] = __builtin_amdgcn_mfma_f32_16x16x32_bf16(Bt[n][k], At[m][k], acc[ai][bj][m][n], 0, 0, 0); __builtin_amdgcn_s_setprio(0); } while (0)
; #define PG8_WAIT_V(n) asm volatile("s_waitcnt vmcnt(" #n ")" ::: "memory")
; #define PG8_WAIT_L(n) asm volatile("s_waitcnt lgkmcnt(" #n ")" ::: "memory")
; #define PG8_BAR __builtin_amdgcn_s_barrier()
; #define PG8_SCHED __builtin_amdgcn_sched_barrier(0)
;     ...
;             const bool last = (t == nt - 2);
;             const char* a1 = cA + (size_t)(t + 1) * kstep;
;             const char* a2 = last ? nA : cA + (size_t)(t + 2) * kstep; const char* b2 = last ? nB : cB + (size_t)(t + 2) * kstep;
;             const char* a3 = a2 + kstep; const char* b3 = b2 + kstep;
;             PG8_LDB(B0, 0, 0); PG8_LDB(B1, 0, 1); PG8_SCHED; PG8_LDA(At, 0, 0); PG8_STAGE(PG8_SA(1, 1), a1 + hsA, voffA);
;             if (Epi::NPRE != 0 && last) { E.pre(sv, cur, wr, fr); PG8_WAIT_V(16); } else { PG8_WAIT_V(8); }
;             PG8_WAIT_L(0); PG8_BAR; PG8_MMA(0, 0, At, B0); PG8_MMA(0, 1, At, B1); PG8_BAR; PG8_SCHED;
;             PG8_LDA(At, 0, 1); PG8_STAGE(PG8_SB(0, 0), b2, voffB); PG8_STAGE(PG8_SB(0, 1), b2 + hsB, voffB); PG8_STAGE(PG8_SA(0, 0), a2, voffA);
;             if (Epi::NPRE != 0 && last) { PG8_WAIT_V(16); } else { PG8_WAIT_V(8); }
;             PG8_WAIT_L(0); PG8_BAR; PG8_MMA(1, 0, At, B0); PG8_MMA(1, 1, At, B1); PG8_BAR; PG8_SCHED;
.LBB0_887:
	ds_read_b128 v[150:153], v146
	ds_read_b128 v[154:157], v146 offset:1024
	ds_read_b128 v[158:161], v146 offset:2048
	ds_read_b128 v[162:165], v146 offset:3072
	ds_read_b128 v[166:169], v147
	ds_read_b128 v[170:173], v147 offset:1024
	ds_read_b128 v[174:177], v147 offset:2048
	ds_read_b128 v[178:181], v147 offset:3072
	s_add_i32 s53, s26, 2
	s_add_u32 s27, s24, 0xfffe0080
	s_addc_u32 s28, s25, -1
	s_cmp_eq_u32 s42, s26
	s_cselect_b32 s26, s50, s51
	s_cselect_b32 s29, s23, s28
	s_cselect_b32 s28, s48, s27
	s_cselect_b32 s27, s49, s52
	s_add_i32 m0, s3, 0xc000
	ds_read_b128 v[182:185], v148
	ds_read_b128 v[186:189], v148 offset:1024
	ds_read_b128 v[194:197], v148 offset:2048
	ds_read_b128 v[198:201], v148 offset:3072
	ds_read_b128 v[202:205], v148 offset:4096
	ds_read_b128 v[206:209], v148 offset:5120
	ds_read_b128 v[210:213], v148 offset:6144
	ds_read_b128 v[214:217], v148 offset:7168
	global_load_lds_dwordx4 v138, s[24:25]
	s_add_i32 m0, s3, 0xe000
	s_nop 0
	global_load_lds_dwordx4 v140, s[24:25]
	s_waitcnt vmcnt(8)
	s_waitcnt lgkmcnt(0)
	s_barrier
	s_setprio 1
	s_waitcnt lgkmcnt(0)
	v_mfma_f32_16x16x32_bf16 v[124:127], v[150:153], v[182:185], v[124:127]
	v_mfma_f32_16x16x32_bf16 v[120:123], v[158:161], v[182:185], v[120:123]
	v_mfma_f32_16x16x32_bf16 v[108:111], v[150:153], v[194:197], v[108:111]
	v_mfma_f32_16x16x32_bf16 v[104:107], v[158:161], v[194:197], v[104:107]
	v_mfma_f32_16x16x32_bf16 v[92:95], v[150:153], v[202:205], v[92:95]
	v_mfma_f32_16x16x32_bf16 v[88:91], v[158:161], v[202:205], v[88:91]
	v_mfma_f32_16x16x32_bf16 v[76:79], v[150:153], v[210:213], v[76:79]
	v_mfma_f32_16x16x32_bf16 v[72:75], v[158:161], v[210:213], v[72:75]
	v_mfma_f32_16x16x32_bf16 v[124:127], v[154:157], v[186:189], v[124:127]
	v_mfma_f32_16x16x32_bf16 v[120:123], v[162:165], v[186:189], v[120:123]
	v_mfma_f32_16x16x32_bf16 v[108:111], v[154:157], v[198:201], v[108:111]
	v_mfma_f32_16x16x32_bf16 v[104:107], v[162:165], v[198:201], v[104:107]
	v_mfma_f32_16x16x32_bf16 v[92:95], v[154:157], v[206:209], v[92:95]
	v_mfma_f32_16x16x32_bf16 v[88:91], v[162:165], v[206:209], v[88:91]
	v_mfma_f32_16x16x32_bf16 v[76:79], v[154:157], v[214:217], v[76:79]
	v_mfma_f32_16x16x32_bf16 v[72:75], v[162:165], v[214:217], v[72:75]
	s_setprio 0
	s_setprio 1
	v_mfma_f32_16x16x32_bf16 v[116:119], v[166:169], v[182:185], v[116:119]
	v_mfma_f32_16x16x32_bf16 v[112:115], v[174:177], v[182:185], v[112:115]
	v_mfma_f32_16x16x32_bf16 v[100:103], v[166:169], v[194:197], v[100:103]
	v_mfma_f32_16x16x32_bf16 v[96:99], v[174:177], v[194:197], v[96:99]
	v_mfma_f32_16x16x32_bf16 v[84:87], v[166:169], v[202:205], v[84:87]
	v_mfma_f32_16x16x32_bf16 v[80:83], v[174:177], v[202:205], v[80:83]
	v_mfma_f32_16x16x32_bf16 v[68:71], v[166:169], v[210:213], v[68:71]
	v_mfma_f32_16x16x32_bf16 v[64:67], v[174:177], v[210:213], v[64:67]
	v_mfma_f32_16x16x32_bf16 v[116:119], v[170:173], v[186:189], v[116:119]
	v_mfma_f32_16x16x32_bf16 v[112:115], v[178:181], v[186:189], v[112:115]
	v_mfma_f32_16x16x32_bf16 v[100:103], v[170:173], v[198:201], v[100:103]
	v_mfma_f32_16x16x32_bf16 v[96:99], v[178:181], v[198:201], v[96:99]
	v_mfma_f32_16x16x32_bf16 v[84:87], v[170:173], v[206:209], v[84:87]
	v_mfma_f32_16x16x32_bf16 v[80:83], v[178:181], v[206:209], v[80:83]
	v_mfma_f32_16x16x32_bf16 v[68:71], v[170:173], v[214:217], v[68:71]
	v_mfma_f32_16x16x32_bf16 v[64:67], v[178:181], v[214:217], v[64:67]
	s_setprio 0
	s_barrier
	s_add_u32 s98, s26, s12
	s_addc_u32 s99, s27, s13
	s_add_u32 s100, s28, s12
	s_addc_u32 s101, s29, s13
	s_add_i32 s54, s43, s34
	s_mov_b32 m0, s54
	ds_read_b128 v[182:185], v148 offset:16384
	ds_read_b128 v[186:189], v148 offset:17408
	ds_read_b128 v[194:197], v148 offset:18432
	ds_read_b128 v[198:201], v148 offset:19456
	ds_read_b128 v[202:205], v148 offset:20480
	ds_read_b128 v[206:209], v148 offset:21504
	ds_read_b128 v[210:213], v148 offset:22528
	ds_read_b128 v[214:217], v148 offset:23552
	global_load_lds_dwordx4 v132, s[26:27]
	s_add_i32 m0, s54, 0x2000
	s_add_u32 s54, s26, 0x20000
	s_addc_u32 s55, s27, 0
	s_add_i32 s56, s44, s34
	global_load_lds_dwordx4 v128, s[26:27]
	s_mov_b32 m0, s56
	s_nop 0
	global_load_lds_dwordx4 v132, s[54:55]
	s_add_i32 m0, s56, 0x2000
	s_nop 0
	global_load_lds_dwordx4 v128, s[54:55]
	s_mov_b32 m0, s3
	s_nop 0
	global_load_lds_dwordx4 v134, s[28:29]
	s_mov_b32 m0, s35
	s_nop 0
	global_load_lds_dwordx4 v130, s[28:29]
	s_waitcnt vmcnt(8)
	s_waitcnt lgkmcnt(0)
	s_barrier
	s_setprio 1
	s_waitcnt lgkmcnt(0)
	v_mfma_f32_16x16x32_bf16 v[60:63], v[150:153], v[182:185], v[60:63]
	v_mfma_f32_16x16x32_bf16 v[56:59], v[158:161], v[182:185], v[56:59]
	v_mfma_f32_16x16x32_bf16 v[44:47], v[150:153], v[194:197], v[44:47]
	v_mfma_f32_16x16x32_bf16 v[40:43], v[158:161], v[194:197], v[40:43]
	v_mfma_f32_16x16x32_bf16 v[28:31], v[150:153], v[202:205], v[28:31]
	v_mfma_f32_16x16x32_bf16 v[24:27], v[158:161], v[202:205], v[24:27]
	v_mfma_f32_16x16x32_bf16 v[12:15], v[150:153], v[210:213], v[12:15]
	v_mfma_f32_16x16x32_bf16 v[8:11], v[158:161], v[210:213], v[8:11]
	v_mfma_f32_16x16x32_bf16 v[60:63], v[154:157], v[186:189], v[60:63]
	v_mfma_f32_16x16x32_bf16 v[56:59], v[162:165], v[186:189], v[56:59]
	v_mfma_f32_16x16x32_bf16 v[44:47], v[154:157], v[198:201], v[44:47]
	v_mfma_f32_16x16x32_bf16 v[40:43], v[162:165], v[198:201], v[40:43]
	v_mfma_f32_16x16x32_bf16 v[28:31], v[154:157], v[206:209], v[28:31]
	v_mfma_f32_16x16x32_bf16 v[24:27], v[162:165], v[206:209], v[24:27]
	v_mfma_f32_16x16x32_bf16 v[12:15], v[154:157], v[214:217], v[12:15]
	v_mfma_f32_16x16x32_bf16 v[8:11], v[162:165], v[214:217], v[8:11]
	s_setprio 0
	s_setprio 1
	v_mfma_f32_16x16x32_bf16 v[52:55], v[166:169], v[182:185], v[52:55]
	v_mfma_f32_16x16x32_bf16 v[48:51], v[174:177], v[182:185], v[48:51]
	v_mfma_f32_16x16x32_bf16 v[36:39], v[166:169], v[194:197], v[36:39]
	v_mfma_f32_16x16x32_bf16 v[32:35], v[174:177], v[194:197], v[32:35]
	v_mfma_f32_16x16x32_bf16 v[20:23], v[166:169], v[202:205], v[20:23]
	v_mfma_f32_16x16x32_bf16 v[16:19], v[174:177], v[202:205], v[16:19]
	v_mfma_f32_16x16x32_bf16 v[4:7], v[166:169], v[210:213], v[4:7]
	v_mfma_f32_16x16x32_bf16 v[0:3], v[174:177], v[210:213], v[0:3]
	v_mfma_f32_16x16x32_bf16 v[52:55], v[170:173], v[186:189], v[52:55]
	v_mfma_f32_16x16x32_bf16 v[48:51], v[178:181], v[186:189], v[48:51]
	v_mfma_f32_16x16x32_bf16 v[36:39], v[170:173], v[198:201], v[36:39]
	v_mfma_f32_16x16x32_bf16 v[32:35], v[178:181], v[198:201], v[32:35]
	v_mfma_f32_16x16x32_bf16 v[20:23], v[170:173], v[206:209], v[20:23]
	v_mfma_f32_16x16x32_bf16 v[16:19], v[178:181], v[206:209], v[16:19]
	v_mfma_f32_16x16x32_bf16 v[4:7], v[170:173], v[214:217], v[4:7]
	v_mfma_f32_16x16x32_bf16 v[0:3], v[178:181], v[214:217], v[0:3]
	s_setprio 0
	s_barrier
; #define PG8_STAGE(bufoff, gbase, voff) do { _Pragma("unroll") for (int _i = 0; _i < 2; ++_i) \
;         __builtin_amdgcn_global_load_lds((const unsigned*)((const char*)(gbase) + (voff)[_i]), (LAS unsigned*)(lds + (bufoff) + ldsw + _i * 8192), 16, 0, ((voff) == voffA ? AUXA : 0)); } while (0)
; #define PG8_LDA(dst, b, h) do { _Pragma("unroll") for (int m = 0; m < 4; ++m) _Pragma("unroll") for (int k = 0; k < 2; ++k) dst[m][k] = *(const LAS bf16x8*)(lds + PG8_SA(b, h) + aoff + m * 2048 + k * 1024); } while (0)
; #define PG8_LDB(dst, b, h) do { _Pragma("unroll") for (int n = 0; n < 2; ++n) _Pragma("unroll") for (int k = 0; k < 2; ++k) dst[n][k] = *(const LAS bf16x8*)(lds + PG8_SB(b, h) + boff + n * 2048 + k * 1024); } while (0)
; #define PG8_MMA(ai, bj, At, Bt) do { __builtin_amdgcn_s_setprio(1); _Pragma("unroll") for (int m = 0; m < 4; ++m) _Pragma("unroll") for (int n = 0; n < 2; ++n) _Pragma("unroll") for (int k = 0; k < 2; ++k) \
;         acc[ai][bj][m][n] = __builtin_amdgcn_mfma_f32_16x16x32_bf16(Bt[n][k], At[m][k], acc[ai][bj][m][n], 0, 0, 0); __builtin_amdgcn_s_setprio(0); } while (0)
; #define PG8_WAIT_V(n) asm volatile("s_waitcnt vmcnt(" #n ")" ::: "memory")
; #define PG8_WAIT_L(n) asm volatile("s_waitcnt lgkmcnt(" #n ")" ::: "memory")
; #define PG8_BAR __builtin_amdgcn_s_barrier()
; #define PG8_SCHED __builtin_amdgcn_sched_barrier(0)
;     ...
;             PG8_LDB(B0, 1, 0); PG8_LDB(B1, 1, 1); PG8_SCHED; PG8_LDA(At, 1, 0); PG8_STAGE(PG8_SA(0, 1), a2 + hsA, voffA);
;             PG8_WAIT_V(8); PG8_WAIT_L(0); PG8_BAR; PG8_MMA(0, 0, At, B0); PG8_MMA(0, 1, At, B1); PG8_BAR; PG8_SCHED;
;             PG8_LDA(At, 1, 1); PG8_STAGE(PG8_SB(1, 0), b3, voffB); PG8_STAGE(PG8_SB(1, 1), b3 + hsB, voffB); PG8_STAGE(PG8_SA(1, 0), a3, voffA);
;             PG8_WAIT_V(8); PG8_WAIT_L(0); PG8_BAR; PG8_MMA(1, 0, At, B0); PG8_MMA(1, 1, At, B1); PG8_BAR; PG8_SCHED;
;         }
	s_add_i32 s54, 0, 0x18000
	v_add_u32_e32 v149, s54, v143
	s_add_i32 s55, 0, 0x1c000
	ds_read_b128 v[150:153], v149
	ds_read_b128 v[154:157], v149 offset:1024
	ds_read_b128 v[158:161], v149 offset:2048
	ds_read_b128 v[162:165], v149 offset:3072
	v_add_u32_e32 v149, s55, v143
	ds_read_b128 v[166:169], v149
	ds_read_b128 v[170:173], v149 offset:1024
	ds_read_b128 v[174:177], v149 offset:2048
	ds_read_b128 v[178:181], v149 offset:3072
	s_add_u32 s28, s28, 0x20000
	s_addc_u32 s29, s29, 0
	s_mov_b32 m0, s36
	ds_read_b128 v[182:185], v148 offset:32768
	ds_read_b128 v[186:189], v148 offset:33792
	ds_read_b128 v[194:197], v148 offset:34816
	ds_read_b128 v[198:201], v148 offset:35840
	ds_read_b128 v[202:205], v148 offset:36864
	ds_read_b128 v[206:209], v148 offset:37888
	ds_read_b128 v[210:213], v148 offset:38912
	ds_read_b128 v[214:217], v148 offset:39936
	global_load_lds_dwordx4 v134, s[28:29]
	s_mov_b32 m0, s37
	s_nop 0
	global_load_lds_dwordx4 v130, s[28:29]
	s_waitcnt vmcnt(8)
	s_waitcnt lgkmcnt(0)
	s_barrier
	s_setprio 1
	s_waitcnt lgkmcnt(0)
	v_mfma_f32_16x16x32_bf16 v[124:127], v[150:153], v[182:185], v[124:127]
	v_mfma_f32_16x16x32_bf16 v[120:123], v[158:161], v[182:185], v[120:123]
	v_mfma_f32_16x16x32_bf16 v[108:111], v[150:153], v[194:197], v[108:111]
	v_mfma_f32_16x16x32_bf16 v[104:107], v[158:161], v[194:197], v[104:107]
	v_mfma_f32_16x16x32_bf16 v[92:95], v[150:153], v[202:205], v[92:95]
	v_mfma_f32_16x16x32_bf16 v[88:91], v[158:161], v[202:205], v[88:91]
	v_mfma_f32_16x16x32_bf16 v[76:79], v[150:153], v[210:213], v[76:79]
	v_mfma_f32_16x16x32_bf16 v[72:75], v[158:161], v[210:213], v[72:75]
	v_mfma_f32_16x16x32_bf16 v[124:127], v[154:157], v[186:189], v[124:127]
	v_mfma_f32_16x16x32_bf16 v[120:123], v[162:165], v[186:189], v[120:123]
	v_mfma_f32_16x16x32_bf16 v[108:111], v[154:157], v[198:201], v[108:111]
	v_mfma_f32_16x16x32_bf16 v[104:107], v[162:165], v[198:201], v[104:107]
	v_mfma_f32_16x16x32_bf16 v[92:95], v[154:157], v[206:209], v[92:95]
	v_mfma_f32_16x16x32_bf16 v[88:91], v[162:165], v[206:209], v[88:91]
	v_mfma_f32_16x16x32_bf16 v[76:79], v[154:157], v[214:217], v[76:79]
	v_mfma_f32_16x16x32_bf16 v[72:75], v[162:165], v[214:217], v[72:75]
	s_setprio 0
	s_setprio 1
	v_mfma_f32_16x16x32_bf16 v[116:119], v[166:169], v[182:185], v[116:119]
	v_mfma_f32_16x16x32_bf16 v[112:115], v[174:177], v[182:185], v[112:115]
	v_mfma_f32_16x16x32_bf16 v[100:103], v[166:169], v[194:197], v[100:103]
	v_mfma_f32_16x16x32_bf16 v[96:99], v[174:177], v[194:197], v[96:99]
	v_mfma_f32_16x16x32_bf16 v[84:87], v[166:169], v[202:205], v[84:87]
	v_mfma_f32_16x16x32_bf16 v[80:83], v[174:177], v[202:205], v[80:83]
	v_mfma_f32_16x16x32_bf16 v[68:71], v[166:169], v[210:213], v[68:71]
	v_mfma_f32_16x16x32_bf16 v[64:67], v[174:177], v[210:213], v[64:67]
	v_mfma_f32_16x16x32_bf16 v[116:119], v[170:173], v[186:189], v[116:119]
	v_mfma_f32_16x16x32_bf16 v[112:115], v[178:181], v[186:189], v[112:115]
	v_mfma_f32_16x16x32_bf16 v[100:103], v[170:173], v[198:201], v[100:103]
	v_mfma_f32_16x16x32_bf16 v[96:99], v[178:181], v[198:201], v[96:99]
	v_mfma_f32_16x16x32_bf16 v[84:87], v[170:173], v[206:209], v[84:87]
	v_mfma_f32_16x16x32_bf16 v[80:83], v[178:181], v[206:209], v[80:83]
	v_mfma_f32_16x16x32_bf16 v[68:71], v[170:173], v[214:217], v[68:71]
	v_mfma_f32_16x16x32_bf16 v[64:67], v[178:181], v[214:217], v[64:67]
	s_setprio 0
	s_barrier
	s_add_i32 s28, s54, s34
	s_mov_b32 m0, s28
	ds_read_b128 v[182:185], v148 offset:49152
	ds_read_b128 v[186:189], v148 offset:50176
	ds_read_b128 v[194:197], v148 offset:51200
	ds_read_b128 v[198:201], v148 offset:52224
	ds_read_b128 v[202:205], v148 offset:53248
	ds_read_b128 v[206:209], v148 offset:54272
	ds_read_b128 v[210:213], v148 offset:55296
	ds_read_b128 v[214:217], v148 offset:56320
	global_load_lds_dwordx4 v132, s[98:99]
	s_add_i32 m0, s28, 0x2000
	s_add_u32 s26, s26, 0x20080
	s_addc_u32 s27, s27, 0
	s_add_i32 s28, s55, s34
	global_load_lds_dwordx4 v128, s[98:99]
	s_mov_b32 m0, s28
	s_nop 0
	global_load_lds_dwordx4 v132, s[26:27]
	s_add_i32 m0, s28, 0x2000
	s_nop 0
	global_load_lds_dwordx4 v128, s[26:27]
	s_mov_b32 m0, s40
	s_nop 0
	global_load_lds_dwordx4 v134, s[100:101]
	s_mov_b32 m0, s41
	s_nop 0
	global_load_lds_dwordx4 v130, s[100:101]
	s_waitcnt vmcnt(8)
	s_waitcnt lgkmcnt(0)
	s_barrier
	s_setprio 1
	s_waitcnt lgkmcnt(0)
	v_mfma_f32_16x16x32_bf16 v[60:63], v[150:153], v[182:185], v[60:63]
	v_mfma_f32_16x16x32_bf16 v[56:59], v[158:161], v[182:185], v[56:59]
	v_mfma_f32_16x16x32_bf16 v[44:47], v[150:153], v[194:197], v[44:47]
	v_mfma_f32_16x16x32_bf16 v[40:43], v[158:161], v[194:197], v[40:43]
	v_mfma_f32_16x16x32_bf16 v[28:31], v[150:153], v[202:205], v[28:31]
	v_mfma_f32_16x16x32_bf16 v[24:27], v[158:161], v[202:205], v[24:27]
	v_mfma_f32_16x16x32_bf16 v[12:15], v[150:153], v[210:213], v[12:15]
	v_mfma_f32_16x16x32_bf16 v[8:11], v[158:161], v[210:213], v[8:11]
	v_mfma_f32_16x16x32_bf16 v[60:63], v[154:157], v[186:189], v[60:63]
	v_mfma_f32_16x16x32_bf16 v[56:59], v[162:165], v[186:189], v[56:59]
	v_mfma_f32_16x16x32_bf16 v[44:47], v[154:157], v[198:201], v[44:47]
	v_mfma_f32_16x16x32_bf16 v[40:43], v[162:165], v[198:201], v[40:43]
	v_mfma_f32_16x16x32_bf16 v[28:31], v[154:157], v[206:209], v[28:31]
	v_mfma_f32_16x16x32_bf16 v[24:27], v[162:165], v[206:209], v[24:27]
	v_mfma_f32_16x16x32_bf16 v[12:15], v[154:157], v[214:217], v[12:15]
	v_mfma_f32_16x16x32_bf16 v[8:11], v[162:165], v[214:217], v[8:11]
	s_setprio 0
	s_setprio 1
	v_mfma_f32_16x16x32_bf16 v[52:55], v[166:169], v[182:185], v[52:55]
	v_mfma_f32_16x16x32_bf16 v[48:51], v[174:177], v[182:185], v[48:51]
	v_mfma_f32_16x16x32_bf16 v[36:39], v[166:169], v[194:197], v[36:39]
	v_mfma_f32_16x16x32_bf16 v[32:35], v[174:177], v[194:197], v[32:35]
	v_mfma_f32_16x16x32_bf16 v[20:23], v[166:169], v[202:205], v[20:23]
	v_mfma_f32_16x16x32_bf16 v[16:19], v[174:177], v[202:205], v[16:19]
	v_mfma_f32_16x16x32_bf16 v[4:7], v[166:169], v[210:213], v[4:7]
	v_mfma_f32_16x16x32_bf16 v[0:3], v[174:177], v[210:213], v[0:3]
	v_mfma_f32_16x16x32_bf16 v[52:55], v[170:173], v[186:189], v[52:55]
	v_mfma_f32_16x16x32_bf16 v[48:51], v[178:181], v[186:189], v[48:51]
	v_mfma_f32_16x16x32_bf16 v[36:39], v[170:173], v[198:201], v[36:39]
	v_mfma_f32_16x16x32_bf16 v[32:35], v[178:181], v[198:201], v[32:35]
	v_mfma_f32_16x16x32_bf16 v[20:23], v[170:173], v[206:209], v[20:23]
	v_mfma_f32_16x16x32_bf16 v[16:19], v[178:181], v[206:209], v[16:19]
	v_mfma_f32_16x16x32_bf16 v[4:7], v[170:173], v[214:217], v[4:7]
	v_mfma_f32_16x16x32_bf16 v[0:3], v[178:181], v[214:217], v[0:3]
	s_setprio 0
	s_barrier
	s_add_u32 s24, s24, 0x100
	s_addc_u32 s25, s25, 0
	s_add_u32 s51, s51, 0x100
	s_addc_u32 s52, s52, 0
	s_cmp_ge_i32 s53, s39
	s_mov_b32 s26, s53
	s_cbranch_scc0 .LBB0_887

; #define PG8_STAGE(bufoff, gbase, voff) do { _Pragma("unroll") for (int _i = 0; _i < 2; ++_i) \
;         __builtin_amdgcn_global_load_lds((const unsigned*)((const char*)(gbase) + (voff)[_i]), (LAS unsigned*)(lds + (bufoff) + ldsw + _i * 8192), 16, 0, ((voff) == voffA ? AUXA : 0)); } while (0)
; #define PG8_LDA(dst, b, h) do { _Pragma("unroll") for (int m = 0; m < 4; ++m) _Pragma("unroll") for (int k = 0; k < 2; ++k) dst[m][k] = *(const LAS bf16x8*)(lds + PG8_SA(b, h) + aoff + m * 2048 + k * 1024); } while (0)
; #define PG8_LDB(dst, b, h) do { _Pragma("unroll") for (int n = 0; n < 2; ++n) _Pragma("unroll") for (int k = 0; k < 2; ++k) dst[n][k] = *(const LAS bf16x8*)(lds + PG8_SB(b, h) + boff + n * 2048 + k * 1024); } while (0)
; #define PG8_MMA(ai, bj, At, Bt) do { __builtin_amdgcn_s_setprio(1); _Pragma("unroll") for (int m = 0; m < 4; ++m) _Pragma("unroll") for (int n = 0; n < 2; ++n) _Pragma("unroll") for (int k = 0; k < 2; ++k) \
;         acc[ai][bj][m][n] = __builtin_amdgcn_mfma_f32_16x16x32_bf16(Bt[n][k], At[m][k], acc[ai][bj][m][n], 0, 0, 0); __builtin_amdgcn_s_setprio(0); } while (0)
; #define PG8_WAIT_V(n) asm volatile("s_waitcnt vmcnt(" #n ")" ::: "memory")
; #define PG8_WAIT_L(n) asm volatile("s_waitcnt lgkmcnt(" #n ")" ::: "memory")
; #define PG8_BAR __builtin_amdgcn_s_barrier()
; #define PG8_SCHED __builtin_amdgcn_sched_barrier(0)
;     ...
;             const bool last = (t == nt - 2);
;             const char* a1 = cA + (size_t)(t + 1) * kstep;
;             const char* a2 = last ? nA : cA + (size_t)(t + 2) * kstep; const char* b2 = last ? nB : cB + (size_t)(t + 2) * kstep;
;             const char* a3 = a2 + kstep; const char* b3 = b2 + kstep;
;             PG8_LDB(B0, 0, 0); PG8_LDB(B1, 0, 1); PG8_SCHED; PG8_LDA(At, 0, 0); PG8_STAGE(PG8_SA(1, 1), a1 + hsA, voffA);
;             if (Epi::NPRE != 0 && last) { E.pre(sv, cur, wr, fr); PG8_WAIT_V(16); } else { PG8_WAIT_V(8); }
;             PG8_WAIT_L(0); PG8_BAR; PG8_MMA(0, 0, At, B0); PG8_MMA(0, 1, At, B1); PG8_BAR; PG8_SCHED;
;             PG8_LDA(At, 0, 1); PG8_STAGE(PG8_SB(0, 0), b2, voffB); PG8_STAGE(PG8_SB(0, 1), b2 + hsB, voffB); PG8_STAGE(PG8_SA(0, 0), a2, voffA);
;             if (Epi::NPRE != 0 && last) { PG8_WAIT_V(16); } else { PG8_WAIT_V(8); }
;             PG8_WAIT_L(0); PG8_BAR; PG8_MMA(1, 0, At, B0); PG8_MMA(1, 1, At, B1); PG8_BAR; PG8_SCHED;
.LBB0_959:
	ds_read_b128 v[88:91], v196
	ds_read_b128 v[92:95], v196 offset:1024
	ds_read_b128 v[104:107], v196 offset:2048
	ds_read_b128 v[108:111], v196 offset:3072
	ds_read_b128 v[144:147], v197
	ds_read_b128 v[148:151], v197 offset:1024
	ds_read_b128 v[152:155], v197 offset:2048
	ds_read_b128 v[156:159], v197 offset:3072
	s_add_i32 s51, s30, 2
	s_add_u32 s31, s28, 0xfffc0080
	s_addc_u32 s34, s29, -1
	s_cmp_eq_u32 s42, s30
	s_cselect_b32 s30, s48, s49
	s_cselect_b32 s35, s19, s34
	s_cselect_b32 s34, s21, s31
	s_cselect_b32 s31, s47, s50
	s_add_i32 m0, s5, 0xc000
	ds_read_b128 v[160:163], v198
	ds_read_b128 v[180:183], v198 offset:1024
	ds_read_b128 v[184:187], v198 offset:2048
	ds_read_b128 v[188:191], v198 offset:3072
	ds_read_b128 v[200:203], v198 offset:4096
	ds_read_b128 v[204:207], v198 offset:5120
	ds_read_b128 v[208:211], v198 offset:6144
	ds_read_b128 v[212:215], v198 offset:7168
	global_load_lds_dwordx4 v172, s[28:29]
	s_add_i32 m0, s5, 0xe000
	s_nop 0
	global_load_lds_dwordx4 v174, s[28:29]
	s_waitcnt vmcnt(8)
	s_waitcnt lgkmcnt(0)
	s_barrier
	s_setprio 1
	s_waitcnt lgkmcnt(0)
	v_mfma_f32_16x16x32_bf16 v[136:139], v[88:91], v[160:163], v[136:139]
	v_mfma_f32_16x16x32_bf16 v[140:143], v[104:107], v[160:163], v[140:143]
	v_mfma_f32_16x16x32_bf16 v[124:127], v[88:91], v[184:187], v[124:127]
	v_mfma_f32_16x16x32_bf16 v[120:123], v[104:107], v[184:187], v[120:123]
	v_mfma_f32_16x16x32_bf16 v[100:103], v[88:91], v[200:203], v[100:103]
	v_mfma_f32_16x16x32_bf16 v[96:99], v[104:107], v[200:203], v[96:99]
	v_mfma_f32_16x16x32_bf16 v[76:79], v[88:91], v[208:211], v[76:79]
	v_mfma_f32_16x16x32_bf16 v[72:75], v[104:107], v[208:211], v[72:75]
	v_mfma_f32_16x16x32_bf16 v[136:139], v[92:95], v[180:183], v[136:139]
	v_mfma_f32_16x16x32_bf16 v[140:143], v[108:111], v[180:183], v[140:143]
	v_mfma_f32_16x16x32_bf16 v[124:127], v[92:95], v[188:191], v[124:127]
	v_mfma_f32_16x16x32_bf16 v[120:123], v[108:111], v[188:191], v[120:123]
	v_mfma_f32_16x16x32_bf16 v[100:103], v[92:95], v[204:207], v[100:103]
	v_mfma_f32_16x16x32_bf16 v[96:99], v[108:111], v[204:207], v[96:99]
	v_mfma_f32_16x16x32_bf16 v[76:79], v[92:95], v[212:215], v[76:79]
	v_mfma_f32_16x16x32_bf16 v[72:75], v[108:111], v[212:215], v[72:75]
	s_setprio 0
	s_setprio 1
	v_mfma_f32_16x16x32_bf16 v[132:135], v[144:147], v[160:163], v[132:135]
	v_mfma_f32_16x16x32_bf16 v[128:131], v[152:155], v[160:163], v[128:131]
	v_mfma_f32_16x16x32_bf16 v[116:119], v[144:147], v[184:187], v[116:119]
	v_mfma_f32_16x16x32_bf16 v[112:115], v[152:155], v[184:187], v[112:115]
	v_mfma_f32_16x16x32_bf16 v[84:87], v[144:147], v[200:203], v[84:87]
	v_mfma_f32_16x16x32_bf16 v[80:83], v[152:155], v[200:203], v[80:83]
	v_mfma_f32_16x16x32_bf16 v[68:71], v[144:147], v[208:211], v[68:71]
	v_mfma_f32_16x16x32_bf16 v[64:67], v[152:155], v[208:211], v[64:67]
	v_mfma_f32_16x16x32_bf16 v[132:135], v[148:151], v[180:183], v[132:135]
	v_mfma_f32_16x16x32_bf16 v[128:131], v[156:159], v[180:183], v[128:131]
	v_mfma_f32_16x16x32_bf16 v[116:119], v[148:151], v[188:191], v[116:119]
	v_mfma_f32_16x16x32_bf16 v[112:115], v[156:159], v[188:191], v[112:115]
	v_mfma_f32_16x16x32_bf16 v[84:87], v[148:151], v[204:207], v[84:87]
	v_mfma_f32_16x16x32_bf16 v[80:83], v[156:159], v[204:207], v[80:83]
	v_mfma_f32_16x16x32_bf16 v[68:71], v[148:151], v[212:215], v[68:71]
	v_mfma_f32_16x16x32_bf16 v[64:67], v[156:159], v[212:215], v[64:67]
	s_setprio 0
	s_barrier
	s_add_u32 s98, s30, s12
	s_addc_u32 s99, s31, s13
	s_add_u32 s100, s34, s12
	s_addc_u32 s101, s35, s13
	s_add_i32 s52, s44, s3
	s_mov_b32 m0, s52
	ds_read_b128 v[160:163], v198 offset:16384
	ds_read_b128 v[180:183], v198 offset:17408
	ds_read_b128 v[184:187], v198 offset:18432
	ds_read_b128 v[188:191], v198 offset:19456
	ds_read_b128 v[200:203], v198 offset:20480
	ds_read_b128 v[204:207], v198 offset:21504
	ds_read_b128 v[208:211], v198 offset:22528
	ds_read_b128 v[212:215], v198 offset:23552
	global_load_lds_dwordx4 v168, s[30:31]
	s_add_i32 m0, s52, 0x2000
	s_add_u32 s52, s30, 0x40000
	s_addc_u32 s53, s31, 0
	s_add_i32 s54, s45, s3
	global_load_lds_dwordx4 v164, s[30:31]
	s_mov_b32 m0, s54
	s_nop 0
	global_load_lds_dwordx4 v168, s[52:53]
	s_add_i32 m0, s54, 0x2000
	s_nop 0
	global_load_lds_dwordx4 v164, s[52:53]
	s_mov_b32 m0, s5
	s_nop 0
	global_load_lds_dwordx4 v170, s[34:35]
	s_mov_b32 m0, s27
	s_nop 0
	global_load_lds_dwordx4 v166, s[34:35]
	s_waitcnt vmcnt(8)
	s_waitcnt lgkmcnt(0)
	s_barrier
	s_setprio 1
	s_waitcnt lgkmcnt(0)
	v_mfma_f32_16x16x32_bf16 v[60:63], v[88:91], v[160:163], v[60:63]
	v_mfma_f32_16x16x32_bf16 v[56:59], v[104:107], v[160:163], v[56:59]
	v_mfma_f32_16x16x32_bf16 v[44:47], v[88:91], v[184:187], v[44:47]
	v_mfma_f32_16x16x32_bf16 v[40:43], v[104:107], v[184:187], v[40:43]
	v_mfma_f32_16x16x32_bf16 v[28:31], v[88:91], v[200:203], v[28:31]
	v_mfma_f32_16x16x32_bf16 v[24:27], v[104:107], v[200:203], v[24:27]
	v_mfma_f32_16x16x32_bf16 v[12:15], v[88:91], v[208:211], v[12:15]
	v_mfma_f32_16x16x32_bf16 v[8:11], v[104:107], v[208:211], v[8:11]
	v_mfma_f32_16x16x32_bf16 v[60:63], v[92:95], v[180:183], v[60:63]
	v_mfma_f32_16x16x32_bf16 v[56:59], v[108:111], v[180:183], v[56:59]
	v_mfma_f32_16x16x32_bf16 v[44:47], v[92:95], v[188:191], v[44:47]
	v_mfma_f32_16x16x32_bf16 v[40:43], v[108:111], v[188:191], v[40:43]
	v_mfma_f32_16x16x32_bf16 v[28:31], v[92:95], v[204:207], v[28:31]
	v_mfma_f32_16x16x32_bf16 v[24:27], v[108:111], v[204:207], v[24:27]
	v_mfma_f32_16x16x32_bf16 v[12:15], v[92:95], v[212:215], v[12:15]
	v_mfma_f32_16x16x32_bf16 v[8:11], v[108:111], v[212:215], v[8:11]
	s_setprio 0
	s_setprio 1
	v_mfma_f32_16x16x32_bf16 v[52:55], v[144:147], v[160:163], v[52:55]
	v_mfma_f32_16x16x32_bf16 v[48:51], v[152:155], v[160:163], v[48:51]
	v_mfma_f32_16x16x32_bf16 v[36:39], v[144:147], v[184:187], v[36:39]
	v_mfma_f32_16x16x32_bf16 v[32:35], v[152:155], v[184:187], v[32:35]
	v_mfma_f32_16x16x32_bf16 v[20:23], v[144:147], v[200:203], v[20:23]
	v_mfma_f32_16x16x32_bf16 v[16:19], v[152:155], v[200:203], v[16:19]
	v_mfma_f32_16x16x32_bf16 v[4:7], v[144:147], v[208:211], v[4:7]
	v_mfma_f32_16x16x32_bf16 v[0:3], v[152:155], v[208:211], v[0:3]
	v_mfma_f32_16x16x32_bf16 v[52:55], v[148:151], v[180:183], v[52:55]
	v_mfma_f32_16x16x32_bf16 v[48:51], v[156:159], v[180:183], v[48:51]
	v_mfma_f32_16x16x32_bf16 v[36:39], v[148:151], v[188:191], v[36:39]
	v_mfma_f32_16x16x32_bf16 v[32:35], v[156:159], v[188:191], v[32:35]
	v_mfma_f32_16x16x32_bf16 v[20:23], v[148:151], v[204:207], v[20:23]
	v_mfma_f32_16x16x32_bf16 v[16:19], v[156:159], v[204:207], v[16:19]
	v_mfma_f32_16x16x32_bf16 v[4:7], v[148:151], v[212:215], v[4:7]
	v_mfma_f32_16x16x32_bf16 v[0:3], v[156:159], v[212:215], v[0:3]
	s_setprio 0
	s_barrier
; #define PG8_STAGE(bufoff, gbase, voff) do { _Pragma("unroll") for (int _i = 0; _i < 2; ++_i) \
;         __builtin_amdgcn_global_load_lds((const unsigned*)((const char*)(gbase) + (voff)[_i]), (LAS unsigned*)(lds + (bufoff) + ldsw + _i * 8192), 16, 0, ((voff) == voffA ? AUXA : 0)); } while (0)
; #define PG8_LDA(dst, b, h) do { _Pragma("unroll") for (int m = 0; m < 4; ++m) _Pragma("unroll") for (int k = 0; k < 2; ++k) dst[m][k] = *(const LAS bf16x8*)(lds + PG8_SA(b, h) + aoff + m * 2048 + k * 1024); } while (0)
; #define PG8_LDB(dst, b, h) do { _Pragma("unroll") for (int n = 0; n < 2; ++n) _Pragma("unroll") for (int k = 0; k < 2; ++k) dst[n][k] = *(const LAS bf16x8*)(lds + PG8_SB(b, h) + boff + n * 2048 + k * 1024); } while (0)
; #define PG8_MMA(ai, bj, At, Bt) do { __builtin_amdgcn_s_setprio(1); _Pragma("unroll") for (int m = 0; m < 4; ++m) _Pragma("unroll") for (int n = 0; n < 2; ++n) _Pragma("unroll") for (int k = 0; k < 2; ++k) \
;         acc[ai][bj][m][n] = __builtin_amdgcn_mfma_f32_16x16x32_bf16(Bt[n][k], At[m][k], acc[ai][bj][m][n], 0, 0, 0); __builtin_amdgcn_s_setprio(0); } while (0)
; #define PG8_WAIT_V(n) asm volatile("s_waitcnt vmcnt(" #n ")" ::: "memory")
; #define PG8_WAIT_L(n) asm volatile("s_waitcnt lgkmcnt(" #n ")" ::: "memory")
; #define PG8_BAR __builtin_amdgcn_s_barrier()
; #define PG8_SCHED __builtin_amdgcn_sched_barrier(0)
;     ...
;             PG8_LDB(B0, 1, 0); PG8_LDB(B1, 1, 1); PG8_SCHED; PG8_LDA(At, 1, 0); PG8_STAGE(PG8_SA(0, 1), a2 + hsA, voffA);
;             PG8_WAIT_V(8); PG8_WAIT_L(0); PG8_BAR; PG8_MMA(0, 0, At, B0); PG8_MMA(0, 1, At, B1); PG8_BAR; PG8_SCHED;
;             PG8_LDA(At, 1, 1); PG8_STAGE(PG8_SB(1, 0), b3, voffB); PG8_STAGE(PG8_SB(1, 1), b3 + hsB, voffB); PG8_STAGE(PG8_SA(1, 0), a3, voffA);
;             PG8_WAIT_V(8); PG8_WAIT_L(0); PG8_BAR; PG8_MMA(1, 0, At, B0); PG8_MMA(1, 1, At, B1); PG8_BAR; PG8_SCHED;
;         }
	s_add_i32 s52, 0, 0x18000
	s_add_i32 s53, 0, 0x1c000
	v_add_u32_e32 v108, s52, v194
	v_add_u32_e32 v156, s53, v194
	ds_read_b128 v[88:91], v108
	ds_read_b128 v[92:95], v108 offset:1024
	ds_read_b128 v[104:107], v108 offset:2048
	ds_read_b128 v[108:111], v108 offset:3072
	ds_read_b128 v[144:147], v156
	ds_read_b128 v[148:151], v156 offset:1024
	ds_read_b128 v[152:155], v156 offset:2048
	ds_read_b128 v[156:159], v156 offset:3072
	s_add_u32 s34, s34, 0x40000
	s_addc_u32 s35, s35, 0
	s_mov_b32 m0, s36
	ds_read_b128 v[160:163], v198 offset:32768
	ds_read_b128 v[180:183], v198 offset:33792
	ds_read_b128 v[184:187], v198 offset:34816
	ds_read_b128 v[188:191], v198 offset:35840
	ds_read_b128 v[200:203], v198 offset:36864
	ds_read_b128 v[204:207], v198 offset:37888
	ds_read_b128 v[208:211], v198 offset:38912
	ds_read_b128 v[212:215], v198 offset:39936
	global_load_lds_dwordx4 v170, s[34:35]
	s_mov_b32 m0, s37
	s_nop 0
	global_load_lds_dwordx4 v166, s[34:35]
	s_waitcnt vmcnt(8)
	s_waitcnt lgkmcnt(0)
	s_barrier
	s_setprio 1
	s_waitcnt lgkmcnt(0)
	v_mfma_f32_16x16x32_bf16 v[136:139], v[88:91], v[160:163], v[136:139]
	v_mfma_f32_16x16x32_bf16 v[140:143], v[104:107], v[160:163], v[140:143]
	v_mfma_f32_16x16x32_bf16 v[124:127], v[88:91], v[184:187], v[124:127]
	v_mfma_f32_16x16x32_bf16 v[120:123], v[104:107], v[184:187], v[120:123]
	v_mfma_f32_16x16x32_bf16 v[100:103], v[88:91], v[200:203], v[100:103]
	v_mfma_f32_16x16x32_bf16 v[96:99], v[104:107], v[200:203], v[96:99]
	v_mfma_f32_16x16x32_bf16 v[76:79], v[88:91], v[208:211], v[76:79]
	v_mfma_f32_16x16x32_bf16 v[72:75], v[104:107], v[208:211], v[72:75]
	v_mfma_f32_16x16x32_bf16 v[136:139], v[92:95], v[180:183], v[136:139]
	v_mfma_f32_16x16x32_bf16 v[140:143], v[108:111], v[180:183], v[140:143]
	v_mfma_f32_16x16x32_bf16 v[124:127], v[92:95], v[188:191], v[124:127]
	v_mfma_f32_16x16x32_bf16 v[120:123], v[108:111], v[188:191], v[120:123]
	v_mfma_f32_16x16x32_bf16 v[100:103], v[92:95], v[204:207], v[100:103]
	v_mfma_f32_16x16x32_bf16 v[96:99], v[108:111], v[204:207], v[96:99]
	v_mfma_f32_16x16x32_bf16 v[76:79], v[92:95], v[212:215], v[76:79]
	v_mfma_f32_16x16x32_bf16 v[72:75], v[108:111], v[212:215], v[72:75]
	s_setprio 0
	s_setprio 1
	v_mfma_f32_16x16x32_bf16 v[132:135], v[144:147], v[160:163], v[132:135]
	v_mfma_f32_16x16x32_bf16 v[128:131], v[152:155], v[160:163], v[128:131]
	v_mfma_f32_16x16x32_bf16 v[116:119], v[144:147], v[184:187], v[116:119]
	v_mfma_f32_16x16x32_bf16 v[112:115], v[152:155], v[184:187], v[112:115]
	v_mfma_f32_16x16x32_bf16 v[84:87], v[144:147], v[200:203], v[84:87]
	v_mfma_f32_16x16x32_bf16 v[80:83], v[152:155], v[200:203], v[80:83]
	v_mfma_f32_16x16x32_bf16 v[68:71], v[144:147], v[208:211], v[68:71]
	v_mfma_f32_16x16x32_bf16 v[64:67], v[152:155], v[208:211], v[64:67]
	v_mfma_f32_16x16x32_bf16 v[132:135], v[148:151], v[180:183], v[132:135]
	v_mfma_f32_16x16x32_bf16 v[128:131], v[156:159], v[180:183], v[128:131]
	v_mfma_f32_16x16x32_bf16 v[116:119], v[148:151], v[188:191], v[116:119]
	v_mfma_f32_16x16x32_bf16 v[112:115], v[156:159], v[188:191], v[112:115]
	v_mfma_f32_16x16x32_bf16 v[84:87], v[148:151], v[204:207], v[84:87]
	v_mfma_f32_16x16x32_bf16 v[80:83], v[156:159], v[204:207], v[80:83]
	v_mfma_f32_16x16x32_bf16 v[68:71], v[148:151], v[212:215], v[68:71]
	v_mfma_f32_16x16x32_bf16 v[64:67], v[156:159], v[212:215], v[64:67]
	s_setprio 0
	s_barrier
	s_add_i32 s34, s52, s3
	s_mov_b32 m0, s34
	ds_read_b128 v[160:163], v198 offset:49152
	ds_read_b128 v[180:183], v198 offset:50176
	ds_read_b128 v[184:187], v198 offset:51200
	ds_read_b128 v[188:191], v198 offset:52224
	ds_read_b128 v[200:203], v198 offset:53248
	ds_read_b128 v[204:207], v198 offset:54272
	ds_read_b128 v[208:211], v198 offset:55296
	ds_read_b128 v[212:215], v198 offset:56320
	global_load_lds_dwordx4 v168, s[98:99]
	s_add_i32 m0, s34, 0x2000
	s_add_u32 s30, s30, 0x40080
	s_addc_u32 s31, s31, 0
	s_add_i32 s34, s53, s3
	global_load_lds_dwordx4 v164, s[98:99]
	s_mov_b32 m0, s34
	s_nop 0
	global_load_lds_dwordx4 v168, s[30:31]
	s_add_i32 m0, s34, 0x2000
	s_nop 0
	global_load_lds_dwordx4 v164, s[30:31]
	s_mov_b32 m0, s40
	s_nop 0
	global_load_lds_dwordx4 v170, s[100:101]
	s_mov_b32 m0, s41
	s_nop 0
	global_load_lds_dwordx4 v166, s[100:101]
	s_waitcnt vmcnt(8)
	s_waitcnt lgkmcnt(0)
	s_barrier
	s_setprio 1
	s_waitcnt lgkmcnt(0)
	v_mfma_f32_16x16x32_bf16 v[60:63], v[88:91], v[160:163], v[60:63]
	v_mfma_f32_16x16x32_bf16 v[56:59], v[104:107], v[160:163], v[56:59]
	v_mfma_f32_16x16x32_bf16 v[44:47], v[88:91], v[184:187], v[44:47]
	v_mfma_f32_16x16x32_bf16 v[40:43], v[104:107], v[184:187], v[40:43]
	v_mfma_f32_16x16x32_bf16 v[28:31], v[88:91], v[200:203], v[28:31]
	v_mfma_f32_16x16x32_bf16 v[24:27], v[104:107], v[200:203], v[24:27]
	v_mfma_f32_16x16x32_bf16 v[12:15], v[88:91], v[208:211], v[12:15]
	v_mfma_f32_16x16x32_bf16 v[8:11], v[104:107], v[208:211], v[8:11]
	v_mfma_f32_16x16x32_bf16 v[60:63], v[92:95], v[180:183], v[60:63]
	v_mfma_f32_16x16x32_bf16 v[56:59], v[108:111], v[180:183], v[56:59]
	v_mfma_f32_16x16x32_bf16 v[44:47], v[92:95], v[188:191], v[44:47]
	v_mfma_f32_16x16x32_bf16 v[40:43], v[108:111], v[188:191], v[40:43]
	v_mfma_f32_16x16x32_bf16 v[28:31], v[92:95], v[204:207], v[28:31]
	v_mfma_f32_16x16x32_bf16 v[24:27], v[108:111], v[204:207], v[24:27]
	v_mfma_f32_16x16x32_bf16 v[12:15], v[92:95], v[212:215], v[12:15]
	v_mfma_f32_16x16x32_bf16 v[8:11], v[108:111], v[212:215], v[8:11]
	s_setprio 0
	s_setprio 1
	v_mfma_f32_16x16x32_bf16 v[52:55], v[144:147], v[160:163], v[52:55]
	v_mfma_f32_16x16x32_bf16 v[48:51], v[152:155], v[160:163], v[48:51]
	v_mfma_f32_16x16x32_bf16 v[36:39], v[144:147], v[184:187], v[36:39]
	v_mfma_f32_16x16x32_bf16 v[32:35], v[152:155], v[184:187], v[32:35]
	v_mfma_f32_16x16x32_bf16 v[20:23], v[144:147], v[200:203], v[20:23]
	v_mfma_f32_16x16x32_bf16 v[16:19], v[152:155], v[200:203], v[16:19]
	v_mfma_f32_16x16x32_bf16 v[4:7], v[144:147], v[208:211], v[4:7]
	v_mfma_f32_16x16x32_bf16 v[0:3], v[152:155], v[208:211], v[0:3]
	v_mfma_f32_16x16x32_bf16 v[52:55], v[148:151], v[180:183], v[52:55]
	v_mfma_f32_16x16x32_bf16 v[48:51], v[156:159], v[180:183], v[48:51]
	v_mfma_f32_16x16x32_bf16 v[36:39], v[148:151], v[188:191], v[36:39]
	v_mfma_f32_16x16x32_bf16 v[32:35], v[156:159], v[188:191], v[32:35]
	v_mfma_f32_16x16x32_bf16 v[20:23], v[148:151], v[204:207], v[20:23]
	v_mfma_f32_16x16x32_bf16 v[16:19], v[156:159], v[204:207], v[16:19]
	v_mfma_f32_16x16x32_bf16 v[4:7], v[148:151], v[212:215], v[4:7]
	v_mfma_f32_16x16x32_bf16 v[0:3], v[156:159], v[212:215], v[0:3]
	s_setprio 0
	s_barrier
	s_add_u32 s28, s28, 0x100
	s_addc_u32 s29, s29, 0
	s_add_u32 s49, s49, 0x100
	s_addc_u32 s50, s50, 0
	s_cmp_ge_i32 s51, s39
	s_mov_b32 s30, s51
	s_cbranch_scc0 .LBB0_959

; #define PG8_STAGE(bufoff, gbase, voff) do { _Pragma("unroll") for (int _i = 0; _i < 2; ++_i) \
;         __builtin_amdgcn_global_load_lds((const unsigned*)((const char*)(gbase) + (voff)[_i]), (LAS unsigned*)(lds + (bufoff) + ldsw + _i * 8192), 16, 0, ((voff) == voffA ? AUXA : 0)); } while (0)
; #define PG8_LDA(dst, b, h) do { _Pragma("unroll") for (int m = 0; m < 4; ++m) _Pragma("unroll") for (int k = 0; k < 2; ++k) dst[m][k] = *(const LAS bf16x8*)(lds + PG8_SA(b, h) + aoff + m * 2048 + k * 1024); } while (0)
; #define PG8_LDB(dst, b, h) do { _Pragma("unroll") for (int n = 0; n < 2; ++n) _Pragma("unroll") for (int k = 0; k < 2; ++k) dst[n][k] = *(const LAS bf16x8*)(lds + PG8_SB(b, h) + boff + n * 2048 + k * 1024); } while (0)
; #define PG8_MMA(ai, bj, At, Bt) do { __builtin_amdgcn_s_setprio(1); _Pragma("unroll") for (int m = 0; m < 4; ++m) _Pragma("unroll") for (int n = 0; n < 2; ++n) _Pragma("unroll") for (int k = 0; k < 2; ++k) \
;         acc[ai][bj][m][n] = __builtin_amdgcn_mfma_f32_16x16x32_bf16(Bt[n][k], At[m][k], acc[ai][bj][m][n], 0, 0, 0); __builtin_amdgcn_s_setprio(0); } while (0)
; #define PG8_WAIT_V(n) asm volatile("s_waitcnt vmcnt(" #n ")" ::: "memory")
; #define PG8_WAIT_L(n) asm volatile("s_waitcnt lgkmcnt(" #n ")" ::: "memory")
; #define PG8_BAR __builtin_amdgcn_s_barrier()
; #define PG8_SCHED __builtin_amdgcn_sched_barrier(0)
;     ...
;             const bool last = (t == nt - 2);
;             const char* a1 = cA + (size_t)(t + 1) * kstep;
;             const char* a2 = last ? nA : cA + (size_t)(t + 2) * kstep; const char* b2 = last ? nB : cB + (size_t)(t + 2) * kstep;
;             const char* a3 = a2 + kstep; const char* b3 = b2 + kstep;
;             PG8_LDB(B0, 0, 0); PG8_LDB(B1, 0, 1); PG8_SCHED; PG8_LDA(At, 0, 0); PG8_STAGE(PG8_SA(1, 1), a1 + hsA, voffA);
;             if (Epi::NPRE != 0 && last) { E.pre(sv, cur, wr, fr); PG8_WAIT_V(16); } else { PG8_WAIT_V(8); }
;             PG8_WAIT_L(0); PG8_BAR; PG8_MMA(0, 0, At, B0); PG8_MMA(0, 1, At, B1); PG8_BAR; PG8_SCHED;
;             PG8_LDA(At, 0, 1); PG8_STAGE(PG8_SB(0, 0), b2, voffB); PG8_STAGE(PG8_SB(0, 1), b2 + hsB, voffB); PG8_STAGE(PG8_SA(0, 0), a2, voffA);
;             if (Epi::NPRE != 0 && last) { PG8_WAIT_V(16); } else { PG8_WAIT_V(8); }
;             PG8_WAIT_L(0); PG8_BAR; PG8_MMA(1, 0, At, B0); PG8_MMA(1, 1, At, B1); PG8_BAR; PG8_SCHED;
.LBB0_1040:
	ds_read_b128 v[150:153], v147
	ds_read_b128 v[154:157], v147 offset:1024
	ds_read_b128 v[158:161], v147 offset:2048
	ds_read_b128 v[162:165], v147 offset:3072
	ds_read_b128 v[166:169], v148
	ds_read_b128 v[170:173], v148 offset:1024
	ds_read_b128 v[174:177], v148 offset:2048
	ds_read_b128 v[178:181], v148 offset:3072
	s_add_i32 s56, s30, 2
	s_add_u32 s31, s28, 0xfffc0080
	s_addc_u32 s34, s29, -1
	s_cmp_eq_u32 s47, s30
	s_cselect_b32 s30, s53, s54
	s_cselect_b32 s35, s21, s34
	s_cselect_b32 s34, s23, s31
	s_cselect_b32 s31, s52, s55
	s_add_i32 m0, s19, 0xc000
	ds_read_b128 v[182:185], v149
	ds_read_b128 v[186:189], v149 offset:1024
	ds_read_b128 v[190:193], v149 offset:2048
	ds_read_b128 v[194:197], v149 offset:3072
	ds_read_b128 v[198:201], v149 offset:4096
	ds_read_b128 v[202:205], v149 offset:5120
	ds_read_b128 v[206:209], v149 offset:6144
	ds_read_b128 v[210:213], v149 offset:7168
	global_load_lds_dwordx4 v136, s[28:29]
	s_add_i32 m0, s19, 0xe000
	s_nop 0
	global_load_lds_dwordx4 v138, s[28:29]
	s_waitcnt vmcnt(8)
	s_waitcnt lgkmcnt(0)
	s_barrier
	s_setprio 1
	s_waitcnt lgkmcnt(0)
	v_mfma_f32_16x16x32_bf16 v[124:127], v[150:153], v[182:185], v[124:127]
	v_mfma_f32_16x16x32_bf16 v[120:123], v[158:161], v[182:185], v[120:123]
	v_mfma_f32_16x16x32_bf16 v[108:111], v[150:153], v[190:193], v[108:111]
	v_mfma_f32_16x16x32_bf16 v[104:107], v[158:161], v[190:193], v[104:107]
	v_mfma_f32_16x16x32_bf16 v[92:95], v[150:153], v[198:201], v[92:95]
	v_mfma_f32_16x16x32_bf16 v[88:91], v[158:161], v[198:201], v[88:91]
	v_mfma_f32_16x16x32_bf16 v[76:79], v[150:153], v[206:209], v[76:79]
	v_mfma_f32_16x16x32_bf16 v[72:75], v[158:161], v[206:209], v[72:75]
	v_mfma_f32_16x16x32_bf16 v[124:127], v[154:157], v[186:189], v[124:127]
	v_mfma_f32_16x16x32_bf16 v[120:123], v[162:165], v[186:189], v[120:123]
	v_mfma_f32_16x16x32_bf16 v[108:111], v[154:157], v[194:197], v[108:111]
	v_mfma_f32_16x16x32_bf16 v[104:107], v[162:165], v[194:197], v[104:107]
	v_mfma_f32_16x16x32_bf16 v[92:95], v[154:157], v[202:205], v[92:95]
	v_mfma_f32_16x16x32_bf16 v[88:91], v[162:165], v[202:205], v[88:91]
	v_mfma_f32_16x16x32_bf16 v[76:79], v[154:157], v[210:213], v[76:79]
	v_mfma_f32_16x16x32_bf16 v[72:75], v[162:165], v[210:213], v[72:75]
	s_setprio 0
	s_setprio 1
	v_mfma_f32_16x16x32_bf16 v[116:119], v[166:169], v[182:185], v[116:119]
	v_mfma_f32_16x16x32_bf16 v[112:115], v[174:177], v[182:185], v[112:115]
	v_mfma_f32_16x16x32_bf16 v[100:103], v[166:169], v[190:193], v[100:103]
	v_mfma_f32_16x16x32_bf16 v[96:99], v[174:177], v[190:193], v[96:99]
	v_mfma_f32_16x16x32_bf16 v[84:87], v[166:169], v[198:201], v[84:87]
	v_mfma_f32_16x16x32_bf16 v[80:83], v[174:177], v[198:201], v[80:83]
	v_mfma_f32_16x16x32_bf16 v[68:71], v[166:169], v[206:209], v[68:71]
	v_mfma_f32_16x16x32_bf16 v[64:67], v[174:177], v[206:209], v[64:67]
	v_mfma_f32_16x16x32_bf16 v[116:119], v[170:173], v[186:189], v[116:119]
	v_mfma_f32_16x16x32_bf16 v[112:115], v[178:181], v[186:189], v[112:115]
	v_mfma_f32_16x16x32_bf16 v[100:103], v[170:173], v[194:197], v[100:103]
	v_mfma_f32_16x16x32_bf16 v[96:99], v[178:181], v[194:197], v[96:99]
	v_mfma_f32_16x16x32_bf16 v[84:87], v[170:173], v[202:205], v[84:87]
	v_mfma_f32_16x16x32_bf16 v[80:83], v[178:181], v[202:205], v[80:83]
	v_mfma_f32_16x16x32_bf16 v[68:71], v[170:173], v[210:213], v[68:71]
	v_mfma_f32_16x16x32_bf16 v[64:67], v[178:181], v[210:213], v[64:67]
	s_setprio 0
	s_barrier
	s_add_u32 s98, s30, s14
	s_addc_u32 s99, s31, s15
	s_add_u32 s100, s34, s14
	s_addc_u32 s101, s35, s15
	s_add_i32 s57, s49, s37
	s_mov_b32 m0, s57
	ds_read_b128 v[182:185], v149 offset:16384
	ds_read_b128 v[186:189], v149 offset:17408
	ds_read_b128 v[190:193], v149 offset:18432
	ds_read_b128 v[194:197], v149 offset:19456
	ds_read_b128 v[198:201], v149 offset:20480
	ds_read_b128 v[202:205], v149 offset:21504
	ds_read_b128 v[206:209], v149 offset:22528
	ds_read_b128 v[210:213], v149 offset:23552
	global_load_lds_dwordx4 v132, s[30:31]
	s_add_i32 m0, s57, 0x2000
	s_add_u32 s58, s30, 0x40000
	s_addc_u32 s59, s31, 0
	s_add_i32 s57, s50, s37
	global_load_lds_dwordx4 v128, s[30:31]
	s_mov_b32 m0, s57
	s_nop 0
	global_load_lds_dwordx4 v132, s[58:59]
	s_add_i32 m0, s57, 0x2000
	s_nop 0
	global_load_lds_dwordx4 v128, s[58:59]
	s_mov_b32 m0, s19
	s_nop 0
	global_load_lds_dwordx4 v134, s[34:35]
	s_mov_b32 m0, s40
	s_nop 0
	global_load_lds_dwordx4 v130, s[34:35]
	s_waitcnt vmcnt(8)
	s_waitcnt lgkmcnt(0)
	s_barrier
	s_setprio 1
	s_waitcnt lgkmcnt(0)
	v_mfma_f32_16x16x32_bf16 v[60:63], v[150:153], v[182:185], v[60:63]
	v_mfma_f32_16x16x32_bf16 v[56:59], v[158:161], v[182:185], v[56:59]
	v_mfma_f32_16x16x32_bf16 v[44:47], v[150:153], v[190:193], v[44:47]
	v_mfma_f32_16x16x32_bf16 v[40:43], v[158:161], v[190:193], v[40:43]
	v_mfma_f32_16x16x32_bf16 v[28:31], v[150:153], v[198:201], v[28:31]
	v_mfma_f32_16x16x32_bf16 v[24:27], v[158:161], v[198:201], v[24:27]
	v_mfma_f32_16x16x32_bf16 v[12:15], v[150:153], v[206:209], v[12:15]
	v_mfma_f32_16x16x32_bf16 v[8:11], v[158:161], v[206:209], v[8:11]
	v_mfma_f32_16x16x32_bf16 v[60:63], v[154:157], v[186:189], v[60:63]
	v_mfma_f32_16x16x32_bf16 v[56:59], v[162:165], v[186:189], v[56:59]
	v_mfma_f32_16x16x32_bf16 v[44:47], v[154:157], v[194:197], v[44:47]
	v_mfma_f32_16x16x32_bf16 v[40:43], v[162:165], v[194:197], v[40:43]
	v_mfma_f32_16x16x32_bf16 v[28:31], v[154:157], v[202:205], v[28:31]
	v_mfma_f32_16x16x32_bf16 v[24:27], v[162:165], v[202:205], v[24:27]
	v_mfma_f32_16x16x32_bf16 v[12:15], v[154:157], v[210:213], v[12:15]
	v_mfma_f32_16x16x32_bf16 v[8:11], v[162:165], v[210:213], v[8:11]
	s_setprio 0
	s_setprio 1
	v_mfma_f32_16x16x32_bf16 v[52:55], v[166:169], v[182:185], v[52:55]
	v_mfma_f32_16x16x32_bf16 v[48:51], v[174:177], v[182:185], v[48:51]
	v_mfma_f32_16x16x32_bf16 v[36:39], v[166:169], v[190:193], v[36:39]
	v_mfma_f32_16x16x32_bf16 v[32:35], v[174:177], v[190:193], v[32:35]
	v_mfma_f32_16x16x32_bf16 v[20:23], v[166:169], v[198:201], v[20:23]
	v_mfma_f32_16x16x32_bf16 v[16:19], v[174:177], v[198:201], v[16:19]
	v_mfma_f32_16x16x32_bf16 v[4:7], v[166:169], v[206:209], v[4:7]
	v_mfma_f32_16x16x32_bf16 v[0:3], v[174:177], v[206:209], v[0:3]
	v_mfma_f32_16x16x32_bf16 v[52:55], v[170:173], v[186:189], v[52:55]
	v_mfma_f32_16x16x32_bf16 v[48:51], v[178:181], v[186:189], v[48:51]
	v_mfma_f32_16x16x32_bf16 v[36:39], v[170:173], v[194:197], v[36:39]
	v_mfma_f32_16x16x32_bf16 v[32:35], v[178:181], v[194:197], v[32:35]
	v_mfma_f32_16x16x32_bf16 v[20:23], v[170:173], v[202:205], v[20:23]
	v_mfma_f32_16x16x32_bf16 v[16:19], v[178:181], v[202:205], v[16:19]
	v_mfma_f32_16x16x32_bf16 v[4:7], v[170:173], v[210:213], v[4:7]
	v_mfma_f32_16x16x32_bf16 v[0:3], v[178:181], v[210:213], v[0:3]
	s_setprio 0
	s_barrier
; #define PG8_STAGE(bufoff, gbase, voff) do { _Pragma("unroll") for (int _i = 0; _i < 2; ++_i) \
;         __builtin_amdgcn_global_load_lds((const unsigned*)((const char*)(gbase) + (voff)[_i]), (LAS unsigned*)(lds + (bufoff) + ldsw + _i * 8192), 16, 0, ((voff) == voffA ? AUXA : 0)); } while (0)
; #define PG8_LDA(dst, b, h) do { _Pragma("unroll") for (int m = 0; m < 4; ++m) _Pragma("unroll") for (int k = 0; k < 2; ++k) dst[m][k] = *(const LAS bf16x8*)(lds + PG8_SA(b, h) + aoff + m * 2048 + k * 1024); } while (0)
; #define PG8_LDB(dst, b, h) do { _Pragma("unroll") for (int n = 0; n < 2; ++n) _Pragma("unroll") for (int k = 0; k < 2; ++k) dst[n][k] = *(const LAS bf16x8*)(lds + PG8_SB(b, h) + boff + n * 2048 + k * 1024); } while (0)
; #define PG8_MMA(ai, bj, At, Bt) do { __builtin_amdgcn_s_setprio(1); _Pragma("unroll") for (int m = 0; m < 4; ++m) _Pragma("unroll") for (int n = 0; n < 2; ++n) _Pragma("unroll") for (int k = 0; k < 2; ++k) \
;         acc[ai][bj][m][n] = __builtin_amdgcn_mfma_f32_16x16x32_bf16(Bt[n][k], At[m][k], acc[ai][bj][m][n], 0, 0, 0); __builtin_amdgcn_s_setprio(0); } while (0)
; #define PG8_WAIT_V(n) asm volatile("s_waitcnt vmcnt(" #n ")" ::: "memory")
; #define PG8_WAIT_L(n) asm volatile("s_waitcnt lgkmcnt(" #n ")" ::: "memory")
; #define PG8_BAR __builtin_amdgcn_s_barrier()
; #define PG8_SCHED __builtin_amdgcn_sched_barrier(0)
;     ...
;             PG8_LDB(B0, 1, 0); PG8_LDB(B1, 1, 1); PG8_SCHED; PG8_LDA(At, 1, 0); PG8_STAGE(PG8_SA(0, 1), a2 + hsA, voffA);
;             PG8_WAIT_V(8); PG8_WAIT_L(0); PG8_BAR; PG8_MMA(0, 0, At, B0); PG8_MMA(0, 1, At, B1); PG8_BAR; PG8_SCHED;
;             PG8_LDA(At, 1, 1); PG8_STAGE(PG8_SB(1, 0), b3, voffB); PG8_STAGE(PG8_SB(1, 1), b3 + hsB, voffB); PG8_STAGE(PG8_SA(1, 0), a3, voffA);
;             PG8_WAIT_V(8); PG8_WAIT_L(0); PG8_BAR; PG8_MMA(1, 0, At, B0); PG8_MMA(1, 1, At, B1); PG8_BAR; PG8_SCHED;
;         }
	s_add_i32 s57, 0, 0x18000
	s_add_i32 s58, 0, 0x1c000
	v_add_u32_e32 v162, s57, v145
	v_add_u32_e32 v178, s58, v145
	ds_read_b128 v[150:153], v162
	ds_read_b128 v[154:157], v162 offset:1024
	ds_read_b128 v[158:161], v162 offset:2048
	ds_read_b128 v[162:165], v162 offset:3072
	ds_read_b128 v[166:169], v178
	ds_read_b128 v[170:173], v178 offset:1024
	ds_read_b128 v[174:177], v178 offset:2048
	ds_read_b128 v[178:181], v178 offset:3072
	s_add_u32 s34, s34, 0x40000
	s_addc_u32 s35, s35, 0
	s_mov_b32 m0, s41
	ds_read_b128 v[182:185], v149 offset:32768
	ds_read_b128 v[186:189], v149 offset:33792
	ds_read_b128 v[190:193], v149 offset:34816
	ds_read_b128 v[194:197], v149 offset:35840
	ds_read_b128 v[198:201], v149 offset:36864
	ds_read_b128 v[202:205], v149 offset:37888
	ds_read_b128 v[206:209], v149 offset:38912
	ds_read_b128 v[210:213], v149 offset:39936
	global_load_lds_dwordx4 v134, s[34:35]
	s_mov_b32 m0, s42
	s_nop 0
	global_load_lds_dwordx4 v130, s[34:35]
	s_waitcnt vmcnt(8)
	s_waitcnt lgkmcnt(0)
	s_barrier
	s_setprio 1
	s_waitcnt lgkmcnt(0)
	v_mfma_f32_16x16x32_bf16 v[124:127], v[150:153], v[182:185], v[124:127]
	v_mfma_f32_16x16x32_bf16 v[120:123], v[158:161], v[182:185], v[120:123]
	v_mfma_f32_16x16x32_bf16 v[108:111], v[150:153], v[190:193], v[108:111]
	v_mfma_f32_16x16x32_bf16 v[104:107], v[158:161], v[190:193], v[104:107]
	v_mfma_f32_16x16x32_bf16 v[92:95], v[150:153], v[198:201], v[92:95]
	v_mfma_f32_16x16x32_bf16 v[88:91], v[158:161], v[198:201], v[88:91]
	v_mfma_f32_16x16x32_bf16 v[76:79], v[150:153], v[206:209], v[76:79]
	v_mfma_f32_16x16x32_bf16 v[72:75], v[158:161], v[206:209], v[72:75]
	v_mfma_f32_16x16x32_bf16 v[124:127], v[154:157], v[186:189], v[124:127]
	v_mfma_f32_16x16x32_bf16 v[120:123], v[162:165], v[186:189], v[120:123]
	v_mfma_f32_16x16x32_bf16 v[108:111], v[154:157], v[194:197], v[108:111]
	v_mfma_f32_16x16x32_bf16 v[104:107], v[162:165], v[194:197], v[104:107]
	v_mfma_f32_16x16x32_bf16 v[92:95], v[154:157], v[202:205], v[92:95]
	v_mfma_f32_16x16x32_bf16 v[88:91], v[162:165], v[202:205], v[88:91]
	v_mfma_f32_16x16x32_bf16 v[76:79], v[154:157], v[210:213], v[76:79]
	v_mfma_f32_16x16x32_bf16 v[72:75], v[162:165], v[210:213], v[72:75]
	s_setprio 0
	s_setprio 1
	v_mfma_f32_16x16x32_bf16 v[116:119], v[166:169], v[182:185], v[116:119]
	v_mfma_f32_16x16x32_bf16 v[112:115], v[174:177], v[182:185], v[112:115]
	v_mfma_f32_16x16x32_bf16 v[100:103], v[166:169], v[190:193], v[100:103]
	v_mfma_f32_16x16x32_bf16 v[96:99], v[174:177], v[190:193], v[96:99]
	v_mfma_f32_16x16x32_bf16 v[84:87], v[166:169], v[198:201], v[84:87]
	v_mfma_f32_16x16x32_bf16 v[80:83], v[174:177], v[198:201], v[80:83]
	v_mfma_f32_16x16x32_bf16 v[68:71], v[166:169], v[206:209], v[68:71]
	v_mfma_f32_16x16x32_bf16 v[64:67], v[174:177], v[206:209], v[64:67]
	v_mfma_f32_16x16x32_bf16 v[116:119], v[170:173], v[186:189], v[116:119]
	v_mfma_f32_16x16x32_bf16 v[112:115], v[178:181], v[186:189], v[112:115]
	v_mfma_f32_16x16x32_bf16 v[100:103], v[170:173], v[194:197], v[100:103]
	v_mfma_f32_16x16x32_bf16 v[96:99], v[178:181], v[194:197], v[96:99]
	v_mfma_f32_16x16x32_bf16 v[84:87], v[170:173], v[202:205], v[84:87]
	v_mfma_f32_16x16x32_bf16 v[80:83], v[178:181], v[202:205], v[80:83]
	v_mfma_f32_16x16x32_bf16 v[68:71], v[170:173], v[210:213], v[68:71]
	v_mfma_f32_16x16x32_bf16 v[64:67], v[178:181], v[210:213], v[64:67]
	s_setprio 0
	s_barrier
	s_add_i32 s34, s57, s37
	s_mov_b32 m0, s34
	ds_read_b128 v[182:185], v149 offset:49152
	ds_read_b128 v[186:189], v149 offset:50176
	ds_read_b128 v[190:193], v149 offset:51200
	ds_read_b128 v[194:197], v149 offset:52224
	ds_read_b128 v[198:201], v149 offset:53248
	ds_read_b128 v[202:205], v149 offset:54272
	ds_read_b128 v[206:209], v149 offset:55296
	ds_read_b128 v[210:213], v149 offset:56320
	global_load_lds_dwordx4 v132, s[98:99]
	s_add_i32 m0, s34, 0x2000
	s_add_u32 s30, s30, 0x40080
	s_addc_u32 s31, s31, 0
	s_add_i32 s34, s58, s37
	global_load_lds_dwordx4 v128, s[98:99]
	s_mov_b32 m0, s34
	s_nop 0
	global_load_lds_dwordx4 v132, s[30:31]
	s_add_i32 m0, s34, 0x2000
	s_nop 0
	global_load_lds_dwordx4 v128, s[30:31]
	s_mov_b32 m0, s45
	s_nop 0
	global_load_lds_dwordx4 v134, s[100:101]
	s_mov_b32 m0, s46
	s_nop 0
	global_load_lds_dwordx4 v130, s[100:101]
	s_waitcnt vmcnt(8)
	s_waitcnt lgkmcnt(0)
	s_barrier
	s_setprio 1
	s_waitcnt lgkmcnt(0)
	v_mfma_f32_16x16x32_bf16 v[60:63], v[150:153], v[182:185], v[60:63]
	v_mfma_f32_16x16x32_bf16 v[56:59], v[158:161], v[182:185], v[56:59]
	v_mfma_f32_16x16x32_bf16 v[44:47], v[150:153], v[190:193], v[44:47]
	v_mfma_f32_16x16x32_bf16 v[40:43], v[158:161], v[190:193], v[40:43]
	v_mfma_f32_16x16x32_bf16 v[28:31], v[150:153], v[198:201], v[28:31]
	v_mfma_f32_16x16x32_bf16 v[24:27], v[158:161], v[198:201], v[24:27]
	v_mfma_f32_16x16x32_bf16 v[12:15], v[150:153], v[206:209], v[12:15]
	v_mfma_f32_16x16x32_bf16 v[8:11], v[158:161], v[206:209], v[8:11]
	v_mfma_f32_16x16x32_bf16 v[60:63], v[154:157], v[186:189], v[60:63]
	v_mfma_f32_16x16x32_bf16 v[56:59], v[162:165], v[186:189], v[56:59]
	v_mfma_f32_16x16x32_bf16 v[44:47], v[154:157], v[194:197], v[44:47]
	v_mfma_f32_16x16x32_bf16 v[40:43], v[162:165], v[194:197], v[40:43]
	v_mfma_f32_16x16x32_bf16 v[28:31], v[154:157], v[202:205], v[28:31]
	v_mfma_f32_16x16x32_bf16 v[24:27], v[162:165], v[202:205], v[24:27]
	v_mfma_f32_16x16x32_bf16 v[12:15], v[154:157], v[210:213], v[12:15]
	v_mfma_f32_16x16x32_bf16 v[8:11], v[162:165], v[210:213], v[8:11]
	s_setprio 0
	s_setprio 1
	v_mfma_f32_16x16x32_bf16 v[52:55], v[166:169], v[182:185], v[52:55]
	v_mfma_f32_16x16x32_bf16 v[48:51], v[174:177], v[182:185], v[48:51]
	v_mfma_f32_16x16x32_bf16 v[36:39], v[166:169], v[190:193], v[36:39]
	v_mfma_f32_16x16x32_bf16 v[32:35], v[174:177], v[190:193], v[32:35]
	v_mfma_f32_16x16x32_bf16 v[20:23], v[166:169], v[198:201], v[20:23]
	v_mfma_f32_16x16x32_bf16 v[16:19], v[174:177], v[198:201], v[16:19]
	v_mfma_f32_16x16x32_bf16 v[4:7], v[166:169], v[206:209], v[4:7]
	v_mfma_f32_16x16x32_bf16 v[0:3], v[174:177], v[206:209], v[0:3]
	v_mfma_f32_16x16x32_bf16 v[52:55], v[170:173], v[186:189], v[52:55]
	v_mfma_f32_16x16x32_bf16 v[48:51], v[178:181], v[186:189], v[48:51]
	v_mfma_f32_16x16x32_bf16 v[36:39], v[170:173], v[194:197], v[36:39]
	v_mfma_f32_16x16x32_bf16 v[32:35], v[178:181], v[194:197], v[32:35]
	v_mfma_f32_16x16x32_bf16 v[20:23], v[170:173], v[202:205], v[20:23]
	v_mfma_f32_16x16x32_bf16 v[16:19], v[178:181], v[202:205], v[16:19]
	v_mfma_f32_16x16x32_bf16 v[4:7], v[170:173], v[210:213], v[4:7]
	v_mfma_f32_16x16x32_bf16 v[0:3], v[178:181], v[210:213], v[0:3]
	s_setprio 0
	s_barrier
	s_add_u32 s28, s28, 0x100
	s_addc_u32 s29, s29, 0
	s_add_u32 s54, s54, 0x100
	s_addc_u32 s55, s55, 0
	s_cmp_ge_i32 s56, s44
	s_mov_b32 s30, s56
	s_cbranch_scc0 .LBB0_1040

; #define PG8_STAGE(bufoff, gbase, voff) do { _Pragma("unroll") for (int _i = 0; _i < 2; ++_i) \
;         __builtin_amdgcn_global_load_lds((const unsigned*)((const char*)(gbase) + (voff)[_i]), (LAS unsigned*)(lds + (bufoff) + ldsw + _i * 8192), 16, 0, ((voff) == voffA ? AUXA : 0)); } while (0)
; #define PG8_LDA(dst, b, h) do { _Pragma("unroll") for (int m = 0; m < 4; ++m) _Pragma("unroll") for (int k = 0; k < 2; ++k) dst[m][k] = *(const LAS bf16x8*)(lds + PG8_SA(b, h) + aoff + m * 2048 + k * 1024); } while (0)
; #define PG8_LDB(dst, b, h) do { _Pragma("unroll") for (int n = 0; n < 2; ++n) _Pragma("unroll") for (int k = 0; k < 2; ++k) dst[n][k] = *(const LAS bf16x8*)(lds + PG8_SB(b, h) + boff + n * 2048 + k * 1024); } while (0)
; #define PG8_MMA(ai, bj, At, Bt) do { __builtin_amdgcn_s_setprio(1); _Pragma("unroll") for (int m = 0; m < 4; ++m) _Pragma("unroll") for (int n = 0; n < 2; ++n) _Pragma("unroll") for (int k = 0; k < 2; ++k) \
;         acc[ai][bj][m][n] = __builtin_amdgcn_mfma_f32_16x16x32_bf16(Bt[n][k], At[m][k], acc[ai][bj][m][n], 0, 0, 0); __builtin_amdgcn_s_setprio(0); } while (0)
; #define PG8_WAIT_V(n) asm volatile("s_waitcnt vmcnt(" #n ")" ::: "memory")
; #define PG8_WAIT_L(n) asm volatile("s_waitcnt lgkmcnt(" #n ")" ::: "memory")
; #define PG8_BAR __builtin_amdgcn_s_barrier()
; #define PG8_SCHED __builtin_amdgcn_sched_barrier(0)
;     ...
;             const bool last = (t == nt - 2);
;             const char* a1 = cA + (size_t)(t + 1) * kstep;
;             const char* a2 = last ? nA : cA + (size_t)(t + 2) * kstep; const char* b2 = last ? nB : cB + (size_t)(t + 2) * kstep;
;             const char* a3 = a2 + kstep; const char* b3 = b2 + kstep;
;             PG8_LDB(B0, 0, 0); PG8_LDB(B1, 0, 1); PG8_SCHED; PG8_LDA(At, 0, 0); PG8_STAGE(PG8_SA(1, 1), a1 + hsA, voffA);
;             if (Epi::NPRE != 0 && last) { E.pre(sv, cur, wr, fr); PG8_WAIT_V(16); } else { PG8_WAIT_V(8); }
;             PG8_WAIT_L(0); PG8_BAR; PG8_MMA(0, 0, At, B0); PG8_MMA(0, 1, At, B1); PG8_BAR; PG8_SCHED;
;             PG8_LDA(At, 0, 1); PG8_STAGE(PG8_SB(0, 0), b2, voffB); PG8_STAGE(PG8_SB(0, 1), b2 + hsB, voffB); PG8_STAGE(PG8_SA(0, 0), a2, voffA);
;             if (Epi::NPRE != 0 && last) { PG8_WAIT_V(16); } else { PG8_WAIT_V(8); }
;             PG8_WAIT_L(0); PG8_BAR; PG8_MMA(1, 0, At, B0); PG8_MMA(1, 1, At, B1); PG8_BAR; PG8_SCHED;
.LBB0_1112:
	ds_read_b128 v[150:153], v147
	ds_read_b128 v[154:157], v147 offset:1024
	ds_read_b128 v[158:161], v147 offset:2048
	ds_read_b128 v[162:165], v147 offset:3072
	ds_read_b128 v[166:169], v148
	ds_read_b128 v[170:173], v148 offset:1024
	ds_read_b128 v[174:177], v148 offset:2048
	ds_read_b128 v[178:181], v148 offset:3072
	s_add_i32 s54, s30, 2
	s_add_u32 s31, s28, 0xfffc0080
	s_addc_u32 s34, s29, -1
	s_cmp_eq_u32 s45, s30
	s_cselect_b32 s30, s51, s52
	s_cselect_b32 s35, s21, s34
	s_cselect_b32 s34, s23, s31
	s_cselect_b32 s31, s50, s53
	s_add_i32 m0, s19, 0xc000
	ds_read_b128 v[182:185], v149
	ds_read_b128 v[186:189], v149 offset:1024
	ds_read_b128 v[190:193], v149 offset:2048
	ds_read_b128 v[194:197], v149 offset:3072
	ds_read_b128 v[198:201], v149 offset:4096
	ds_read_b128 v[202:205], v149 offset:5120
	ds_read_b128 v[206:209], v149 offset:6144
	ds_read_b128 v[210:213], v149 offset:7168
	global_load_lds_dwordx4 v136, s[28:29]
	s_add_i32 m0, s19, 0xe000
	s_nop 0
	global_load_lds_dwordx4 v138, s[28:29]
	s_waitcnt vmcnt(8)
	s_waitcnt lgkmcnt(0)
	s_barrier
	s_setprio 1
	s_waitcnt lgkmcnt(0)
	v_mfma_f32_16x16x32_bf16 v[124:127], v[150:153], v[182:185], v[124:127]
	v_mfma_f32_16x16x32_bf16 v[120:123], v[158:161], v[182:185], v[120:123]
	v_mfma_f32_16x16x32_bf16 v[108:111], v[150:153], v[190:193], v[108:111]
	v_mfma_f32_16x16x32_bf16 v[104:107], v[158:161], v[190:193], v[104:107]
	v_mfma_f32_16x16x32_bf16 v[92:95], v[150:153], v[198:201], v[92:95]
	v_mfma_f32_16x16x32_bf16 v[88:91], v[158:161], v[198:201], v[88:91]
	v_mfma_f32_16x16x32_bf16 v[76:79], v[150:153], v[206:209], v[76:79]
	v_mfma_f32_16x16x32_bf16 v[72:75], v[158:161], v[206:209], v[72:75]
	v_mfma_f32_16x16x32_bf16 v[124:127], v[154:157], v[186:189], v[124:127]
	v_mfma_f32_16x16x32_bf16 v[120:123], v[162:165], v[186:189], v[120:123]
	v_mfma_f32_16x16x32_bf16 v[108:111], v[154:157], v[194:197], v[108:111]
	v_mfma_f32_16x16x32_bf16 v[104:107], v[162:165], v[194:197], v[104:107]
	v_mfma_f32_16x16x32_bf16 v[92:95], v[154:157], v[202:205], v[92:95]
	v_mfma_f32_16x16x32_bf16 v[88:91], v[162:165], v[202:205], v[88:91]
	v_mfma_f32_16x16x32_bf16 v[76:79], v[154:157], v[210:213], v[76:79]
	v_mfma_f32_16x16x32_bf16 v[72:75], v[162:165], v[210:213], v[72:75]
	s_setprio 0
	s_setprio 1
	v_mfma_f32_16x16x32_bf16 v[116:119], v[166:169], v[182:185], v[116:119]
	v_mfma_f32_16x16x32_bf16 v[112:115], v[174:177], v[182:185], v[112:115]
	v_mfma_f32_16x16x32_bf16 v[100:103], v[166:169], v[190:193], v[100:103]
	v_mfma_f32_16x16x32_bf16 v[96:99], v[174:177], v[190:193], v[96:99]
	v_mfma_f32_16x16x32_bf16 v[84:87], v[166:169], v[198:201], v[84:87]
	v_mfma_f32_16x16x32_bf16 v[80:83], v[174:177], v[198:201], v[80:83]
	v_mfma_f32_16x16x32_bf16 v[68:71], v[166:169], v[206:209], v[68:71]
	v_mfma_f32_16x16x32_bf16 v[64:67], v[174:177], v[206:209], v[64:67]
	v_mfma_f32_16x16x32_bf16 v[116:119], v[170:173], v[186:189], v[116:119]
	v_mfma_f32_16x16x32_bf16 v[112:115], v[178:181], v[186:189], v[112:115]
	v_mfma_f32_16x16x32_bf16 v[100:103], v[170:173], v[194:197], v[100:103]
	v_mfma_f32_16x16x32_bf16 v[96:99], v[178:181], v[194:197], v[96:99]
	v_mfma_f32_16x16x32_bf16 v[84:87], v[170:173], v[202:205], v[84:87]
	v_mfma_f32_16x16x32_bf16 v[80:83], v[178:181], v[202:205], v[80:83]
	v_mfma_f32_16x16x32_bf16 v[68:71], v[170:173], v[210:213], v[68:71]
	v_mfma_f32_16x16x32_bf16 v[64:67], v[178:181], v[210:213], v[64:67]
	s_setprio 0
	s_barrier
	s_add_u32 s98, s30, s14
	s_addc_u32 s99, s31, s15
	s_add_u32 s100, s34, s14
	s_addc_u32 s101, s35, s15
	s_add_i32 s55, s47, s5
	s_mov_b32 m0, s55
	ds_read_b128 v[182:185], v149 offset:16384
	ds_read_b128 v[186:189], v149 offset:17408
	ds_read_b128 v[190:193], v149 offset:18432
	ds_read_b128 v[194:197], v149 offset:19456
	ds_read_b128 v[198:201], v149 offset:20480
	ds_read_b128 v[202:205], v149 offset:21504
	ds_read_b128 v[206:209], v149 offset:22528
	ds_read_b128 v[210:213], v149 offset:23552
	global_load_lds_dwordx4 v132, s[30:31]
	s_add_i32 m0, s55, 0x2000
	s_add_u32 s56, s30, 0x40000
	s_addc_u32 s57, s31, 0
	s_add_i32 s55, s48, s5
	global_load_lds_dwordx4 v128, s[30:31]
	s_mov_b32 m0, s55
	s_nop 0
	global_load_lds_dwordx4 v132, s[56:57]
	s_add_i32 m0, s55, 0x2000
	s_nop 0
	global_load_lds_dwordx4 v128, s[56:57]
	s_mov_b32 m0, s19
	s_nop 0
	global_load_lds_dwordx4 v134, s[34:35]
	s_mov_b32 m0, s38
	s_nop 0
	global_load_lds_dwordx4 v130, s[34:35]
	s_waitcnt vmcnt(8)
	s_waitcnt lgkmcnt(0)
	s_barrier
	s_setprio 1
	s_waitcnt lgkmcnt(0)
	v_mfma_f32_16x16x32_bf16 v[60:63], v[150:153], v[182:185], v[60:63]
	v_mfma_f32_16x16x32_bf16 v[56:59], v[158:161], v[182:185], v[56:59]
	v_mfma_f32_16x16x32_bf16 v[44:47], v[150:153], v[190:193], v[44:47]
	v_mfma_f32_16x16x32_bf16 v[40:43], v[158:161], v[190:193], v[40:43]
	v_mfma_f32_16x16x32_bf16 v[28:31], v[150:153], v[198:201], v[28:31]
	v_mfma_f32_16x16x32_bf16 v[24:27], v[158:161], v[198:201], v[24:27]
	v_mfma_f32_16x16x32_bf16 v[12:15], v[150:153], v[206:209], v[12:15]
	v_mfma_f32_16x16x32_bf16 v[8:11], v[158:161], v[206:209], v[8:11]
	v_mfma_f32_16x16x32_bf16 v[60:63], v[154:157], v[186:189], v[60:63]
	v_mfma_f32_16x16x32_bf16 v[56:59], v[162:165], v[186:189], v[56:59]
	v_mfma_f32_16x16x32_bf16 v[44:47], v[154:157], v[194:197], v[44:47]
	v_mfma_f32_16x16x32_bf16 v[40:43], v[162:165], v[194:197], v[40:43]
	v_mfma_f32_16x16x32_bf16 v[28:31], v[154:157], v[202:205], v[28:31]
	v_mfma_f32_16x16x32_bf16 v[24:27], v[162:165], v[202:205], v[24:27]
	v_mfma_f32_16x16x32_bf16 v[12:15], v[154:157], v[210:213], v[12:15]
	v_mfma_f32_16x16x32_bf16 v[8:11], v[162:165], v[210:213], v[8:11]
	s_setprio 0
	s_setprio 1
	v_mfma_f32_16x16x32_bf16 v[52:55], v[166:169], v[182:185], v[52:55]
	v_mfma_f32_16x16x32_bf16 v[48:51], v[174:177], v[182:185], v[48:51]
	v_mfma_f32_16x16x32_bf16 v[36:39], v[166:169], v[190:193], v[36:39]
	v_mfma_f32_16x16x32_bf16 v[32:35], v[174:177], v[190:193], v[32:35]
	v_mfma_f32_16x16x32_bf16 v[20:23], v[166:169], v[198:201], v[20:23]
	v_mfma_f32_16x16x32_bf16 v[16:19], v[174:177], v[198:201], v[16:19]
	v_mfma_f32_16x16x32_bf16 v[4:7], v[166:169], v[206:209], v[4:7]
	v_mfma_f32_16x16x32_bf16 v[0:3], v[174:177], v[206:209], v[0:3]
	v_mfma_f32_16x16x32_bf16 v[52:55], v[170:173], v[186:189], v[52:55]
	v_mfma_f32_16x16x32_bf16 v[48:51], v[178:181], v[186:189], v[48:51]
	v_mfma_f32_16x16x32_bf16 v[36:39], v[170:173], v[194:197], v[36:39]
	v_mfma_f32_16x16x32_bf16 v[32:35], v[178:181], v[194:197], v[32:35]
	v_mfma_f32_16x16x32_bf16 v[20:23], v[170:173], v[202:205], v[20:23]
	v_mfma_f32_16x16x32_bf16 v[16:19], v[178:181], v[202:205], v[16:19]
	v_mfma_f32_16x16x32_bf16 v[4:7], v[170:173], v[210:213], v[4:7]
	v_mfma_f32_16x16x32_bf16 v[0:3], v[178:181], v[210:213], v[0:3]
	s_setprio 0
	s_barrier
; #define PG8_STAGE(bufoff, gbase, voff) do { _Pragma("unroll") for (int _i = 0; _i < 2; ++_i) \
;         __builtin_amdgcn_global_load_lds((const unsigned*)((const char*)(gbase) + (voff)[_i]), (LAS unsigned*)(lds + (bufoff) + ldsw + _i * 8192), 16, 0, ((voff) == voffA ? AUXA : 0)); } while (0)
; #define PG8_LDA(dst, b, h) do { _Pragma("unroll") for (int m = 0; m < 4; ++m) _Pragma("unroll") for (int k = 0; k < 2; ++k) dst[m][k] = *(const LAS bf16x8*)(lds + PG8_SA(b, h) + aoff + m * 2048 + k * 1024); } while (0)
; #define PG8_LDB(dst, b, h) do { _Pragma("unroll") for (int n = 0; n < 2; ++n) _Pragma("unroll") for (int k = 0; k < 2; ++k) dst[n][k] = *(const LAS bf16x8*)(lds + PG8_SB(b, h) + boff + n * 2048 + k * 1024); } while (0)
; #define PG8_MMA(ai, bj, At, Bt) do { __builtin_amdgcn_s_setprio(1); _Pragma("unroll") for (int m = 0; m < 4; ++m) _Pragma("unroll") for (int n = 0; n < 2; ++n) _Pragma("unroll") for (int k = 0; k < 2; ++k) \
;         acc[ai][bj][m][n] = __builtin_amdgcn_mfma_f32_16x16x32_bf16(Bt[n][k], At[m][k], acc[ai][bj][m][n], 0, 0, 0); __builtin_amdgcn_s_setprio(0); } while (0)
; #define PG8_WAIT_V(n) asm volatile("s_waitcnt vmcnt(" #n ")" ::: "memory")
; #define PG8_WAIT_L(n) asm volatile("s_waitcnt lgkmcnt(" #n ")" ::: "memory")
; #define PG8_BAR __builtin_amdgcn_s_barrier()
; #define PG8_SCHED __builtin_amdgcn_sched_barrier(0)
;     ...
;             PG8_LDB(B0, 1, 0); PG8_LDB(B1, 1, 1); PG8_SCHED; PG8_LDA(At, 1, 0); PG8_STAGE(PG8_SA(0, 1), a2 + hsA, voffA);
;             PG8_WAIT_V(8); PG8_WAIT_L(0); PG8_BAR; PG8_MMA(0, 0, At, B0); PG8_MMA(0, 1, At, B1); PG8_BAR; PG8_SCHED;
;             PG8_LDA(At, 1, 1); PG8_STAGE(PG8_SB(1, 0), b3, voffB); PG8_STAGE(PG8_SB(1, 1), b3 + hsB, voffB); PG8_STAGE(PG8_SA(1, 0), a3, voffA);
;             PG8_WAIT_V(8); PG8_WAIT_L(0); PG8_BAR; PG8_MMA(1, 0, At, B0); PG8_MMA(1, 1, At, B1); PG8_BAR; PG8_SCHED;
;         }
	s_add_i32 s55, 0, 0x18000
	s_add_i32 s56, 0, 0x1c000
	v_add_u32_e32 v162, s55, v145
	v_add_u32_e32 v178, s56, v145
	ds_read_b128 v[150:153], v162
	ds_read_b128 v[154:157], v162 offset:1024
	ds_read_b128 v[158:161], v162 offset:2048
	ds_read_b128 v[162:165], v162 offset:3072
	ds_read_b128 v[166:169], v178
	ds_read_b128 v[170:173], v178 offset:1024
	ds_read_b128 v[174:177], v178 offset:2048
	ds_read_b128 v[178:181], v178 offset:3072
	s_add_u32 s34, s34, 0x40000
	s_addc_u32 s35, s35, 0
	s_mov_b32 m0, s39
	ds_read_b128 v[182:185], v149 offset:32768
	ds_read_b128 v[186:189], v149 offset:33792
	ds_read_b128 v[190:193], v149 offset:34816
	ds_read_b128 v[194:197], v149 offset:35840
	ds_read_b128 v[198:201], v149 offset:36864
	ds_read_b128 v[202:205], v149 offset:37888
	ds_read_b128 v[206:209], v149 offset:38912
	ds_read_b128 v[210:213], v149 offset:39936
	global_load_lds_dwordx4 v134, s[34:35]
	s_mov_b32 m0, s40
	s_nop 0
	global_load_lds_dwordx4 v130, s[34:35]
	s_waitcnt vmcnt(8)
	s_waitcnt lgkmcnt(0)
	s_barrier
	s_setprio 1
	s_waitcnt lgkmcnt(0)
	v_mfma_f32_16x16x32_bf16 v[124:127], v[150:153], v[182:185], v[124:127]
	v_mfma_f32_16x16x32_bf16 v[120:123], v[158:161], v[182:185], v[120:123]
	v_mfma_f32_16x16x32_bf16 v[108:111], v[150:153], v[190:193], v[108:111]
	v_mfma_f32_16x16x32_bf16 v[104:107], v[158:161], v[190:193], v[104:107]
	v_mfma_f32_16x16x32_bf16 v[92:95], v[150:153], v[198:201], v[92:95]
	v_mfma_f32_16x16x32_bf16 v[88:91], v[158:161], v[198:201], v[88:91]
	v_mfma_f32_16x16x32_bf16 v[76:79], v[150:153], v[206:209], v[76:79]
	v_mfma_f32_16x16x32_bf16 v[72:75], v[158:161], v[206:209], v[72:75]
	v_mfma_f32_16x16x32_bf16 v[124:127], v[154:157], v[186:189], v[124:127]
	v_mfma_f32_16x16x32_bf16 v[120:123], v[162:165], v[186:189], v[120:123]
	v_mfma_f32_16x16x32_bf16 v[108:111], v[154:157], v[194:197], v[108:111]
	v_mfma_f32_16x16x32_bf16 v[104:107], v[162:165], v[194:197], v[104:107]
	v_mfma_f32_16x16x32_bf16 v[92:95], v[154:157], v[202:205], v[92:95]
	v_mfma_f32_16x16x32_bf16 v[88:91], v[162:165], v[202:205], v[88:91]
	v_mfma_f32_16x16x32_bf16 v[76:79], v[154:157], v[210:213], v[76:79]
	v_mfma_f32_16x16x32_bf16 v[72:75], v[162:165], v[210:213], v[72:75]
	s_setprio 0
	s_setprio 1
	v_mfma_f32_16x16x32_bf16 v[116:119], v[166:169], v[182:185], v[116:119]
	v_mfma_f32_16x16x32_bf16 v[112:115], v[174:177], v[182:185], v[112:115]
	v_mfma_f32_16x16x32_bf16 v[100:103], v[166:169], v[190:193], v[100:103]
	v_mfma_f32_16x16x32_bf16 v[96:99], v[174:177], v[190:193], v[96:99]
	v_mfma_f32_16x16x32_bf16 v[84:87], v[166:169], v[198:201], v[84:87]
	v_mfma_f32_16x16x32_bf16 v[80:83], v[174:177], v[198:201], v[80:83]
	v_mfma_f32_16x16x32_bf16 v[68:71], v[166:169], v[206:209], v[68:71]
	v_mfma_f32_16x16x32_bf16 v[64:67], v[174:177], v[206:209], v[64:67]
	v_mfma_f32_16x16x32_bf16 v[116:119], v[170:173], v[186:189], v[116:119]
	v_mfma_f32_16x16x32_bf16 v[112:115], v[178:181], v[186:189], v[112:115]
	v_mfma_f32_16x16x32_bf16 v[100:103], v[170:173], v[194:197], v[100:103]
	v_mfma_f32_16x16x32_bf16 v[96:99], v[178:181], v[194:197], v[96:99]
	v_mfma_f32_16x16x32_bf16 v[84:87], v[170:173], v[202:205], v[84:87]
	v_mfma_f32_16x16x32_bf16 v[80:83], v[178:181], v[202:205], v[80:83]
	v_mfma_f32_16x16x32_bf16 v[68:71], v[170:173], v[210:213], v[68:71]
	v_mfma_f32_16x16x32_bf16 v[64:67], v[178:181], v[210:213], v[64:67]
	s_setprio 0
	s_barrier
	s_add_i32 s34, s55, s5
	s_mov_b32 m0, s34
	ds_read_b128 v[182:185], v149 offset:49152
	ds_read_b128 v[186:189], v149 offset:50176
	ds_read_b128 v[190:193], v149 offset:51200
	ds_read_b128 v[194:197], v149 offset:52224
	ds_read_b128 v[198:201], v149 offset:53248
	ds_read_b128 v[202:205], v149 offset:54272
	ds_read_b128 v[206:209], v149 offset:55296
	ds_read_b128 v[210:213], v149 offset:56320
	global_load_lds_dwordx4 v132, s[98:99]
	s_add_i32 m0, s34, 0x2000
	s_add_u32 s30, s30, 0x40080
	s_addc_u32 s31, s31, 0
	s_add_i32 s34, s56, s5
	global_load_lds_dwordx4 v128, s[98:99]
	s_mov_b32 m0, s34
	s_nop 0
	global_load_lds_dwordx4 v132, s[30:31]
	s_add_i32 m0, s34, 0x2000
	s_nop 0
	global_load_lds_dwordx4 v128, s[30:31]
	s_mov_b32 m0, s43
	s_nop 0
	global_load_lds_dwordx4 v134, s[100:101]
	s_mov_b32 m0, s44
	s_nop 0
	global_load_lds_dwordx4 v130, s[100:101]
	s_waitcnt vmcnt(8)
	s_waitcnt lgkmcnt(0)
	s_barrier
	s_setprio 1
	s_waitcnt lgkmcnt(0)
	v_mfma_f32_16x16x32_bf16 v[60:63], v[150:153], v[182:185], v[60:63]
	v_mfma_f32_16x16x32_bf16 v[56:59], v[158:161], v[182:185], v[56:59]
	v_mfma_f32_16x16x32_bf16 v[44:47], v[150:153], v[190:193], v[44:47]
	v_mfma_f32_16x16x32_bf16 v[40:43], v[158:161], v[190:193], v[40:43]
	v_mfma_f32_16x16x32_bf16 v[28:31], v[150:153], v[198:201], v[28:31]
	v_mfma_f32_16x16x32_bf16 v[24:27], v[158:161], v[198:201], v[24:27]
	v_mfma_f32_16x16x32_bf16 v[12:15], v[150:153], v[206:209], v[12:15]
	v_mfma_f32_16x16x32_bf16 v[8:11], v[158:161], v[206:209], v[8:11]
	v_mfma_f32_16x16x32_bf16 v[60:63], v[154:157], v[186:189], v[60:63]
	v_mfma_f32_16x16x32_bf16 v[56:59], v[162:165], v[186:189], v[56:59]
	v_mfma_f32_16x16x32_bf16 v[44:47], v[154:157], v[194:197], v[44:47]
	v_mfma_f32_16x16x32_bf16 v[40:43], v[162:165], v[194:197], v[40:43]
	v_mfma_f32_16x16x32_bf16 v[28:31], v[154:157], v[202:205], v[28:31]
	v_mfma_f32_16x16x32_bf16 v[24:27], v[162:165], v[202:205], v[24:27]
	v_mfma_f32_16x16x32_bf16 v[12:15], v[154:157], v[210:213], v[12:15]
	v_mfma_f32_16x16x32_bf16 v[8:11], v[162:165], v[210:213], v[8:11]
	s_setprio 0
	s_setprio 1
	v_mfma_f32_16x16x32_bf16 v[52:55], v[166:169], v[182:185], v[52:55]
	v_mfma_f32_16x16x32_bf16 v[48:51], v[174:177], v[182:185], v[48:51]
	v_mfma_f32_16x16x32_bf16 v[36:39], v[166:169], v[190:193], v[36:39]
	v_mfma_f32_16x16x32_bf16 v[32:35], v[174:177], v[190:193], v[32:35]
	v_mfma_f32_16x16x32_bf16 v[20:23], v[166:169], v[198:201], v[20:23]
	v_mfma_f32_16x16x32_bf16 v[16:19], v[174:177], v[198:201], v[16:19]
	v_mfma_f32_16x16x32_bf16 v[4:7], v[166:169], v[206:209], v[4:7]
	v_mfma_f32_16x16x32_bf16 v[0:3], v[174:177], v[206:209], v[0:3]
	v_mfma_f32_16x16x32_bf16 v[52:55], v[170:173], v[186:189], v[52:55]
	v_mfma_f32_16x16x32_bf16 v[48:51], v[178:181], v[186:189], v[48:51]
	v_mfma_f32_16x16x32_bf16 v[36:39], v[170:173], v[194:197], v[36:39]
	v_mfma_f32_16x16x32_bf16 v[32:35], v[178:181], v[194:197], v[32:35]
	v_mfma_f32_16x16x32_bf16 v[20:23], v[170:173], v[202:205], v[20:23]
	v_mfma_f32_16x16x32_bf16 v[16:19], v[178:181], v[202:205], v[16:19]
	v_mfma_f32_16x16x32_bf16 v[4:7], v[170:173], v[210:213], v[4:7]
	v_mfma_f32_16x16x32_bf16 v[0:3], v[178:181], v[210:213], v[0:3]
	s_setprio 0
	s_barrier
	s_add_u32 s28, s28, 0x100
	s_addc_u32 s29, s29, 0
	s_add_u32 s52, s52, 0x100
	s_addc_u32 s53, s53, 0
	s_cmp_ge_i32 s54, s42
	s_mov_b32 s30, s54
	s_cbranch_scc0 .LBB0_1112

; #define PG8_STAGE(bufoff, gbase, voff) do { _Pragma("unroll") for (int _i = 0; _i < 2; ++_i) \
;         __builtin_amdgcn_global_load_lds((const unsigned*)((const char*)(gbase) + (voff)[_i]), (LAS unsigned*)(lds + (bufoff) + ldsw + _i * 8192), 16, 0, ((voff) == voffA ? AUXA : 0)); } while (0)
; #define PG8_LDA(dst, b, h) do { _Pragma("unroll") for (int m = 0; m < 4; ++m) _Pragma("unroll") for (int k = 0; k < 2; ++k) dst[m][k] = *(const LAS bf16x8*)(lds + PG8_SA(b, h) + aoff + m * 2048 + k * 1024); } while (0)
; #define PG8_LDB(dst, b, h) do { _Pragma("unroll") for (int n = 0; n < 2; ++n) _Pragma("unroll") for (int k = 0; k < 2; ++k) dst[n][k] = *(const LAS bf16x8*)(lds + PG8_SB(b, h) + boff + n * 2048 + k * 1024); } while (0)
; #define PG8_MMA(ai, bj, At, Bt) do { __builtin_amdgcn_s_setprio(1); _Pragma("unroll") for (int m = 0; m < 4; ++m) _Pragma("unroll") for (int n = 0; n < 2; ++n) _Pragma("unroll") for (int k = 0; k < 2; ++k) \
;         acc[ai][bj][m][n] = __builtin_amdgcn_mfma_f32_16x16x32_bf16(Bt[n][k], At[m][k], acc[ai][bj][m][n], 0, 0, 0); __builtin_amdgcn_s_setprio(0); } while (0)
; #define PG8_WAIT_V(n) asm volatile("s_waitcnt vmcnt(" #n ")" ::: "memory")
; #define PG8_WAIT_L(n) asm volatile("s_waitcnt lgkmcnt(" #n ")" ::: "memory")
; #define PG8_BAR __builtin_amdgcn_s_barrier()
; #define PG8_SCHED __builtin_amdgcn_sched_barrier(0)
;     ...
;             PG8_WAIT_L(0); PG8_BAR; PG8_MMA(1, 0, At, B0); PG8_MMA(1, 1, At, B1); PG8_BAR; PG8_SCHED;
;             PG8_LDB(B0, 1, 0); PG8_LDB(B1, 1, 1); PG8_SCHED; PG8_LDA(At, 1, 0); PG8_STAGE(PG8_SA(0, 1), a2 + hsA, voffA);
;             PG8_WAIT_V(8); PG8_WAIT_L(0); PG8_BAR; PG8_MMA(0, 0, At, B0); PG8_MMA(0, 1, At, B1); PG8_BAR; PG8_SCHED;
.LBB0_1184:
	s_waitcnt lgkmcnt(0)
	s_add_i32 s62, s62, 2
	s_barrier
	s_setprio 1
	s_waitcnt lgkmcnt(0)
	v_mfma_f32_16x16x32_bf16 v[60:63], v[144:147], v[184:187], v[60:63]
	v_mfma_f32_16x16x32_bf16 v[52:55], v[152:155], v[184:187], v[52:55]
	v_mfma_f32_16x16x32_bf16 v[44:47], v[144:147], v[176:179], v[44:47]
	v_mfma_f32_16x16x32_bf16 v[36:39], v[152:155], v[176:179], v[36:39]
	v_mfma_f32_16x16x32_bf16 v[28:31], v[144:147], v[168:171], v[28:31]
	v_mfma_f32_16x16x32_bf16 v[20:23], v[152:155], v[168:171], v[20:23]
	v_mfma_f32_16x16x32_bf16 v[12:15], v[144:147], v[160:163], v[12:15]
	v_mfma_f32_16x16x32_bf16 v[4:7], v[152:155], v[160:163], v[4:7]
	v_mfma_f32_16x16x32_bf16 v[60:63], v[148:151], v[188:191], v[60:63]
	v_mfma_f32_16x16x32_bf16 v[52:55], v[156:159], v[188:191], v[52:55]
	v_mfma_f32_16x16x32_bf16 v[44:47], v[148:151], v[180:183], v[44:47]
	v_mfma_f32_16x16x32_bf16 v[36:39], v[156:159], v[180:183], v[36:39]
	v_mfma_f32_16x16x32_bf16 v[28:31], v[148:151], v[172:175], v[28:31]
	v_mfma_f32_16x16x32_bf16 v[20:23], v[156:159], v[172:175], v[20:23]
	v_mfma_f32_16x16x32_bf16 v[12:15], v[148:151], v[164:167], v[12:15]
	v_mfma_f32_16x16x32_bf16 v[4:7], v[156:159], v[164:167], v[4:7]
	s_setprio 0
	s_setprio 1
	v_mfma_f32_16x16x32_bf16 v[56:59], v[128:131], v[184:187], v[56:59]
	v_mfma_f32_16x16x32_bf16 v[48:51], v[136:139], v[184:187], v[48:51]
	v_mfma_f32_16x16x32_bf16 v[40:43], v[128:131], v[176:179], v[40:43]
	v_mfma_f32_16x16x32_bf16 v[32:35], v[136:139], v[176:179], v[32:35]
	v_mfma_f32_16x16x32_bf16 v[24:27], v[128:131], v[168:171], v[24:27]
	v_mfma_f32_16x16x32_bf16 v[16:19], v[136:139], v[168:171], v[16:19]
	v_mfma_f32_16x16x32_bf16 v[8:11], v[128:131], v[160:163], v[8:11]
	v_mfma_f32_16x16x32_bf16 v[0:3], v[136:139], v[160:163], v[0:3]
	v_mfma_f32_16x16x32_bf16 v[56:59], v[132:135], v[188:191], v[56:59]
	v_mfma_f32_16x16x32_bf16 v[48:51], v[140:143], v[188:191], v[48:51]
	v_mfma_f32_16x16x32_bf16 v[40:43], v[132:135], v[180:183], v[40:43]
	v_mfma_f32_16x16x32_bf16 v[32:35], v[140:143], v[180:183], v[32:35]
	v_mfma_f32_16x16x32_bf16 v[24:27], v[132:135], v[172:175], v[24:27]
	v_mfma_f32_16x16x32_bf16 v[16:19], v[140:143], v[172:175], v[16:19]
	v_mfma_f32_16x16x32_bf16 v[8:11], v[132:135], v[164:167], v[8:11]
	v_mfma_f32_16x16x32_bf16 v[0:3], v[140:143], v[164:167], v[0:3]
	s_setprio 0
	s_barrier
	s_add_i32 s36, 0, 0x18000
	s_add_i32 s37, 0, 0x1c000
	v_add_u32_e32 v140, s36, v221
	v_add_u32_e32 v156, s37, v221
	ds_read_b128 v[128:131], v140
	ds_read_b128 v[132:135], v140 offset:1024
	ds_read_b128 v[136:139], v140 offset:2048
	ds_read_b128 v[140:143], v140 offset:3072
	ds_read_b128 v[144:147], v156
	ds_read_b128 v[148:151], v156 offset:1024
	ds_read_b128 v[152:155], v156 offset:2048
	ds_read_b128 v[156:159], v156 offset:3072
	s_add_u32 s34, s34, 0x80000
	s_addc_u32 s35, s35, 0
	s_mov_b32 m0, s48
	ds_read_b128 v[160:163], v225 offset:32768
	ds_read_b128 v[164:167], v225 offset:33792
	ds_read_b128 v[168:171], v225 offset:34816
	ds_read_b128 v[172:175], v225 offset:35840
	ds_read_b128 v[176:179], v225 offset:36864
	ds_read_b128 v[180:183], v225 offset:37888
	ds_read_b128 v[184:187], v225 offset:38912
	ds_read_b128 v[188:191], v225 offset:39936
	global_load_lds_dwordx4 v198, s[34:35]
	s_mov_b32 m0, s49
	s_nop 0
	global_load_lds_dwordx4 v194, s[34:35]
	s_waitcnt vmcnt(8)
	s_waitcnt lgkmcnt(0)
	s_barrier
	s_setprio 1
	s_waitcnt lgkmcnt(0)
	v_mfma_f32_16x16x32_bf16 v[124:127], v[128:131], v[160:163], v[124:127]
	v_mfma_f32_16x16x32_bf16 v[116:119], v[136:139], v[160:163], v[116:119]
	v_mfma_f32_16x16x32_bf16 v[108:111], v[128:131], v[168:171], v[108:111]
	v_mfma_f32_16x16x32_bf16 v[100:103], v[136:139], v[168:171], v[100:103]
	v_mfma_f32_16x16x32_bf16 v[92:95], v[128:131], v[176:179], v[92:95]
	v_mfma_f32_16x16x32_bf16 v[84:87], v[136:139], v[176:179], v[84:87]
	v_mfma_f32_16x16x32_bf16 v[76:79], v[128:131], v[184:187], v[76:79]
	v_mfma_f32_16x16x32_bf16 v[68:71], v[136:139], v[184:187], v[68:71]
	v_mfma_f32_16x16x32_bf16 v[124:127], v[132:135], v[164:167], v[124:127]
	v_mfma_f32_16x16x32_bf16 v[116:119], v[140:143], v[164:167], v[116:119]
	v_mfma_f32_16x16x32_bf16 v[108:111], v[132:135], v[172:175], v[108:111]
	v_mfma_f32_16x16x32_bf16 v[100:103], v[140:143], v[172:175], v[100:103]
	v_mfma_f32_16x16x32_bf16 v[92:95], v[132:135], v[180:183], v[92:95]
	v_mfma_f32_16x16x32_bf16 v[84:87], v[140:143], v[180:183], v[84:87]
	v_mfma_f32_16x16x32_bf16 v[76:79], v[132:135], v[188:191], v[76:79]
	v_mfma_f32_16x16x32_bf16 v[68:71], v[140:143], v[188:191], v[68:71]
	s_setprio 0
	s_setprio 1
	v_mfma_f32_16x16x32_bf16 v[120:123], v[144:147], v[160:163], v[120:123]
	v_mfma_f32_16x16x32_bf16 v[112:115], v[152:155], v[160:163], v[112:115]
	v_mfma_f32_16x16x32_bf16 v[104:107], v[144:147], v[168:171], v[104:107]
	v_mfma_f32_16x16x32_bf16 v[96:99], v[152:155], v[168:171], v[96:99]
	v_mfma_f32_16x16x32_bf16 v[88:91], v[144:147], v[176:179], v[88:91]
	v_mfma_f32_16x16x32_bf16 v[80:83], v[152:155], v[176:179], v[80:83]
	v_mfma_f32_16x16x32_bf16 v[72:75], v[144:147], v[184:187], v[72:75]
	v_mfma_f32_16x16x32_bf16 v[64:67], v[152:155], v[184:187], v[64:67]
	v_mfma_f32_16x16x32_bf16 v[120:123], v[148:151], v[164:167], v[120:123]
	v_mfma_f32_16x16x32_bf16 v[112:115], v[156:159], v[164:167], v[112:115]
	v_mfma_f32_16x16x32_bf16 v[104:107], v[148:151], v[172:175], v[104:107]
	v_mfma_f32_16x16x32_bf16 v[96:99], v[156:159], v[172:175], v[96:99]
	v_mfma_f32_16x16x32_bf16 v[88:91], v[148:151], v[180:183], v[88:91]
	v_mfma_f32_16x16x32_bf16 v[80:83], v[156:159], v[180:183], v[80:83]
	v_mfma_f32_16x16x32_bf16 v[72:75], v[148:151], v[188:191], v[72:75]
	v_mfma_f32_16x16x32_bf16 v[64:67], v[156:159], v[188:191], v[64:67]
	s_setprio 0
	s_barrier
; #define PG8_STAGE(bufoff, gbase, voff) do { _Pragma("unroll") for (int _i = 0; _i < 2; ++_i) \
;         __builtin_amdgcn_global_load_lds((const unsigned*)((const char*)(gbase) + (voff)[_i]), (LAS unsigned*)(lds + (bufoff) + ldsw + _i * 8192), 16, 0, ((voff) == voffA ? AUXA : 0)); } while (0)
; #define PG8_LDA(dst, b, h) do { _Pragma("unroll") for (int m = 0; m < 4; ++m) _Pragma("unroll") for (int k = 0; k < 2; ++k) dst[m][k] = *(const LAS bf16x8*)(lds + PG8_SA(b, h) + aoff + m * 2048 + k * 1024); } while (0)
; #define PG8_LDB(dst, b, h) do { _Pragma("unroll") for (int n = 0; n < 2; ++n) _Pragma("unroll") for (int k = 0; k < 2; ++k) dst[n][k] = *(const LAS bf16x8*)(lds + PG8_SB(b, h) + boff + n * 2048 + k * 1024); } while (0)
; #define PG8_MMA(ai, bj, At, Bt) do { __builtin_amdgcn_s_setprio(1); _Pragma("unroll") for (int m = 0; m < 4; ++m) _Pragma("unroll") for (int n = 0; n < 2; ++n) _Pragma("unroll") for (int k = 0; k < 2; ++k) \
;         acc[ai][bj][m][n] = __builtin_amdgcn_mfma_f32_16x16x32_bf16(Bt[n][k], At[m][k], acc[ai][bj][m][n], 0, 0, 0); __builtin_amdgcn_s_setprio(0); } while (0)
; #define PG8_WAIT_V(n) asm volatile("s_waitcnt vmcnt(" #n ")" ::: "memory")
; #define PG8_WAIT_L(n) asm volatile("s_waitcnt lgkmcnt(" #n ")" ::: "memory")
; #define PG8_BAR __builtin_amdgcn_s_barrier()
; #define PG8_SCHED __builtin_amdgcn_sched_barrier(0)
;     ...
;         for (int t = 0; t < nt; t += 2) {
;             const bool last = (t == nt - 2);
;             const char* a1 = cA + (size_t)(t + 1) * kstep;
;             const char* a2 = last ? nA : cA + (size_t)(t + 2) * kstep; const char* b2 = last ? nB : cB + (size_t)(t + 2) * kstep;
;             const char* a3 = a2 + kstep; const char* b3 = b2 + kstep;
;             PG8_LDB(B0, 0, 0); PG8_LDB(B1, 0, 1); PG8_SCHED; PG8_LDA(At, 0, 0); PG8_STAGE(PG8_SA(1, 1), a1 + hsA, voffA);
;             if (Epi::NPRE != 0 && last) { E.pre(sv, cur, wr, fr); PG8_WAIT_V(16); } else { PG8_WAIT_V(8); }
;     ...
;             PG8_LDA(At, 1, 1); PG8_STAGE(PG8_SB(1, 0), b3, voffB); PG8_STAGE(PG8_SB(1, 1), b3 + hsB, voffB); PG8_STAGE(PG8_SA(1, 0), a3, voffA);
;             PG8_WAIT_V(8); PG8_WAIT_L(0); PG8_BAR; PG8_MMA(1, 0, At, B0); PG8_MMA(1, 1, At, B1); PG8_BAR; PG8_SCHED;
	s_add_i32 s34, s36, s5
	s_mov_b32 m0, s34
	ds_read_b128 v[160:163], v225 offset:49152
	ds_read_b128 v[164:167], v225 offset:50176
	ds_read_b128 v[168:171], v225 offset:51200
	ds_read_b128 v[172:175], v225 offset:52224
	ds_read_b128 v[176:179], v225 offset:53248
	ds_read_b128 v[180:183], v225 offset:54272
	ds_read_b128 v[184:187], v225 offset:55296
	ds_read_b128 v[188:191], v225 offset:56320
	global_load_lds_dwordx4 v196, s[98:99]
	s_add_i32 m0, s34, 0x2000
	s_add_u32 s30, s30, 0x80080
	s_addc_u32 s31, s31, 0
	s_add_i32 s34, s37, s5
	global_load_lds_dwordx4 v192, s[98:99]
	s_mov_b32 m0, s34
	s_nop 0
	global_load_lds_dwordx4 v196, s[30:31]
	s_add_i32 m0, s34, 0x2000
	s_nop 0
	global_load_lds_dwordx4 v192, s[30:31]
	s_mov_b32 m0, s52
	s_nop 0
	global_load_lds_dwordx4 v198, s[100:101]
	s_mov_b32 m0, s53
	s_nop 0
	global_load_lds_dwordx4 v194, s[100:101]
	s_waitcnt vmcnt(8)
	s_waitcnt lgkmcnt(0)
	s_barrier
	s_setprio 1
	s_waitcnt lgkmcnt(0)
	v_mfma_f32_16x16x32_bf16 v[60:63], v[128:131], v[160:163], v[60:63]
	v_mfma_f32_16x16x32_bf16 v[52:55], v[136:139], v[160:163], v[52:55]
	v_mfma_f32_16x16x32_bf16 v[44:47], v[128:131], v[168:171], v[44:47]
	v_mfma_f32_16x16x32_bf16 v[36:39], v[136:139], v[168:171], v[36:39]
	v_mfma_f32_16x16x32_bf16 v[28:31], v[128:131], v[176:179], v[28:31]
	v_mfma_f32_16x16x32_bf16 v[20:23], v[136:139], v[176:179], v[20:23]
	v_mfma_f32_16x16x32_bf16 v[12:15], v[128:131], v[184:187], v[12:15]
	v_mfma_f32_16x16x32_bf16 v[4:7], v[136:139], v[184:187], v[4:7]
	v_mfma_f32_16x16x32_bf16 v[60:63], v[132:135], v[164:167], v[60:63]
	v_mfma_f32_16x16x32_bf16 v[52:55], v[140:143], v[164:167], v[52:55]
	v_mfma_f32_16x16x32_bf16 v[44:47], v[132:135], v[172:175], v[44:47]
	v_mfma_f32_16x16x32_bf16 v[36:39], v[140:143], v[172:175], v[36:39]
	v_mfma_f32_16x16x32_bf16 v[28:31], v[132:135], v[180:183], v[28:31]
	v_mfma_f32_16x16x32_bf16 v[20:23], v[140:143], v[180:183], v[20:23]
	v_mfma_f32_16x16x32_bf16 v[12:15], v[132:135], v[188:191], v[12:15]
	v_mfma_f32_16x16x32_bf16 v[4:7], v[140:143], v[188:191], v[4:7]
	s_setprio 0
	s_setprio 1
	v_mfma_f32_16x16x32_bf16 v[56:59], v[144:147], v[160:163], v[56:59]
	v_mfma_f32_16x16x32_bf16 v[48:51], v[152:155], v[160:163], v[48:51]
	v_mfma_f32_16x16x32_bf16 v[40:43], v[144:147], v[168:171], v[40:43]
	v_mfma_f32_16x16x32_bf16 v[32:35], v[152:155], v[168:171], v[32:35]
	v_mfma_f32_16x16x32_bf16 v[24:27], v[144:147], v[176:179], v[24:27]
	v_mfma_f32_16x16x32_bf16 v[16:19], v[152:155], v[176:179], v[16:19]
	v_mfma_f32_16x16x32_bf16 v[8:11], v[144:147], v[184:187], v[8:11]
	v_mfma_f32_16x16x32_bf16 v[0:3], v[152:155], v[184:187], v[0:3]
	v_mfma_f32_16x16x32_bf16 v[56:59], v[148:151], v[164:167], v[56:59]
	v_mfma_f32_16x16x32_bf16 v[48:51], v[156:159], v[164:167], v[48:51]
	v_mfma_f32_16x16x32_bf16 v[40:43], v[148:151], v[172:175], v[40:43]
	v_mfma_f32_16x16x32_bf16 v[32:35], v[156:159], v[172:175], v[32:35]
	v_mfma_f32_16x16x32_bf16 v[24:27], v[148:151], v[180:183], v[24:27]
	v_mfma_f32_16x16x32_bf16 v[16:19], v[156:159], v[180:183], v[16:19]
	v_mfma_f32_16x16x32_bf16 v[8:11], v[148:151], v[188:191], v[8:11]
	v_mfma_f32_16x16x32_bf16 v[0:3], v[156:159], v[188:191], v[0:3]
	s_setprio 0
	s_barrier
	s_add_u32 s28, s28, 0x100
	s_addc_u32 s29, s29, 0
	s_add_u32 s60, s60, 0x100
	s_addc_u32 s61, s61, 0
	s_cmp_ge_i32 s62, s51
	s_cbranch_scc1 .LBB0_1194
.LBB0_1185:
	ds_read_b128 v[144:147], v223
	ds_read_b128 v[148:151], v223 offset:1024
	ds_read_b128 v[152:155], v223 offset:2048
	ds_read_b128 v[156:159], v223 offset:3072
	ds_read_b128 v[128:131], v224
	ds_read_b128 v[132:135], v224 offset:1024
	ds_read_b128 v[136:139], v224 offset:2048
	ds_read_b128 v[140:143], v224 offset:3072
	s_cmp_eq_u32 s54, s62
	s_cselect_b64 s[30:31], -1, 0
	s_cmp_lg_u32 s54, s62
	s_cselect_b64 s[36:37], -1, 0
	s_add_i32 m0, s42, 0xc000
	ds_read_b128 v[184:187], v225
	ds_read_b128 v[188:191], v225 offset:1024
	ds_read_b128 v[176:179], v225 offset:2048
	ds_read_b128 v[180:183], v225 offset:3072
	ds_read_b128 v[168:171], v225 offset:4096
	ds_read_b128 v[172:175], v225 offset:5120
	ds_read_b128 v[160:163], v225 offset:6144
	ds_read_b128 v[164:167], v225 offset:7168
	global_load_lds_dwordx4 v200, s[28:29]
	s_add_i32 m0, s42, 0xe000
	s_mov_b64 s[34:35], -1
	global_load_lds_dwordx4 v202, s[28:29]
	s_and_b64 vcc, exec, s[36:37]
	s_cbranch_vccz .LBB0_1187
	s_waitcnt vmcnt(8)
	s_mov_b64 s[34:35], 0

; #define PG8_STAGE(bufoff, gbase, voff) do { _Pragma("unroll") for (int _i = 0; _i < 2; ++_i) \
;         __builtin_amdgcn_global_load_lds((const unsigned*)((const char*)(gbase) + (voff)[_i]), (LAS unsigned*)(lds + (bufoff) + ldsw + _i * 8192), 16, 0, ((voff) == voffA ? AUXA : 0)); } while (0)
; #define PG8_LDA(dst, b, h) do { _Pragma("unroll") for (int m = 0; m < 4; ++m) _Pragma("unroll") for (int k = 0; k < 2; ++k) dst[m][k] = *(const LAS bf16x8*)(lds + PG8_SA(b, h) + aoff + m * 2048 + k * 1024); } while (0)
; #define PG8_LDB(dst, b, h) do { _Pragma("unroll") for (int n = 0; n < 2; ++n) _Pragma("unroll") for (int k = 0; k < 2; ++k) dst[n][k] = *(const LAS bf16x8*)(lds + PG8_SB(b, h) + boff + n * 2048 + k * 1024); } while (0)
; #define PG8_MMA(ai, bj, At, Bt) do { __builtin_amdgcn_s_setprio(1); _Pragma("unroll") for (int m = 0; m < 4; ++m) _Pragma("unroll") for (int n = 0; n < 2; ++n) _Pragma("unroll") for (int k = 0; k < 2; ++k) \
;         acc[ai][bj][m][n] = __builtin_amdgcn_mfma_f32_16x16x32_bf16(Bt[n][k], At[m][k], acc[ai][bj][m][n], 0, 0, 0); __builtin_amdgcn_s_setprio(0); } while (0)
; #define PG8_WAIT_V(n) asm volatile("s_waitcnt vmcnt(" #n ")" ::: "memory")
; #define PG8_WAIT_L(n) asm volatile("s_waitcnt lgkmcnt(" #n ")" ::: "memory")
; #define PG8_BAR __builtin_amdgcn_s_barrier()
; #define PG8_SCHED __builtin_amdgcn_sched_barrier(0)
;     ...
;             const char* a2 = last ? nA : cA + (size_t)(t + 2) * kstep; const char* b2 = last ? nB : cB + (size_t)(t + 2) * kstep;
;             const char* a3 = a2 + kstep; const char* b3 = b2 + kstep;
;             PG8_LDB(B0, 0, 0); PG8_LDB(B1, 0, 1); PG8_SCHED; PG8_LDA(At, 0, 0); PG8_STAGE(PG8_SA(1, 1), a1 + hsA, voffA);
;             if (Epi::NPRE != 0 && last) { E.pre(sv, cur, wr, fr); PG8_WAIT_V(16); } else { PG8_WAIT_V(8); }
;             PG8_WAIT_L(0); PG8_BAR; PG8_MMA(0, 0, At, B0); PG8_MMA(0, 1, At, B1); PG8_BAR; PG8_SCHED;
;             PG8_LDA(At, 0, 1); PG8_STAGE(PG8_SB(0, 0), b2, voffB); PG8_STAGE(PG8_SB(0, 1), b2 + hsB, voffB); PG8_STAGE(PG8_SA(0, 0), a2, voffA);
;             if (Epi::NPRE != 0 && last) { PG8_WAIT_V(16); } else { PG8_WAIT_V(8); }
.LBB0_1189:
	s_add_u32 s34, s28, 0xfff80080
	s_addc_u32 s35, s29, -1
	s_waitcnt lgkmcnt(0)
	s_and_b64 s[30:31], s[30:31], exec
	s_cselect_b32 s35, s21, s35
	s_cselect_b32 s34, s23, s34
	s_cselect_b32 s31, s58, s61
	s_cselect_b32 s30, s59, s60
	s_barrier
	s_setprio 1
	s_waitcnt lgkmcnt(0)
	v_mfma_f32_16x16x32_bf16 v[124:127], v[144:147], v[184:187], v[124:127]
	v_mfma_f32_16x16x32_bf16 v[116:119], v[152:155], v[184:187], v[116:119]
	v_mfma_f32_16x16x32_bf16 v[108:111], v[144:147], v[176:179], v[108:111]
	v_mfma_f32_16x16x32_bf16 v[100:103], v[152:155], v[176:179], v[100:103]
	v_mfma_f32_16x16x32_bf16 v[92:95], v[144:147], v[168:171], v[92:95]
	v_mfma_f32_16x16x32_bf16 v[84:87], v[152:155], v[168:171], v[84:87]
	v_mfma_f32_16x16x32_bf16 v[76:79], v[144:147], v[160:163], v[76:79]
	v_mfma_f32_16x16x32_bf16 v[68:71], v[152:155], v[160:163], v[68:71]
	v_mfma_f32_16x16x32_bf16 v[124:127], v[148:151], v[188:191], v[124:127]
	v_mfma_f32_16x16x32_bf16 v[116:119], v[156:159], v[188:191], v[116:119]
	v_mfma_f32_16x16x32_bf16 v[108:111], v[148:151], v[180:183], v[108:111]
	v_mfma_f32_16x16x32_bf16 v[100:103], v[156:159], v[180:183], v[100:103]
	v_mfma_f32_16x16x32_bf16 v[92:95], v[148:151], v[172:175], v[92:95]
	v_mfma_f32_16x16x32_bf16 v[84:87], v[156:159], v[172:175], v[84:87]
	v_mfma_f32_16x16x32_bf16 v[76:79], v[148:151], v[164:167], v[76:79]
	v_mfma_f32_16x16x32_bf16 v[68:71], v[156:159], v[164:167], v[68:71]
	s_setprio 0
	s_setprio 1
	v_mfma_f32_16x16x32_bf16 v[120:123], v[128:131], v[184:187], v[120:123]
	v_mfma_f32_16x16x32_bf16 v[112:115], v[136:139], v[184:187], v[112:115]
	v_mfma_f32_16x16x32_bf16 v[104:107], v[128:131], v[176:179], v[104:107]
	v_mfma_f32_16x16x32_bf16 v[96:99], v[136:139], v[176:179], v[96:99]
	v_mfma_f32_16x16x32_bf16 v[88:91], v[128:131], v[168:171], v[88:91]
	v_mfma_f32_16x16x32_bf16 v[80:83], v[136:139], v[168:171], v[80:83]
	v_mfma_f32_16x16x32_bf16 v[72:75], v[128:131], v[160:163], v[72:75]
	v_mfma_f32_16x16x32_bf16 v[64:67], v[136:139], v[160:163], v[64:67]
	v_mfma_f32_16x16x32_bf16 v[120:123], v[132:135], v[188:191], v[120:123]
	v_mfma_f32_16x16x32_bf16 v[112:115], v[140:143], v[188:191], v[112:115]
	v_mfma_f32_16x16x32_bf16 v[104:107], v[132:135], v[180:183], v[104:107]
	v_mfma_f32_16x16x32_bf16 v[96:99], v[140:143], v[180:183], v[96:99]
	v_mfma_f32_16x16x32_bf16 v[88:91], v[132:135], v[172:175], v[88:91]
	v_mfma_f32_16x16x32_bf16 v[80:83], v[140:143], v[172:175], v[80:83]
	v_mfma_f32_16x16x32_bf16 v[72:75], v[132:135], v[164:167], v[72:75]
	v_mfma_f32_16x16x32_bf16 v[64:67], v[140:143], v[164:167], v[64:67]
	s_setprio 0
	s_barrier
	s_add_u32 s98, s30, s16
	s_addc_u32 s99, s31, s17
	s_add_u32 s100, s34, s16
	s_addc_u32 s101, s35, s17
	s_mov_b32 m0, s43
	s_add_u32 s38, s30, 0x80000
	ds_read_b128 v[184:187], v225 offset:16384
	ds_read_b128 v[188:191], v225 offset:17408
	ds_read_b128 v[176:179], v225 offset:18432
	ds_read_b128 v[180:183], v225 offset:19456
	ds_read_b128 v[168:171], v225 offset:20480
	ds_read_b128 v[172:175], v225 offset:21504
	ds_read_b128 v[160:163], v225 offset:22528
	ds_read_b128 v[164:167], v225 offset:23552
	global_load_lds_dwordx4 v196, s[30:31]
	s_mov_b32 m0, s44
	s_addc_u32 s39, s31, 0
	global_load_lds_dwordx4 v192, s[30:31]
	s_mov_b32 m0, s45
	s_nop 0
	global_load_lds_dwordx4 v196, s[38:39]
	s_mov_b32 m0, s46
	s_nop 0
	global_load_lds_dwordx4 v192, s[38:39]
	s_mov_b64 s[38:39], -1
	s_mov_b32 m0, s42
	s_and_b64 vcc, exec, s[36:37]
	global_load_lds_dwordx4 v198, s[34:35]
	s_mov_b32 m0, s47
	s_nop 0
	global_load_lds_dwordx4 v194, s[34:35]
	s_cbranch_vccz .LBB0_1191
	s_waitcnt vmcnt(8)
	s_mov_b64 s[38:39], 0

; #define PG8_STAGE(bufoff, gbase, voff) do { _Pragma("unroll") for (int _i = 0; _i < 2; ++_i) \
;         __builtin_amdgcn_global_load_lds((const unsigned*)((const char*)(gbase) + (voff)[_i]), (LAS unsigned*)(lds + (bufoff) + ldsw + _i * 8192), 16, 0, ((voff) == voffA ? AUXA : 0)); } while (0)
; #define PG8_LDA(dst, b, h) do { _Pragma("unroll") for (int m = 0; m < 4; ++m) _Pragma("unroll") for (int k = 0; k < 2; ++k) dst[m][k] = *(const LAS bf16x8*)(lds + PG8_SA(b, h) + aoff + m * 2048 + k * 1024); } while (0)
; #define PG8_LDB(dst, b, h) do { _Pragma("unroll") for (int n = 0; n < 2; ++n) _Pragma("unroll") for (int k = 0; k < 2; ++k) dst[n][k] = *(const LAS bf16x8*)(lds + PG8_SB(b, h) + boff + n * 2048 + k * 1024); } while (0)
; #define PG8_MMA(ai, bj, At, Bt) do { __builtin_amdgcn_s_setprio(1); _Pragma("unroll") for (int m = 0; m < 4; ++m) _Pragma("unroll") for (int n = 0; n < 2; ++n) _Pragma("unroll") for (int k = 0; k < 2; ++k) \
;         acc[ai][bj][m][n] = __builtin_amdgcn_mfma_f32_16x16x32_bf16(Bt[n][k], At[m][k], acc[ai][bj][m][n], 0, 0, 0); __builtin_amdgcn_s_setprio(0); } while (0)
; #define PG8_WAIT_V(n) asm volatile("s_waitcnt vmcnt(" #n ")" ::: "memory")
; #define PG8_WAIT_L(n) asm volatile("s_waitcnt lgkmcnt(" #n ")" ::: "memory")
; #define PG8_BAR __builtin_amdgcn_s_barrier()
; #define PG8_SCHED __builtin_amdgcn_sched_barrier(0)
;     ...
;             PG8_LDB(B0, 0, 0); PG8_LDB(B1, 0, 1); PG8_SCHED; PG8_LDA(At, 0, 0); PG8_STAGE(PG8_SA(1, 1), a1 + hsA, voffA);
;             if (Epi::NPRE != 0 && last) { E.pre(sv, cur, wr, fr); PG8_WAIT_V(16); } else { PG8_WAIT_V(8); }
;             PG8_WAIT_L(0); PG8_BAR; PG8_MMA(0, 0, At, B0); PG8_MMA(0, 1, At, B1); PG8_BAR; PG8_SCHED;
;             PG8_LDA(At, 0, 1); PG8_STAGE(PG8_SB(0, 0), b2, voffB); PG8_STAGE(PG8_SB(0, 1), b2 + hsB, voffB); PG8_STAGE(PG8_SA(0, 0), a2, voffA);
;             if (Epi::NPRE != 0 && last) { PG8_WAIT_V(16); } else { PG8_WAIT_V(8); }
;             PG8_WAIT_L(0); PG8_BAR; PG8_MMA(1, 0, At, B0); PG8_MMA(1, 1, At, B1); PG8_BAR; PG8_SCHED;
.LBB0_1267:
	ds_read_b128 v[128:131], v189
	ds_read_b128 v[132:135], v189 offset:1024
	ds_read_b128 v[136:139], v189 offset:2048
	ds_read_b128 v[140:143], v189 offset:3072
	ds_read_b128 v[144:147], v190
	ds_read_b128 v[148:151], v190 offset:1024
	ds_read_b128 v[168:171], v190 offset:2048
	ds_read_b128 v[172:175], v190 offset:3072
	s_add_i32 s58, s36, 2
	s_add_u32 s37, s34, 0xfff80080
	s_addc_u32 s38, s35, -1
	s_cmp_eq_u32 s49, s36
	s_cselect_b32 s36, s55, s56
	s_cselect_b32 s39, s21, s38
	s_cselect_b32 s38, s23, s37
	s_cselect_b32 s37, s29, s57
	s_add_i32 m0, s31, 0xc000
	ds_read_b128 v[176:179], v191
	ds_read_b128 v[180:183], v191 offset:1024
	ds_read_b128 v[194:197], v191 offset:2048
	ds_read_b128 v[198:201], v191 offset:3072
	ds_read_b128 v[202:205], v191 offset:4096
	ds_read_b128 v[206:209], v191 offset:5120
	ds_read_b128 v[210:213], v191 offset:6144
	ds_read_b128 v[214:217], v191 offset:7168
	global_load_lds_dwordx4 v160, s[34:35]
	s_add_i32 m0, s31, 0xe000
	s_nop 0
	global_load_lds_dwordx4 v162, s[34:35]
	s_waitcnt vmcnt(8)
	s_waitcnt lgkmcnt(0)
	s_barrier
	s_setprio 1
	s_waitcnt lgkmcnt(0)
	v_mfma_f32_16x16x32_bf16 v[124:127], v[128:131], v[176:179], v[124:127]
	v_mfma_f32_16x16x32_bf16 v[120:123], v[136:139], v[176:179], v[120:123]
	v_mfma_f32_16x16x32_bf16 v[108:111], v[128:131], v[194:197], v[108:111]
	v_mfma_f32_16x16x32_bf16 v[104:107], v[136:139], v[194:197], v[104:107]
	v_mfma_f32_16x16x32_bf16 v[92:95], v[128:131], v[202:205], v[92:95]
	v_mfma_f32_16x16x32_bf16 v[88:91], v[136:139], v[202:205], v[88:91]
	v_mfma_f32_16x16x32_bf16 v[76:79], v[128:131], v[210:213], v[76:79]
	v_mfma_f32_16x16x32_bf16 v[72:75], v[136:139], v[210:213], v[72:75]
	v_mfma_f32_16x16x32_bf16 v[124:127], v[132:135], v[180:183], v[124:127]
	v_mfma_f32_16x16x32_bf16 v[120:123], v[140:143], v[180:183], v[120:123]
	v_mfma_f32_16x16x32_bf16 v[108:111], v[132:135], v[198:201], v[108:111]
	v_mfma_f32_16x16x32_bf16 v[104:107], v[140:143], v[198:201], v[104:107]
	v_mfma_f32_16x16x32_bf16 v[92:95], v[132:135], v[206:209], v[92:95]
	v_mfma_f32_16x16x32_bf16 v[88:91], v[140:143], v[206:209], v[88:91]
	v_mfma_f32_16x16x32_bf16 v[76:79], v[132:135], v[214:217], v[76:79]
	v_mfma_f32_16x16x32_bf16 v[72:75], v[140:143], v[214:217], v[72:75]
	s_setprio 0
	s_setprio 1
	v_mfma_f32_16x16x32_bf16 v[116:119], v[144:147], v[176:179], v[116:119]
	v_mfma_f32_16x16x32_bf16 v[112:115], v[168:171], v[176:179], v[112:115]
	v_mfma_f32_16x16x32_bf16 v[100:103], v[144:147], v[194:197], v[100:103]
	v_mfma_f32_16x16x32_bf16 v[96:99], v[168:171], v[194:197], v[96:99]
	v_mfma_f32_16x16x32_bf16 v[84:87], v[144:147], v[202:205], v[84:87]
	v_mfma_f32_16x16x32_bf16 v[80:83], v[168:171], v[202:205], v[80:83]
	v_mfma_f32_16x16x32_bf16 v[68:71], v[144:147], v[210:213], v[68:71]
	v_mfma_f32_16x16x32_bf16 v[64:67], v[168:171], v[210:213], v[64:67]
	v_mfma_f32_16x16x32_bf16 v[116:119], v[148:151], v[180:183], v[116:119]
	v_mfma_f32_16x16x32_bf16 v[112:115], v[172:175], v[180:183], v[112:115]
	v_mfma_f32_16x16x32_bf16 v[100:103], v[148:151], v[198:201], v[100:103]
	v_mfma_f32_16x16x32_bf16 v[96:99], v[172:175], v[198:201], v[96:99]
	v_mfma_f32_16x16x32_bf16 v[84:87], v[148:151], v[206:209], v[84:87]
	v_mfma_f32_16x16x32_bf16 v[80:83], v[172:175], v[206:209], v[80:83]
	v_mfma_f32_16x16x32_bf16 v[68:71], v[148:151], v[214:217], v[68:71]
	v_mfma_f32_16x16x32_bf16 v[64:67], v[172:175], v[214:217], v[64:67]
	s_setprio 0
	s_barrier
	s_add_u32 s98, s36, s16
	s_addc_u32 s99, s37, s17
	s_add_u32 s100, s38, s16
	s_addc_u32 s101, s39, s17
	s_add_i32 s59, s53, s41
	s_mov_b32 m0, s59
	ds_read_b128 v[176:179], v191 offset:16384
	ds_read_b128 v[180:183], v191 offset:17408
	ds_read_b128 v[194:197], v191 offset:18432
	ds_read_b128 v[198:201], v191 offset:19456
	ds_read_b128 v[202:205], v191 offset:20480
	ds_read_b128 v[206:209], v191 offset:21504
	ds_read_b128 v[210:213], v191 offset:22528
	ds_read_b128 v[214:217], v191 offset:23552
	global_load_lds_dwordx4 v154, s[36:37]
	s_add_i32 m0, s59, 0x2000
	s_add_u32 s60, s36, 0x80000
	s_addc_u32 s61, s37, 0
	s_add_i32 s59, s54, s41
	global_load_lds_dwordx4 v158, s[36:37]
	s_mov_b32 m0, s59
	s_nop 0
	global_load_lds_dwordx4 v154, s[60:61]
	s_add_i32 m0, s59, 0x2000
	s_nop 0
	global_load_lds_dwordx4 v158, s[60:61]
	s_mov_b32 m0, s31
	s_nop 0
	global_load_lds_dwordx4 v152, s[38:39]
	s_mov_b32 m0, s42
	s_nop 0
	global_load_lds_dwordx4 v156, s[38:39]
	s_waitcnt vmcnt(8)
	s_waitcnt lgkmcnt(0)
	s_barrier
	s_setprio 1
	s_waitcnt lgkmcnt(0)
	v_mfma_f32_16x16x32_bf16 v[60:63], v[128:131], v[176:179], v[60:63]
	v_mfma_f32_16x16x32_bf16 v[56:59], v[136:139], v[176:179], v[56:59]
	v_mfma_f32_16x16x32_bf16 v[44:47], v[128:131], v[194:197], v[44:47]
	v_mfma_f32_16x16x32_bf16 v[40:43], v[136:139], v[194:197], v[40:43]
	v_mfma_f32_16x16x32_bf16 v[28:31], v[128:131], v[202:205], v[28:31]
	v_mfma_f32_16x16x32_bf16 v[24:27], v[136:139], v[202:205], v[24:27]
	v_mfma_f32_16x16x32_bf16 v[12:15], v[128:131], v[210:213], v[12:15]
	v_mfma_f32_16x16x32_bf16 v[8:11], v[136:139], v[210:213], v[8:11]
	v_mfma_f32_16x16x32_bf16 v[60:63], v[132:135], v[180:183], v[60:63]
	v_mfma_f32_16x16x32_bf16 v[56:59], v[140:143], v[180:183], v[56:59]
	v_mfma_f32_16x16x32_bf16 v[44:47], v[132:135], v[198:201], v[44:47]
	v_mfma_f32_16x16x32_bf16 v[40:43], v[140:143], v[198:201], v[40:43]
	v_mfma_f32_16x16x32_bf16 v[28:31], v[132:135], v[206:209], v[28:31]
	v_mfma_f32_16x16x32_bf16 v[24:27], v[140:143], v[206:209], v[24:27]
	v_mfma_f32_16x16x32_bf16 v[12:15], v[132:135], v[214:217], v[12:15]
	v_mfma_f32_16x16x32_bf16 v[8:11], v[140:143], v[214:217], v[8:11]
	s_setprio 0
	s_setprio 1
	v_mfma_f32_16x16x32_bf16 v[52:55], v[144:147], v[176:179], v[52:55]
	v_mfma_f32_16x16x32_bf16 v[48:51], v[168:171], v[176:179], v[48:51]
	v_mfma_f32_16x16x32_bf16 v[36:39], v[144:147], v[194:197], v[36:39]
	v_mfma_f32_16x16x32_bf16 v[32:35], v[168:171], v[194:197], v[32:35]
	v_mfma_f32_16x16x32_bf16 v[20:23], v[144:147], v[202:205], v[20:23]
	v_mfma_f32_16x16x32_bf16 v[16:19], v[168:171], v[202:205], v[16:19]
	v_mfma_f32_16x16x32_bf16 v[4:7], v[144:147], v[210:213], v[4:7]
	v_mfma_f32_16x16x32_bf16 v[0:3], v[168:171], v[210:213], v[0:3]
	v_mfma_f32_16x16x32_bf16 v[52:55], v[148:151], v[180:183], v[52:55]
	v_mfma_f32_16x16x32_bf16 v[48:51], v[172:175], v[180:183], v[48:51]
	v_mfma_f32_16x16x32_bf16 v[36:39], v[148:151], v[198:201], v[36:39]
	v_mfma_f32_16x16x32_bf16 v[32:35], v[172:175], v[198:201], v[32:35]
	v_mfma_f32_16x16x32_bf16 v[20:23], v[148:151], v[206:209], v[20:23]
	v_mfma_f32_16x16x32_bf16 v[16:19], v[172:175], v[206:209], v[16:19]
	v_mfma_f32_16x16x32_bf16 v[4:7], v[148:151], v[214:217], v[4:7]
	v_mfma_f32_16x16x32_bf16 v[0:3], v[172:175], v[214:217], v[0:3]
	s_setprio 0
	s_barrier
; #define PG8_STAGE(bufoff, gbase, voff) do { _Pragma("unroll") for (int _i = 0; _i < 2; ++_i) \
;         __builtin_amdgcn_global_load_lds((const unsigned*)((const char*)(gbase) + (voff)[_i]), (LAS unsigned*)(lds + (bufoff) + ldsw + _i * 8192), 16, 0, ((voff) == voffA ? AUXA : 0)); } while (0)
; #define PG8_LDA(dst, b, h) do { _Pragma("unroll") for (int m = 0; m < 4; ++m) _Pragma("unroll") for (int k = 0; k < 2; ++k) dst[m][k] = *(const LAS bf16x8*)(lds + PG8_SA(b, h) + aoff + m * 2048 + k * 1024); } while (0)
; #define PG8_LDB(dst, b, h) do { _Pragma("unroll") for (int n = 0; n < 2; ++n) _Pragma("unroll") for (int k = 0; k < 2; ++k) dst[n][k] = *(const LAS bf16x8*)(lds + PG8_SB(b, h) + boff + n * 2048 + k * 1024); } while (0)
; #define PG8_MMA(ai, bj, At, Bt) do { __builtin_amdgcn_s_setprio(1); _Pragma("unroll") for (int m = 0; m < 4; ++m) _Pragma("unroll") for (int n = 0; n < 2; ++n) _Pragma("unroll") for (int k = 0; k < 2; ++k) \
;         acc[ai][bj][m][n] = __builtin_amdgcn_mfma_f32_16x16x32_bf16(Bt[n][k], At[m][k], acc[ai][bj][m][n], 0, 0, 0); __builtin_amdgcn_s_setprio(0); } while (0)
; #define PG8_WAIT_V(n) asm volatile("s_waitcnt vmcnt(" #n ")" ::: "memory")
; #define PG8_WAIT_L(n) asm volatile("s_waitcnt lgkmcnt(" #n ")" ::: "memory")
; #define PG8_BAR __builtin_amdgcn_s_barrier()
; #define PG8_SCHED __builtin_amdgcn_sched_barrier(0)
;     ...
;             PG8_LDB(B0, 1, 0); PG8_LDB(B1, 1, 1); PG8_SCHED; PG8_LDA(At, 1, 0); PG8_STAGE(PG8_SA(0, 1), a2 + hsA, voffA);
;             PG8_WAIT_V(8); PG8_WAIT_L(0); PG8_BAR; PG8_MMA(0, 0, At, B0); PG8_MMA(0, 1, At, B1); PG8_BAR; PG8_SCHED;
;             PG8_LDA(At, 1, 1); PG8_STAGE(PG8_SB(1, 0), b3, voffB); PG8_STAGE(PG8_SB(1, 1), b3 + hsB, voffB); PG8_STAGE(PG8_SA(1, 0), a3, voffA);
;             PG8_WAIT_V(8); PG8_WAIT_L(0); PG8_BAR; PG8_MMA(1, 0, At, B0); PG8_MMA(1, 1, At, B1); PG8_BAR; PG8_SCHED;
;         }
	s_add_i32 s59, 0, 0x18000
	s_add_i32 s60, 0, 0x1c000
	v_add_u32_e32 v140, s59, v187
	v_add_u32_e32 v172, s60, v187
	ds_read_b128 v[128:131], v140
	ds_read_b128 v[132:135], v140 offset:1024
	ds_read_b128 v[136:139], v140 offset:2048
	ds_read_b128 v[140:143], v140 offset:3072
	ds_read_b128 v[144:147], v172
	ds_read_b128 v[148:151], v172 offset:1024
	ds_read_b128 v[168:171], v172 offset:2048
	ds_read_b128 v[172:175], v172 offset:3072
	s_add_u32 s38, s38, 0x80000
	s_addc_u32 s39, s39, 0
	s_mov_b32 m0, s43
	ds_read_b128 v[176:179], v191 offset:32768
	ds_read_b128 v[180:183], v191 offset:33792
	ds_read_b128 v[194:197], v191 offset:34816
	ds_read_b128 v[198:201], v191 offset:35840
	ds_read_b128 v[202:205], v191 offset:36864
	ds_read_b128 v[206:209], v191 offset:37888
	ds_read_b128 v[210:213], v191 offset:38912
	ds_read_b128 v[214:217], v191 offset:39936
	global_load_lds_dwordx4 v152, s[38:39]
	s_mov_b32 m0, s44
	s_nop 0
	global_load_lds_dwordx4 v156, s[38:39]
	s_waitcnt vmcnt(8)
	s_waitcnt lgkmcnt(0)
	s_barrier
	s_setprio 1
	s_waitcnt lgkmcnt(0)
	v_mfma_f32_16x16x32_bf16 v[124:127], v[128:131], v[176:179], v[124:127]
	v_mfma_f32_16x16x32_bf16 v[120:123], v[136:139], v[176:179], v[120:123]
	v_mfma_f32_16x16x32_bf16 v[108:111], v[128:131], v[194:197], v[108:111]
	v_mfma_f32_16x16x32_bf16 v[104:107], v[136:139], v[194:197], v[104:107]
	v_mfma_f32_16x16x32_bf16 v[92:95], v[128:131], v[202:205], v[92:95]
	v_mfma_f32_16x16x32_bf16 v[88:91], v[136:139], v[202:205], v[88:91]
	v_mfma_f32_16x16x32_bf16 v[76:79], v[128:131], v[210:213], v[76:79]
	v_mfma_f32_16x16x32_bf16 v[72:75], v[136:139], v[210:213], v[72:75]
	v_mfma_f32_16x16x32_bf16 v[124:127], v[132:135], v[180:183], v[124:127]
	v_mfma_f32_16x16x32_bf16 v[120:123], v[140:143], v[180:183], v[120:123]
	v_mfma_f32_16x16x32_bf16 v[108:111], v[132:135], v[198:201], v[108:111]
	v_mfma_f32_16x16x32_bf16 v[104:107], v[140:143], v[198:201], v[104:107]
	v_mfma_f32_16x16x32_bf16 v[92:95], v[132:135], v[206:209], v[92:95]
	v_mfma_f32_16x16x32_bf16 v[88:91], v[140:143], v[206:209], v[88:91]
	v_mfma_f32_16x16x32_bf16 v[76:79], v[132:135], v[214:217], v[76:79]
	v_mfma_f32_16x16x32_bf16 v[72:75], v[140:143], v[214:217], v[72:75]
	s_setprio 0
	s_setprio 1
	v_mfma_f32_16x16x32_bf16 v[116:119], v[144:147], v[176:179], v[116:119]
	v_mfma_f32_16x16x32_bf16 v[112:115], v[168:171], v[176:179], v[112:115]
	v_mfma_f32_16x16x32_bf16 v[100:103], v[144:147], v[194:197], v[100:103]
	v_mfma_f32_16x16x32_bf16 v[96:99], v[168:171], v[194:197], v[96:99]
	v_mfma_f32_16x16x32_bf16 v[84:87], v[144:147], v[202:205], v[84:87]
	v_mfma_f32_16x16x32_bf16 v[80:83], v[168:171], v[202:205], v[80:83]
	v_mfma_f32_16x16x32_bf16 v[68:71], v[144:147], v[210:213], v[68:71]
	v_mfma_f32_16x16x32_bf16 v[64:67], v[168:171], v[210:213], v[64:67]
	v_mfma_f32_16x16x32_bf16 v[116:119], v[148:151], v[180:183], v[116:119]
	v_mfma_f32_16x16x32_bf16 v[112:115], v[172:175], v[180:183], v[112:115]
	v_mfma_f32_16x16x32_bf16 v[100:103], v[148:151], v[198:201], v[100:103]
	v_mfma_f32_16x16x32_bf16 v[96:99], v[172:175], v[198:201], v[96:99]
	v_mfma_f32_16x16x32_bf16 v[84:87], v[148:151], v[206:209], v[84:87]
	v_mfma_f32_16x16x32_bf16 v[80:83], v[172:175], v[206:209], v[80:83]
	v_mfma_f32_16x16x32_bf16 v[68:71], v[148:151], v[214:217], v[68:71]
	v_mfma_f32_16x16x32_bf16 v[64:67], v[172:175], v[214:217], v[64:67]
	s_setprio 0
	s_barrier
	s_add_i32 s38, s59, s41
	s_mov_b32 m0, s38
	ds_read_b128 v[176:179], v191 offset:49152
	ds_read_b128 v[180:183], v191 offset:50176
	ds_read_b128 v[194:197], v191 offset:51200
	ds_read_b128 v[198:201], v191 offset:52224
	ds_read_b128 v[202:205], v191 offset:53248
	ds_read_b128 v[206:209], v191 offset:54272
	ds_read_b128 v[210:213], v191 offset:55296
	ds_read_b128 v[214:217], v191 offset:56320
	global_load_lds_dwordx4 v154, s[98:99]
	s_add_i32 m0, s38, 0x2000
	s_add_u32 s36, s36, 0x80080
	s_addc_u32 s37, s37, 0
	s_add_i32 s38, s60, s41
	global_load_lds_dwordx4 v158, s[98:99]
	s_mov_b32 m0, s38
	s_nop 0
	global_load_lds_dwordx4 v154, s[36:37]
	s_add_i32 m0, s38, 0x2000
	s_nop 0
	global_load_lds_dwordx4 v158, s[36:37]
	s_mov_b32 m0, s47
	s_nop 0
	global_load_lds_dwordx4 v152, s[100:101]
	s_mov_b32 m0, s48
	s_nop 0
	global_load_lds_dwordx4 v156, s[100:101]
	s_waitcnt vmcnt(8)
	s_waitcnt lgkmcnt(0)
	s_barrier
	s_setprio 1
	s_waitcnt lgkmcnt(0)
	v_mfma_f32_16x16x32_bf16 v[60:63], v[128:131], v[176:179], v[60:63]
	v_mfma_f32_16x16x32_bf16 v[56:59], v[136:139], v[176:179], v[56:59]
	v_mfma_f32_16x16x32_bf16 v[44:47], v[128:131], v[194:197], v[44:47]
	v_mfma_f32_16x16x32_bf16 v[40:43], v[136:139], v[194:197], v[40:43]
	v_mfma_f32_16x16x32_bf16 v[28:31], v[128:131], v[202:205], v[28:31]
	v_mfma_f32_16x16x32_bf16 v[24:27], v[136:139], v[202:205], v[24:27]
	v_mfma_f32_16x16x32_bf16 v[12:15], v[128:131], v[210:213], v[12:15]
	v_mfma_f32_16x16x32_bf16 v[8:11], v[136:139], v[210:213], v[8:11]
	v_mfma_f32_16x16x32_bf16 v[60:63], v[132:135], v[180:183], v[60:63]
	v_mfma_f32_16x16x32_bf16 v[56:59], v[140:143], v[180:183], v[56:59]
	v_mfma_f32_16x16x32_bf16 v[44:47], v[132:135], v[198:201], v[44:47]
	v_mfma_f32_16x16x32_bf16 v[40:43], v[140:143], v[198:201], v[40:43]
	v_mfma_f32_16x16x32_bf16 v[28:31], v[132:135], v[206:209], v[28:31]
	v_mfma_f32_16x16x32_bf16 v[24:27], v[140:143], v[206:209], v[24:27]
	v_mfma_f32_16x16x32_bf16 v[12:15], v[132:135], v[214:217], v[12:15]
	v_mfma_f32_16x16x32_bf16 v[8:11], v[140:143], v[214:217], v[8:11]
	s_setprio 0
	s_setprio 1
	v_mfma_f32_16x16x32_bf16 v[52:55], v[144:147], v[176:179], v[52:55]
	v_mfma_f32_16x16x32_bf16 v[48:51], v[168:171], v[176:179], v[48:51]
	v_mfma_f32_16x16x32_bf16 v[36:39], v[144:147], v[194:197], v[36:39]
	v_mfma_f32_16x16x32_bf16 v[32:35], v[168:171], v[194:197], v[32:35]
	v_mfma_f32_16x16x32_bf16 v[20:23], v[144:147], v[202:205], v[20:23]
	v_mfma_f32_16x16x32_bf16 v[16:19], v[168:171], v[202:205], v[16:19]
	v_mfma_f32_16x16x32_bf16 v[4:7], v[144:147], v[210:213], v[4:7]
	v_mfma_f32_16x16x32_bf16 v[0:3], v[168:171], v[210:213], v[0:3]
	v_mfma_f32_16x16x32_bf16 v[52:55], v[148:151], v[180:183], v[52:55]
	v_mfma_f32_16x16x32_bf16 v[48:51], v[172:175], v[180:183], v[48:51]
	v_mfma_f32_16x16x32_bf16 v[36:39], v[148:151], v[198:201], v[36:39]
	v_mfma_f32_16x16x32_bf16 v[32:35], v[172:175], v[198:201], v[32:35]
	v_mfma_f32_16x16x32_bf16 v[20:23], v[148:151], v[206:209], v[20:23]
	v_mfma_f32_16x16x32_bf16 v[16:19], v[172:175], v[206:209], v[16:19]
	v_mfma_f32_16x16x32_bf16 v[4:7], v[148:151], v[214:217], v[4:7]
	v_mfma_f32_16x16x32_bf16 v[0:3], v[172:175], v[214:217], v[0:3]
	s_setprio 0
	s_barrier
	s_add_u32 s34, s34, 0x100
	s_addc_u32 s35, s35, 0
	s_add_u32 s56, s56, 0x100
	s_addc_u32 s57, s57, 0
	s_cmp_ge_i32 s58, s46
	s_mov_b32 s36, s58
	s_cbranch_scc0 .LBB0_1267

; #define PG8_STAGE(bufoff, gbase, voff) do { _Pragma("unroll") for (int _i = 0; _i < 2; ++_i) \
;         __builtin_amdgcn_global_load_lds((const unsigned*)((const char*)(gbase) + (voff)[_i]), (LAS unsigned*)(lds + (bufoff) + ldsw + _i * 8192), 16, 0, ((voff) == voffA ? AUXA : 0)); } while (0)
; #define PG8_LDA(dst, b, h) do { _Pragma("unroll") for (int m = 0; m < 4; ++m) _Pragma("unroll") for (int k = 0; k < 2; ++k) dst[m][k] = *(const LAS bf16x8*)(lds + PG8_SA(b, h) + aoff + m * 2048 + k * 1024); } while (0)
; #define PG8_LDB(dst, b, h) do { _Pragma("unroll") for (int n = 0; n < 2; ++n) _Pragma("unroll") for (int k = 0; k < 2; ++k) dst[n][k] = *(const LAS bf16x8*)(lds + PG8_SB(b, h) + boff + n * 2048 + k * 1024); } while (0)
; #define PG8_MMA(ai, bj, At, Bt) do { __builtin_amdgcn_s_setprio(1); _Pragma("unroll") for (int m = 0; m < 4; ++m) _Pragma("unroll") for (int n = 0; n < 2; ++n) _Pragma("unroll") for (int k = 0; k < 2; ++k) \
;         acc[ai][bj][m][n] = __builtin_amdgcn_mfma_f32_16x16x32_bf16(Bt[n][k], At[m][k], acc[ai][bj][m][n], 0, 0, 0); __builtin_amdgcn_s_setprio(0); } while (0)
; #define PG8_WAIT_V(n) asm volatile("s_waitcnt vmcnt(" #n ")" ::: "memory")
; #define PG8_WAIT_L(n) asm volatile("s_waitcnt lgkmcnt(" #n ")" ::: "memory")
; #define PG8_BAR __builtin_amdgcn_s_barrier()
; #define PG8_SCHED __builtin_amdgcn_sched_barrier(0)
;     ...
;             PG8_WAIT_L(0); PG8_BAR; PG8_MMA(1, 0, At, B0); PG8_MMA(1, 1, At, B1); PG8_BAR; PG8_SCHED;
;             PG8_LDB(B0, 1, 0); PG8_LDB(B1, 1, 1); PG8_SCHED; PG8_LDA(At, 1, 0); PG8_STAGE(PG8_SA(0, 1), a2 + hsA, voffA);
;             PG8_WAIT_V(8); PG8_WAIT_L(0); PG8_BAR; PG8_MMA(0, 0, At, B0); PG8_MMA(0, 1, At, B1); PG8_BAR; PG8_SCHED;
.LBB0_1355:
	s_waitcnt lgkmcnt(0)
	s_add_i32 s61, s61, 2
	s_barrier
	s_setprio 1
	s_waitcnt lgkmcnt(0)
	v_mfma_f32_16x16x32_bf16 v[60:63], v[144:147], v[184:187], v[60:63]
	v_mfma_f32_16x16x32_bf16 v[52:55], v[152:155], v[184:187], v[52:55]
	v_mfma_f32_16x16x32_bf16 v[44:47], v[144:147], v[176:179], v[44:47]
	v_mfma_f32_16x16x32_bf16 v[36:39], v[152:155], v[176:179], v[36:39]
	v_mfma_f32_16x16x32_bf16 v[28:31], v[144:147], v[168:171], v[28:31]
	v_mfma_f32_16x16x32_bf16 v[20:23], v[152:155], v[168:171], v[20:23]
	v_mfma_f32_16x16x32_bf16 v[12:15], v[144:147], v[160:163], v[12:15]
	v_mfma_f32_16x16x32_bf16 v[4:7], v[152:155], v[160:163], v[4:7]
	v_mfma_f32_16x16x32_bf16 v[60:63], v[148:151], v[188:191], v[60:63]
	v_mfma_f32_16x16x32_bf16 v[52:55], v[156:159], v[188:191], v[52:55]
	v_mfma_f32_16x16x32_bf16 v[44:47], v[148:151], v[180:183], v[44:47]
	v_mfma_f32_16x16x32_bf16 v[36:39], v[156:159], v[180:183], v[36:39]
	v_mfma_f32_16x16x32_bf16 v[28:31], v[148:151], v[172:175], v[28:31]
	v_mfma_f32_16x16x32_bf16 v[20:23], v[156:159], v[172:175], v[20:23]
	v_mfma_f32_16x16x32_bf16 v[12:15], v[148:151], v[164:167], v[12:15]
	v_mfma_f32_16x16x32_bf16 v[4:7], v[156:159], v[164:167], v[4:7]
	s_setprio 0
	s_setprio 1
	v_mfma_f32_16x16x32_bf16 v[56:59], v[128:131], v[184:187], v[56:59]
	v_mfma_f32_16x16x32_bf16 v[48:51], v[136:139], v[184:187], v[48:51]
	v_mfma_f32_16x16x32_bf16 v[40:43], v[128:131], v[176:179], v[40:43]
	v_mfma_f32_16x16x32_bf16 v[32:35], v[136:139], v[176:179], v[32:35]
	v_mfma_f32_16x16x32_bf16 v[24:27], v[128:131], v[168:171], v[24:27]
	v_mfma_f32_16x16x32_bf16 v[16:19], v[136:139], v[168:171], v[16:19]
	v_mfma_f32_16x16x32_bf16 v[8:11], v[128:131], v[160:163], v[8:11]
	v_mfma_f32_16x16x32_bf16 v[0:3], v[136:139], v[160:163], v[0:3]
	v_mfma_f32_16x16x32_bf16 v[56:59], v[132:135], v[188:191], v[56:59]
	v_mfma_f32_16x16x32_bf16 v[48:51], v[140:143], v[188:191], v[48:51]
	v_mfma_f32_16x16x32_bf16 v[40:43], v[132:135], v[180:183], v[40:43]
	v_mfma_f32_16x16x32_bf16 v[32:35], v[140:143], v[180:183], v[32:35]
	v_mfma_f32_16x16x32_bf16 v[24:27], v[132:135], v[172:175], v[24:27]
	v_mfma_f32_16x16x32_bf16 v[16:19], v[140:143], v[172:175], v[16:19]
	v_mfma_f32_16x16x32_bf16 v[8:11], v[132:135], v[164:167], v[8:11]
	v_mfma_f32_16x16x32_bf16 v[0:3], v[140:143], v[164:167], v[0:3]
	s_setprio 0
	s_barrier
	s_add_i32 s34, 0, 0x18000
	s_add_i32 s35, 0, 0x1c000
	v_add_u32_e32 v140, s34, v221
	v_add_u32_e32 v156, s35, v221
	ds_read_b128 v[128:131], v140
	ds_read_b128 v[132:135], v140 offset:1024
	ds_read_b128 v[136:139], v140 offset:2048
	ds_read_b128 v[140:143], v140 offset:3072
	ds_read_b128 v[144:147], v156
	ds_read_b128 v[148:151], v156 offset:1024
	ds_read_b128 v[152:155], v156 offset:2048
	ds_read_b128 v[156:159], v156 offset:3072
	s_add_u32 s30, s30, 0x80000
	s_addc_u32 s31, s31, 0
	s_mov_b32 m0, s46
	ds_read_b128 v[160:163], v225 offset:32768
	ds_read_b128 v[164:167], v225 offset:33792
	ds_read_b128 v[168:171], v225 offset:34816
	ds_read_b128 v[172:175], v225 offset:35840
	ds_read_b128 v[176:179], v225 offset:36864
	ds_read_b128 v[180:183], v225 offset:37888
	ds_read_b128 v[184:187], v225 offset:38912
	ds_read_b128 v[188:191], v225 offset:39936
	global_load_lds_dwordx4 v198, s[30:31]
	s_mov_b32 m0, s47
	s_nop 0
	global_load_lds_dwordx4 v194, s[30:31]
	s_waitcnt vmcnt(8)
	s_waitcnt lgkmcnt(0)
	s_barrier
	s_setprio 1
	s_waitcnt lgkmcnt(0)
	v_mfma_f32_16x16x32_bf16 v[124:127], v[128:131], v[160:163], v[124:127]
	v_mfma_f32_16x16x32_bf16 v[116:119], v[136:139], v[160:163], v[116:119]
	v_mfma_f32_16x16x32_bf16 v[108:111], v[128:131], v[168:171], v[108:111]
	v_mfma_f32_16x16x32_bf16 v[100:103], v[136:139], v[168:171], v[100:103]
	v_mfma_f32_16x16x32_bf16 v[92:95], v[128:131], v[176:179], v[92:95]
	v_mfma_f32_16x16x32_bf16 v[84:87], v[136:139], v[176:179], v[84:87]
	v_mfma_f32_16x16x32_bf16 v[76:79], v[128:131], v[184:187], v[76:79]
	v_mfma_f32_16x16x32_bf16 v[68:71], v[136:139], v[184:187], v[68:71]
	v_mfma_f32_16x16x32_bf16 v[124:127], v[132:135], v[164:167], v[124:127]
	v_mfma_f32_16x16x32_bf16 v[116:119], v[140:143], v[164:167], v[116:119]
	v_mfma_f32_16x16x32_bf16 v[108:111], v[132:135], v[172:175], v[108:111]
	v_mfma_f32_16x16x32_bf16 v[100:103], v[140:143], v[172:175], v[100:103]
	v_mfma_f32_16x16x32_bf16 v[92:95], v[132:135], v[180:183], v[92:95]
	v_mfma_f32_16x16x32_bf16 v[84:87], v[140:143], v[180:183], v[84:87]
	v_mfma_f32_16x16x32_bf16 v[76:79], v[132:135], v[188:191], v[76:79]
	v_mfma_f32_16x16x32_bf16 v[68:71], v[140:143], v[188:191], v[68:71]
	s_setprio 0
	s_setprio 1
	v_mfma_f32_16x16x32_bf16 v[120:123], v[144:147], v[160:163], v[120:123]
	v_mfma_f32_16x16x32_bf16 v[112:115], v[152:155], v[160:163], v[112:115]
	v_mfma_f32_16x16x32_bf16 v[104:107], v[144:147], v[168:171], v[104:107]
	v_mfma_f32_16x16x32_bf16 v[96:99], v[152:155], v[168:171], v[96:99]
	v_mfma_f32_16x16x32_bf16 v[88:91], v[144:147], v[176:179], v[88:91]
	v_mfma_f32_16x16x32_bf16 v[80:83], v[152:155], v[176:179], v[80:83]
	v_mfma_f32_16x16x32_bf16 v[72:75], v[144:147], v[184:187], v[72:75]
	v_mfma_f32_16x16x32_bf16 v[64:67], v[152:155], v[184:187], v[64:67]
	v_mfma_f32_16x16x32_bf16 v[120:123], v[148:151], v[164:167], v[120:123]
	v_mfma_f32_16x16x32_bf16 v[112:115], v[156:159], v[164:167], v[112:115]
	v_mfma_f32_16x16x32_bf16 v[104:107], v[148:151], v[172:175], v[104:107]
	v_mfma_f32_16x16x32_bf16 v[96:99], v[156:159], v[172:175], v[96:99]
	v_mfma_f32_16x16x32_bf16 v[88:91], v[148:151], v[180:183], v[88:91]
	v_mfma_f32_16x16x32_bf16 v[80:83], v[156:159], v[180:183], v[80:83]
	v_mfma_f32_16x16x32_bf16 v[72:75], v[148:151], v[188:191], v[72:75]
	v_mfma_f32_16x16x32_bf16 v[64:67], v[156:159], v[188:191], v[64:67]
	s_setprio 0
	s_barrier
; #define PG8_STAGE(bufoff, gbase, voff) do { _Pragma("unroll") for (int _i = 0; _i < 2; ++_i) \
;         __builtin_amdgcn_global_load_lds((const unsigned*)((const char*)(gbase) + (voff)[_i]), (LAS unsigned*)(lds + (bufoff) + ldsw + _i * 8192), 16, 0, ((voff) == voffA ? AUXA : 0)); } while (0)
; #define PG8_LDA(dst, b, h) do { _Pragma("unroll") for (int m = 0; m < 4; ++m) _Pragma("unroll") for (int k = 0; k < 2; ++k) dst[m][k] = *(const LAS bf16x8*)(lds + PG8_SA(b, h) + aoff + m * 2048 + k * 1024); } while (0)
; #define PG8_LDB(dst, b, h) do { _Pragma("unroll") for (int n = 0; n < 2; ++n) _Pragma("unroll") for (int k = 0; k < 2; ++k) dst[n][k] = *(const LAS bf16x8*)(lds + PG8_SB(b, h) + boff + n * 2048 + k * 1024); } while (0)
; #define PG8_MMA(ai, bj, At, Bt) do { __builtin_amdgcn_s_setprio(1); _Pragma("unroll") for (int m = 0; m < 4; ++m) _Pragma("unroll") for (int n = 0; n < 2; ++n) _Pragma("unroll") for (int k = 0; k < 2; ++k) \
;         acc[ai][bj][m][n] = __builtin_amdgcn_mfma_f32_16x16x32_bf16(Bt[n][k], At[m][k], acc[ai][bj][m][n], 0, 0, 0); __builtin_amdgcn_s_setprio(0); } while (0)
; #define PG8_WAIT_V(n) asm volatile("s_waitcnt vmcnt(" #n ")" ::: "memory")
; #define PG8_WAIT_L(n) asm volatile("s_waitcnt lgkmcnt(" #n ")" ::: "memory")
; #define PG8_BAR __builtin_amdgcn_s_barrier()
; #define PG8_SCHED __builtin_amdgcn_sched_barrier(0)
;     ...
;         for (int t = 0; t < nt; t += 2) {
;             const bool last = (t == nt - 2);
;             const char* a1 = cA + (size_t)(t + 1) * kstep;
;             const char* a2 = last ? nA : cA + (size_t)(t + 2) * kstep; const char* b2 = last ? nB : cB + (size_t)(t + 2) * kstep;
;             const char* a3 = a2 + kstep; const char* b3 = b2 + kstep;
;             PG8_LDB(B0, 0, 0); PG8_LDB(B1, 0, 1); PG8_SCHED; PG8_LDA(At, 0, 0); PG8_STAGE(PG8_SA(1, 1), a1 + hsA, voffA);
;             if (Epi::NPRE != 0 && last) { E.pre(sv, cur, wr, fr); PG8_WAIT_V(16); } else { PG8_WAIT_V(8); }
;     ...
;             PG8_LDA(At, 1, 1); PG8_STAGE(PG8_SB(1, 0), b3, voffB); PG8_STAGE(PG8_SB(1, 1), b3 + hsB, voffB); PG8_STAGE(PG8_SA(1, 0), a3, voffA);
;             PG8_WAIT_V(8); PG8_WAIT_L(0); PG8_BAR; PG8_MMA(1, 0, At, B0); PG8_MMA(1, 1, At, B1); PG8_BAR; PG8_SCHED;
	s_add_i32 s30, s34, s5
	s_mov_b32 m0, s30
	ds_read_b128 v[160:163], v225 offset:49152
	ds_read_b128 v[164:167], v225 offset:50176
	ds_read_b128 v[168:171], v225 offset:51200
	ds_read_b128 v[172:175], v225 offset:52224
	ds_read_b128 v[176:179], v225 offset:53248
	ds_read_b128 v[180:183], v225 offset:54272
	ds_read_b128 v[184:187], v225 offset:55296
	ds_read_b128 v[188:191], v225 offset:56320
	global_load_lds_dwordx4 v196, s[98:99]
	s_add_i32 m0, s30, 0x2000
	s_add_u32 s28, s28, 0x80080
	s_addc_u32 s29, s29, 0
	s_add_i32 s30, s35, s5
	global_load_lds_dwordx4 v192, s[98:99]
	s_mov_b32 m0, s30
	s_nop 0
	global_load_lds_dwordx4 v196, s[28:29]
	s_add_i32 m0, s30, 0x2000
	s_nop 0
	global_load_lds_dwordx4 v192, s[28:29]
	s_mov_b32 m0, s50
	s_nop 0
	global_load_lds_dwordx4 v198, s[100:101]
	s_mov_b32 m0, s51
	s_nop 0
	global_load_lds_dwordx4 v194, s[100:101]
	s_waitcnt vmcnt(8)
	s_waitcnt lgkmcnt(0)
	s_barrier
	s_setprio 1
	s_waitcnt lgkmcnt(0)
	v_mfma_f32_16x16x32_bf16 v[60:63], v[128:131], v[160:163], v[60:63]
	v_mfma_f32_16x16x32_bf16 v[52:55], v[136:139], v[160:163], v[52:55]
	v_mfma_f32_16x16x32_bf16 v[44:47], v[128:131], v[168:171], v[44:47]
	v_mfma_f32_16x16x32_bf16 v[36:39], v[136:139], v[168:171], v[36:39]
	v_mfma_f32_16x16x32_bf16 v[28:31], v[128:131], v[176:179], v[28:31]
	v_mfma_f32_16x16x32_bf16 v[20:23], v[136:139], v[176:179], v[20:23]
	v_mfma_f32_16x16x32_bf16 v[12:15], v[128:131], v[184:187], v[12:15]
	v_mfma_f32_16x16x32_bf16 v[4:7], v[136:139], v[184:187], v[4:7]
	v_mfma_f32_16x16x32_bf16 v[60:63], v[132:135], v[164:167], v[60:63]
	v_mfma_f32_16x16x32_bf16 v[52:55], v[140:143], v[164:167], v[52:55]
	v_mfma_f32_16x16x32_bf16 v[44:47], v[132:135], v[172:175], v[44:47]
	v_mfma_f32_16x16x32_bf16 v[36:39], v[140:143], v[172:175], v[36:39]
	v_mfma_f32_16x16x32_bf16 v[28:31], v[132:135], v[180:183], v[28:31]
	v_mfma_f32_16x16x32_bf16 v[20:23], v[140:143], v[180:183], v[20:23]
	v_mfma_f32_16x16x32_bf16 v[12:15], v[132:135], v[188:191], v[12:15]
	v_mfma_f32_16x16x32_bf16 v[4:7], v[140:143], v[188:191], v[4:7]
	s_setprio 0
	s_setprio 1
	v_mfma_f32_16x16x32_bf16 v[56:59], v[144:147], v[160:163], v[56:59]
	v_mfma_f32_16x16x32_bf16 v[48:51], v[152:155], v[160:163], v[48:51]
	v_mfma_f32_16x16x32_bf16 v[40:43], v[144:147], v[168:171], v[40:43]
	v_mfma_f32_16x16x32_bf16 v[32:35], v[152:155], v[168:171], v[32:35]
	v_mfma_f32_16x16x32_bf16 v[24:27], v[144:147], v[176:179], v[24:27]
	v_mfma_f32_16x16x32_bf16 v[16:19], v[152:155], v[176:179], v[16:19]
	v_mfma_f32_16x16x32_bf16 v[8:11], v[144:147], v[184:187], v[8:11]
	v_mfma_f32_16x16x32_bf16 v[0:3], v[152:155], v[184:187], v[0:3]
	v_mfma_f32_16x16x32_bf16 v[56:59], v[148:151], v[164:167], v[56:59]
	v_mfma_f32_16x16x32_bf16 v[48:51], v[156:159], v[164:167], v[48:51]
	v_mfma_f32_16x16x32_bf16 v[40:43], v[148:151], v[172:175], v[40:43]
	v_mfma_f32_16x16x32_bf16 v[32:35], v[156:159], v[172:175], v[32:35]
	v_mfma_f32_16x16x32_bf16 v[24:27], v[148:151], v[180:183], v[24:27]
	v_mfma_f32_16x16x32_bf16 v[16:19], v[156:159], v[180:183], v[16:19]
	v_mfma_f32_16x16x32_bf16 v[8:11], v[148:151], v[188:191], v[8:11]
	v_mfma_f32_16x16x32_bf16 v[0:3], v[156:159], v[188:191], v[0:3]
	s_setprio 0
	s_barrier
	s_add_u32 s26, s26, 0x100
	s_addc_u32 s27, s27, 0
	s_add_u32 s59, s59, 0x100
	s_addc_u32 s60, s60, 0
	s_cmp_ge_i32 s61, s49
	s_cbranch_scc1 .LBB0_1365
.LBB0_1356:
	ds_read_b128 v[144:147], v223
	ds_read_b128 v[148:151], v223 offset:1024
	ds_read_b128 v[152:155], v223 offset:2048
	ds_read_b128 v[156:159], v223 offset:3072
	ds_read_b128 v[128:131], v224
	ds_read_b128 v[132:135], v224 offset:1024
	ds_read_b128 v[136:139], v224 offset:2048
	ds_read_b128 v[140:143], v224 offset:3072
	s_cmp_eq_u32 s52, s61
	s_cselect_b64 s[28:29], -1, 0
	s_cmp_lg_u32 s52, s61
	s_cselect_b64 s[34:35], -1, 0
	s_add_i32 m0, s40, 0xc000
	ds_read_b128 v[184:187], v225
	ds_read_b128 v[188:191], v225 offset:1024
	ds_read_b128 v[176:179], v225 offset:2048
	ds_read_b128 v[180:183], v225 offset:3072
	ds_read_b128 v[168:171], v225 offset:4096
	ds_read_b128 v[172:175], v225 offset:5120
	ds_read_b128 v[160:163], v225 offset:6144
	ds_read_b128 v[164:167], v225 offset:7168
	global_load_lds_dwordx4 v200, s[26:27]
	s_add_i32 m0, s40, 0xe000
	s_mov_b64 s[30:31], -1
	global_load_lds_dwordx4 v202, s[26:27]
	s_and_b64 vcc, exec, s[34:35]
	s_cbranch_vccz .LBB0_1358
	s_waitcnt vmcnt(8)
	s_mov_b64 s[30:31], 0

; #define PG8_STAGE(bufoff, gbase, voff) do { _Pragma("unroll") for (int _i = 0; _i < 2; ++_i) \
;         __builtin_amdgcn_global_load_lds((const unsigned*)((const char*)(gbase) + (voff)[_i]), (LAS unsigned*)(lds + (bufoff) + ldsw + _i * 8192), 16, 0, ((voff) == voffA ? AUXA : 0)); } while (0)
; #define PG8_LDA(dst, b, h) do { _Pragma("unroll") for (int m = 0; m < 4; ++m) _Pragma("unroll") for (int k = 0; k < 2; ++k) dst[m][k] = *(const LAS bf16x8*)(lds + PG8_SA(b, h) + aoff + m * 2048 + k * 1024); } while (0)
; #define PG8_LDB(dst, b, h) do { _Pragma("unroll") for (int n = 0; n < 2; ++n) _Pragma("unroll") for (int k = 0; k < 2; ++k) dst[n][k] = *(const LAS bf16x8*)(lds + PG8_SB(b, h) + boff + n * 2048 + k * 1024); } while (0)
; #define PG8_MMA(ai, bj, At, Bt) do { __builtin_amdgcn_s_setprio(1); _Pragma("unroll") for (int m = 0; m < 4; ++m) _Pragma("unroll") for (int n = 0; n < 2; ++n) _Pragma("unroll") for (int k = 0; k < 2; ++k) \
;         acc[ai][bj][m][n] = __builtin_amdgcn_mfma_f32_16x16x32_bf16(Bt[n][k], At[m][k], acc[ai][bj][m][n], 0, 0, 0); __builtin_amdgcn_s_setprio(0); } while (0)
; #define PG8_WAIT_V(n) asm volatile("s_waitcnt vmcnt(" #n ")" ::: "memory")
; #define PG8_WAIT_L(n) asm volatile("s_waitcnt lgkmcnt(" #n ")" ::: "memory")
; #define PG8_BAR __builtin_amdgcn_s_barrier()
; #define PG8_SCHED __builtin_amdgcn_sched_barrier(0)
;     ...
;             const char* a2 = last ? nA : cA + (size_t)(t + 2) * kstep; const char* b2 = last ? nB : cB + (size_t)(t + 2) * kstep;
;             const char* a3 = a2 + kstep; const char* b3 = b2 + kstep;
;             PG8_LDB(B0, 0, 0); PG8_LDB(B1, 0, 1); PG8_SCHED; PG8_LDA(At, 0, 0); PG8_STAGE(PG8_SA(1, 1), a1 + hsA, voffA);
;             if (Epi::NPRE != 0 && last) { E.pre(sv, cur, wr, fr); PG8_WAIT_V(16); } else { PG8_WAIT_V(8); }
;             PG8_WAIT_L(0); PG8_BAR; PG8_MMA(0, 0, At, B0); PG8_MMA(0, 1, At, B1); PG8_BAR; PG8_SCHED;
;             PG8_LDA(At, 0, 1); PG8_STAGE(PG8_SB(0, 0), b2, voffB); PG8_STAGE(PG8_SB(0, 1), b2 + hsB, voffB); PG8_STAGE(PG8_SA(0, 0), a2, voffA);
;             if (Epi::NPRE != 0 && last) { PG8_WAIT_V(16); } else { PG8_WAIT_V(8); }
.LBB0_1360:
	s_add_u32 s30, s26, 0xfff80080
	s_addc_u32 s31, s27, -1
	s_waitcnt lgkmcnt(0)
	s_and_b64 s[28:29], s[28:29], exec
	s_cselect_b32 s31, s19, s31
	s_cselect_b32 s30, s21, s30
	s_cselect_b32 s29, s57, s60
	s_cselect_b32 s28, s58, s59
	s_barrier
	s_setprio 1
	s_waitcnt lgkmcnt(0)
	v_mfma_f32_16x16x32_bf16 v[124:127], v[144:147], v[184:187], v[124:127]
	v_mfma_f32_16x16x32_bf16 v[116:119], v[152:155], v[184:187], v[116:119]
	v_mfma_f32_16x16x32_bf16 v[108:111], v[144:147], v[176:179], v[108:111]
	v_mfma_f32_16x16x32_bf16 v[100:103], v[152:155], v[176:179], v[100:103]
	v_mfma_f32_16x16x32_bf16 v[92:95], v[144:147], v[168:171], v[92:95]
	v_mfma_f32_16x16x32_bf16 v[84:87], v[152:155], v[168:171], v[84:87]
	v_mfma_f32_16x16x32_bf16 v[76:79], v[144:147], v[160:163], v[76:79]
	v_mfma_f32_16x16x32_bf16 v[68:71], v[152:155], v[160:163], v[68:71]
	v_mfma_f32_16x16x32_bf16 v[124:127], v[148:151], v[188:191], v[124:127]
	v_mfma_f32_16x16x32_bf16 v[116:119], v[156:159], v[188:191], v[116:119]
	v_mfma_f32_16x16x32_bf16 v[108:111], v[148:151], v[180:183], v[108:111]
	v_mfma_f32_16x16x32_bf16 v[100:103], v[156:159], v[180:183], v[100:103]
	v_mfma_f32_16x16x32_bf16 v[92:95], v[148:151], v[172:175], v[92:95]
	v_mfma_f32_16x16x32_bf16 v[84:87], v[156:159], v[172:175], v[84:87]
	v_mfma_f32_16x16x32_bf16 v[76:79], v[148:151], v[164:167], v[76:79]
	v_mfma_f32_16x16x32_bf16 v[68:71], v[156:159], v[164:167], v[68:71]
	s_setprio 0
	s_setprio 1
	v_mfma_f32_16x16x32_bf16 v[120:123], v[128:131], v[184:187], v[120:123]
	v_mfma_f32_16x16x32_bf16 v[112:115], v[136:139], v[184:187], v[112:115]
	v_mfma_f32_16x16x32_bf16 v[104:107], v[128:131], v[176:179], v[104:107]
	v_mfma_f32_16x16x32_bf16 v[96:99], v[136:139], v[176:179], v[96:99]
	v_mfma_f32_16x16x32_bf16 v[88:91], v[128:131], v[168:171], v[88:91]
	v_mfma_f32_16x16x32_bf16 v[80:83], v[136:139], v[168:171], v[80:83]
	v_mfma_f32_16x16x32_bf16 v[72:75], v[128:131], v[160:163], v[72:75]
	v_mfma_f32_16x16x32_bf16 v[64:67], v[136:139], v[160:163], v[64:67]
	v_mfma_f32_16x16x32_bf16 v[120:123], v[132:135], v[188:191], v[120:123]
	v_mfma_f32_16x16x32_bf16 v[112:115], v[140:143], v[188:191], v[112:115]
	v_mfma_f32_16x16x32_bf16 v[104:107], v[132:135], v[180:183], v[104:107]
	v_mfma_f32_16x16x32_bf16 v[96:99], v[140:143], v[180:183], v[96:99]
	v_mfma_f32_16x16x32_bf16 v[88:91], v[132:135], v[172:175], v[88:91]
	v_mfma_f32_16x16x32_bf16 v[80:83], v[140:143], v[172:175], v[80:83]
	v_mfma_f32_16x16x32_bf16 v[72:75], v[132:135], v[164:167], v[72:75]
	v_mfma_f32_16x16x32_bf16 v[64:67], v[140:143], v[164:167], v[64:67]
	s_setprio 0
	s_barrier
	s_add_u32 s98, s28, s14
	s_addc_u32 s99, s29, s15
	s_add_u32 s100, s30, s14
	s_addc_u32 s101, s31, s15
	s_mov_b32 m0, s41
	s_add_u32 s36, s28, 0x80000
	ds_read_b128 v[184:187], v225 offset:16384
	ds_read_b128 v[188:191], v225 offset:17408
	ds_read_b128 v[176:179], v225 offset:18432
	ds_read_b128 v[180:183], v225 offset:19456
	ds_read_b128 v[168:171], v225 offset:20480
	ds_read_b128 v[172:175], v225 offset:21504
	ds_read_b128 v[160:163], v225 offset:22528
	ds_read_b128 v[164:167], v225 offset:23552
	global_load_lds_dwordx4 v196, s[28:29]
	s_mov_b32 m0, s42
	s_addc_u32 s37, s29, 0
	global_load_lds_dwordx4 v192, s[28:29]
	s_mov_b32 m0, s43
	s_nop 0
	global_load_lds_dwordx4 v196, s[36:37]
	s_mov_b32 m0, s44
	s_nop 0
	global_load_lds_dwordx4 v192, s[36:37]
	s_mov_b64 s[36:37], -1
	s_mov_b32 m0, s40
	s_and_b64 vcc, exec, s[34:35]
	global_load_lds_dwordx4 v198, s[30:31]
	s_mov_b32 m0, s45
	s_nop 0
	global_load_lds_dwordx4 v194, s[30:31]
	s_cbranch_vccz .LBB0_1362
	s_waitcnt vmcnt(8)
	s_mov_b64 s[36:37], 0

; #define PG8_STAGE(bufoff, gbase, voff) do { _Pragma("unroll") for (int _i = 0; _i < 2; ++_i) \
;         __builtin_amdgcn_global_load_lds((const unsigned*)((const char*)(gbase) + (voff)[_i]), (LAS unsigned*)(lds + (bufoff) + ldsw + _i * 8192), 16, 0, ((voff) == voffA ? AUXA : 0)); } while (0)
; #define PG8_LDA(dst, b, h) do { _Pragma("unroll") for (int m = 0; m < 4; ++m) _Pragma("unroll") for (int k = 0; k < 2; ++k) dst[m][k] = *(const LAS bf16x8*)(lds + PG8_SA(b, h) + aoff + m * 2048 + k * 1024); } while (0)
; #define PG8_LDB(dst, b, h) do { _Pragma("unroll") for (int n = 0; n < 2; ++n) _Pragma("unroll") for (int k = 0; k < 2; ++k) dst[n][k] = *(const LAS bf16x8*)(lds + PG8_SB(b, h) + boff + n * 2048 + k * 1024); } while (0)
; #define PG8_MMA(ai, bj, At, Bt) do { __builtin_amdgcn_s_setprio(1); _Pragma("unroll") for (int m = 0; m < 4; ++m) _Pragma("unroll") for (int n = 0; n < 2; ++n) _Pragma("unroll") for (int k = 0; k < 2; ++k) \
;         acc[ai][bj][m][n] = __builtin_amdgcn_mfma_f32_16x16x32_bf16(Bt[n][k], At[m][k], acc[ai][bj][m][n], 0, 0, 0); __builtin_amdgcn_s_setprio(0); } while (0)
; #define PG8_WAIT_V(n) asm volatile("s_waitcnt vmcnt(" #n ")" ::: "memory")
; #define PG8_WAIT_L(n) asm volatile("s_waitcnt lgkmcnt(" #n ")" ::: "memory")
; #define PG8_BAR __builtin_amdgcn_s_barrier()
; #define PG8_SCHED __builtin_amdgcn_sched_barrier(0)
;     ...
;             PG8_LDB(B0, 0, 0); PG8_LDB(B1, 0, 1); PG8_SCHED; PG8_LDA(At, 0, 0); PG8_STAGE(PG8_SA(1, 1), a1 + hsA, voffA);
;             if (Epi::NPRE != 0 && last) { E.pre(sv, cur, wr, fr); PG8_WAIT_V(16); } else { PG8_WAIT_V(8); }
;             PG8_WAIT_L(0); PG8_BAR; PG8_MMA(0, 0, At, B0); PG8_MMA(0, 1, At, B1); PG8_BAR; PG8_SCHED;
;             PG8_LDA(At, 0, 1); PG8_STAGE(PG8_SB(0, 0), b2, voffB); PG8_STAGE(PG8_SB(0, 1), b2 + hsB, voffB); PG8_STAGE(PG8_SA(0, 0), a2, voffA);
;             if (Epi::NPRE != 0 && last) { PG8_WAIT_V(16); } else { PG8_WAIT_V(8); }
;             PG8_WAIT_L(0); PG8_BAR; PG8_MMA(1, 0, At, B0); PG8_MMA(1, 1, At, B1); PG8_BAR; PG8_SCHED;
.LBB0_1440:
	ds_read_b128 v[144:147], v159
	ds_read_b128 v[148:151], v159 offset:1024
	ds_read_b128 v[152:155], v159 offset:2048
	ds_read_b128 v[162:165], v159 offset:3072
	ds_read_b128 v[166:169], v160
	ds_read_b128 v[170:173], v160 offset:1024
	ds_read_b128 v[174:177], v160 offset:2048
	ds_read_b128 v[178:181], v160 offset:3072
	s_add_i32 s46, s18, 2
	s_add_u32 s19, s16, 0xffea0080
	s_addc_u32 s20, s17, -1
	s_cmp_eq_u32 s36, s18
	s_cselect_b32 s18, s14, s44
	s_cselect_b32 s21, s5, s20
	s_cselect_b32 s20, s4, s19
	s_cselect_b32 s19, s15, s45
	s_add_i32 m0, s26, 0xc000
	ds_read_b128 v[182:185], v161
	ds_read_b128 v[186:189], v161 offset:1024
	ds_read_b128 v[190:193], v161 offset:2048
	ds_read_b128 v[194:197], v161 offset:3072
	ds_read_b128 v[198:201], v161 offset:4096
	ds_read_b128 v[202:205], v161 offset:5120
	ds_read_b128 v[206:209], v161 offset:6144
	ds_read_b128 v[210:213], v161 offset:7168
	global_load_lds_dwordx4 v136, s[16:17]
	s_add_i32 m0, s26, 0xe000
	s_nop 0
	global_load_lds_dwordx4 v138, s[16:17]
	s_waitcnt vmcnt(8)
	s_waitcnt lgkmcnt(0)
	s_barrier
	s_setprio 1
	s_waitcnt lgkmcnt(0)
	v_mfma_f32_16x16x32_bf16 v[124:127], v[144:147], v[182:185], v[124:127]
	v_mfma_f32_16x16x32_bf16 v[120:123], v[152:155], v[182:185], v[120:123]
	v_mfma_f32_16x16x32_bf16 v[116:119], v[144:147], v[190:193], v[116:119]
	v_mfma_f32_16x16x32_bf16 v[112:115], v[152:155], v[190:193], v[112:115]
	v_mfma_f32_16x16x32_bf16 v[104:107], v[144:147], v[198:201], v[104:107]
	v_mfma_f32_16x16x32_bf16 v[96:99], v[152:155], v[198:201], v[96:99]
	v_mfma_f32_16x16x32_bf16 v[88:91], v[144:147], v[206:209], v[88:91]
	v_mfma_f32_16x16x32_bf16 v[80:83], v[152:155], v[206:209], v[80:83]
	v_mfma_f32_16x16x32_bf16 v[124:127], v[148:151], v[186:189], v[124:127]
	v_mfma_f32_16x16x32_bf16 v[120:123], v[162:165], v[186:189], v[120:123]
	v_mfma_f32_16x16x32_bf16 v[116:119], v[148:151], v[194:197], v[116:119]
	v_mfma_f32_16x16x32_bf16 v[112:115], v[162:165], v[194:197], v[112:115]
	v_mfma_f32_16x16x32_bf16 v[104:107], v[148:151], v[202:205], v[104:107]
	v_mfma_f32_16x16x32_bf16 v[96:99], v[162:165], v[202:205], v[96:99]
	v_mfma_f32_16x16x32_bf16 v[88:91], v[148:151], v[210:213], v[88:91]
	v_mfma_f32_16x16x32_bf16 v[80:83], v[162:165], v[210:213], v[80:83]
	s_setprio 0
	s_setprio 1
	v_mfma_f32_16x16x32_bf16 v[108:111], v[166:169], v[182:185], v[108:111]
	v_mfma_f32_16x16x32_bf16 v[100:103], v[174:177], v[182:185], v[100:103]
	v_mfma_f32_16x16x32_bf16 v[92:95], v[166:169], v[190:193], v[92:95]
	v_mfma_f32_16x16x32_bf16 v[84:87], v[174:177], v[190:193], v[84:87]
	v_mfma_f32_16x16x32_bf16 v[76:79], v[166:169], v[198:201], v[76:79]
	v_mfma_f32_16x16x32_bf16 v[72:75], v[174:177], v[198:201], v[72:75]
	v_mfma_f32_16x16x32_bf16 v[68:71], v[166:169], v[206:209], v[68:71]
	v_mfma_f32_16x16x32_bf16 v[64:67], v[174:177], v[206:209], v[64:67]
	v_mfma_f32_16x16x32_bf16 v[108:111], v[170:173], v[186:189], v[108:111]
	v_mfma_f32_16x16x32_bf16 v[100:103], v[178:181], v[186:189], v[100:103]
	v_mfma_f32_16x16x32_bf16 v[92:95], v[170:173], v[194:197], v[92:95]
	v_mfma_f32_16x16x32_bf16 v[84:87], v[178:181], v[194:197], v[84:87]
	v_mfma_f32_16x16x32_bf16 v[76:79], v[170:173], v[202:205], v[76:79]
	v_mfma_f32_16x16x32_bf16 v[72:75], v[178:181], v[202:205], v[72:75]
	v_mfma_f32_16x16x32_bf16 v[68:71], v[170:173], v[210:213], v[68:71]
	v_mfma_f32_16x16x32_bf16 v[64:67], v[178:181], v[210:213], v[64:67]
	s_setprio 0
	s_barrier
	s_add_u32 s98, s18, s8
	s_addc_u32 s99, s19, s9
	s_add_u32 s100, s20, s8
	s_addc_u32 s101, s21, s9
	s_add_i32 s47, s38, s23
	s_mov_b32 m0, s47
	ds_read_b128 v[182:185], v161 offset:16384
	ds_read_b128 v[186:189], v161 offset:17408
	ds_read_b128 v[190:193], v161 offset:18432
	ds_read_b128 v[194:197], v161 offset:19456
	ds_read_b128 v[198:201], v161 offset:20480
	ds_read_b128 v[202:205], v161 offset:21504
	ds_read_b128 v[206:209], v161 offset:22528
	ds_read_b128 v[210:213], v161 offset:23552
	global_load_lds_dwordx4 v132, s[18:19]
	s_add_i32 m0, s47, 0x2000
	s_add_u32 s48, s18, 0x160000
	s_addc_u32 s49, s19, 0
	s_add_i32 s47, s39, s23
	global_load_lds_dwordx4 v128, s[18:19]
	s_mov_b32 m0, s47
	s_nop 0
	global_load_lds_dwordx4 v132, s[48:49]
	s_add_i32 m0, s47, 0x2000
	s_nop 0
	global_load_lds_dwordx4 v128, s[48:49]
	s_mov_b32 m0, s26
	s_nop 0
	global_load_lds_dwordx4 v134, s[20:21]
	s_mov_b32 m0, s27
	s_nop 0
	global_load_lds_dwordx4 v130, s[20:21]
	s_waitcnt vmcnt(8)
	s_waitcnt lgkmcnt(0)
	s_barrier
	s_setprio 1
	s_waitcnt lgkmcnt(0)
	v_mfma_f32_16x16x32_bf16 v[60:63], v[144:147], v[182:185], v[60:63]
	v_mfma_f32_16x16x32_bf16 v[56:59], v[152:155], v[182:185], v[56:59]
	v_mfma_f32_16x16x32_bf16 v[52:55], v[144:147], v[190:193], v[52:55]
	v_mfma_f32_16x16x32_bf16 v[48:51], v[152:155], v[190:193], v[48:51]
	v_mfma_f32_16x16x32_bf16 v[40:43], v[144:147], v[198:201], v[40:43]
	v_mfma_f32_16x16x32_bf16 v[32:35], v[152:155], v[198:201], v[32:35]
	v_mfma_f32_16x16x32_bf16 v[24:27], v[144:147], v[206:209], v[24:27]
	v_mfma_f32_16x16x32_bf16 v[16:19], v[152:155], v[206:209], v[16:19]
	v_mfma_f32_16x16x32_bf16 v[60:63], v[148:151], v[186:189], v[60:63]
	v_mfma_f32_16x16x32_bf16 v[56:59], v[162:165], v[186:189], v[56:59]
	v_mfma_f32_16x16x32_bf16 v[52:55], v[148:151], v[194:197], v[52:55]
	v_mfma_f32_16x16x32_bf16 v[48:51], v[162:165], v[194:197], v[48:51]
	v_mfma_f32_16x16x32_bf16 v[40:43], v[148:151], v[202:205], v[40:43]
	v_mfma_f32_16x16x32_bf16 v[32:35], v[162:165], v[202:205], v[32:35]
	v_mfma_f32_16x16x32_bf16 v[24:27], v[148:151], v[210:213], v[24:27]
	v_mfma_f32_16x16x32_bf16 v[16:19], v[162:165], v[210:213], v[16:19]
	s_setprio 0
	s_setprio 1
	v_mfma_f32_16x16x32_bf16 v[44:47], v[166:169], v[182:185], v[44:47]
	v_mfma_f32_16x16x32_bf16 v[36:39], v[174:177], v[182:185], v[36:39]
	v_mfma_f32_16x16x32_bf16 v[28:31], v[166:169], v[190:193], v[28:31]
	v_mfma_f32_16x16x32_bf16 v[20:23], v[174:177], v[190:193], v[20:23]
	v_mfma_f32_16x16x32_bf16 v[12:15], v[166:169], v[198:201], v[12:15]
	v_mfma_f32_16x16x32_bf16 v[8:11], v[174:177], v[198:201], v[8:11]
	v_mfma_f32_16x16x32_bf16 v[4:7], v[166:169], v[206:209], v[4:7]
	v_mfma_f32_16x16x32_bf16 v[0:3], v[174:177], v[206:209], v[0:3]
	v_mfma_f32_16x16x32_bf16 v[44:47], v[170:173], v[186:189], v[44:47]
	v_mfma_f32_16x16x32_bf16 v[36:39], v[178:181], v[186:189], v[36:39]
	v_mfma_f32_16x16x32_bf16 v[28:31], v[170:173], v[194:197], v[28:31]
	v_mfma_f32_16x16x32_bf16 v[20:23], v[178:181], v[194:197], v[20:23]
	v_mfma_f32_16x16x32_bf16 v[12:15], v[170:173], v[202:205], v[12:15]
	v_mfma_f32_16x16x32_bf16 v[8:11], v[178:181], v[202:205], v[8:11]
	v_mfma_f32_16x16x32_bf16 v[4:7], v[170:173], v[210:213], v[4:7]
	v_mfma_f32_16x16x32_bf16 v[0:3], v[178:181], v[210:213], v[0:3]
	s_setprio 0
	s_barrier
; #define PG8_STAGE(bufoff, gbase, voff) do { _Pragma("unroll") for (int _i = 0; _i < 2; ++_i) \
;         __builtin_amdgcn_global_load_lds((const unsigned*)((const char*)(gbase) + (voff)[_i]), (LAS unsigned*)(lds + (bufoff) + ldsw + _i * 8192), 16, 0, ((voff) == voffA ? AUXA : 0)); } while (0)
; #define PG8_LDA(dst, b, h) do { _Pragma("unroll") for (int m = 0; m < 4; ++m) _Pragma("unroll") for (int k = 0; k < 2; ++k) dst[m][k] = *(const LAS bf16x8*)(lds + PG8_SA(b, h) + aoff + m * 2048 + k * 1024); } while (0)
; #define PG8_LDB(dst, b, h) do { _Pragma("unroll") for (int n = 0; n < 2; ++n) _Pragma("unroll") for (int k = 0; k < 2; ++k) dst[n][k] = *(const LAS bf16x8*)(lds + PG8_SB(b, h) + boff + n * 2048 + k * 1024); } while (0)
; #define PG8_MMA(ai, bj, At, Bt) do { __builtin_amdgcn_s_setprio(1); _Pragma("unroll") for (int m = 0; m < 4; ++m) _Pragma("unroll") for (int n = 0; n < 2; ++n) _Pragma("unroll") for (int k = 0; k < 2; ++k) \
;         acc[ai][bj][m][n] = __builtin_amdgcn_mfma_f32_16x16x32_bf16(Bt[n][k], At[m][k], acc[ai][bj][m][n], 0, 0, 0); __builtin_amdgcn_s_setprio(0); } while (0)
; #define PG8_WAIT_V(n) asm volatile("s_waitcnt vmcnt(" #n ")" ::: "memory")
; #define PG8_WAIT_L(n) asm volatile("s_waitcnt lgkmcnt(" #n ")" ::: "memory")
; #define PG8_BAR __builtin_amdgcn_s_barrier()
; #define PG8_SCHED __builtin_amdgcn_sched_barrier(0)
;     ...
;             PG8_LDB(B0, 1, 0); PG8_LDB(B1, 1, 1); PG8_SCHED; PG8_LDA(At, 1, 0); PG8_STAGE(PG8_SA(0, 1), a2 + hsA, voffA);
;             PG8_WAIT_V(8); PG8_WAIT_L(0); PG8_BAR; PG8_MMA(0, 0, At, B0); PG8_MMA(0, 1, At, B1); PG8_BAR; PG8_SCHED;
;             PG8_LDA(At, 1, 1); PG8_STAGE(PG8_SB(1, 0), b3, voffB); PG8_STAGE(PG8_SB(1, 1), b3 + hsB, voffB); PG8_STAGE(PG8_SA(1, 0), a3, voffA);
;             PG8_WAIT_V(8); PG8_WAIT_L(0); PG8_BAR; PG8_MMA(1, 0, At, B0); PG8_MMA(1, 1, At, B1); PG8_BAR; PG8_SCHED;
	s_add_i32 s47, 0, 0x18000
	s_add_i32 s48, 0, 0x1c000
	v_add_u32_e32 v162, s47, v157
	v_add_u32_e32 v178, s48, v157
	ds_read_b128 v[144:147], v162
	ds_read_b128 v[148:151], v162 offset:1024
	ds_read_b128 v[152:155], v162 offset:2048
	ds_read_b128 v[162:165], v162 offset:3072
	ds_read_b128 v[166:169], v178
	ds_read_b128 v[170:173], v178 offset:1024
	ds_read_b128 v[174:177], v178 offset:2048
	ds_read_b128 v[178:181], v178 offset:3072
	s_add_u32 s20, s20, 0x160000
	s_addc_u32 s21, s21, 0
	s_mov_b32 m0, s28
	ds_read_b128 v[182:185], v161 offset:32768
	ds_read_b128 v[186:189], v161 offset:33792
	ds_read_b128 v[190:193], v161 offset:34816
	ds_read_b128 v[194:197], v161 offset:35840
	ds_read_b128 v[198:201], v161 offset:36864
	ds_read_b128 v[202:205], v161 offset:37888
	ds_read_b128 v[206:209], v161 offset:38912
	ds_read_b128 v[210:213], v161 offset:39936
	global_load_lds_dwordx4 v134, s[20:21]
	s_mov_b32 m0, s29
	s_nop 0
	global_load_lds_dwordx4 v130, s[20:21]
	s_waitcnt vmcnt(8)
	s_waitcnt lgkmcnt(0)
	s_barrier
	s_setprio 1
	s_waitcnt lgkmcnt(0)
	v_mfma_f32_16x16x32_bf16 v[124:127], v[144:147], v[182:185], v[124:127]
	v_mfma_f32_16x16x32_bf16 v[120:123], v[152:155], v[182:185], v[120:123]
	v_mfma_f32_16x16x32_bf16 v[116:119], v[144:147], v[190:193], v[116:119]
	v_mfma_f32_16x16x32_bf16 v[112:115], v[152:155], v[190:193], v[112:115]
	v_mfma_f32_16x16x32_bf16 v[104:107], v[144:147], v[198:201], v[104:107]
	v_mfma_f32_16x16x32_bf16 v[96:99], v[152:155], v[198:201], v[96:99]
	v_mfma_f32_16x16x32_bf16 v[88:91], v[144:147], v[206:209], v[88:91]
	v_mfma_f32_16x16x32_bf16 v[80:83], v[152:155], v[206:209], v[80:83]
	v_mfma_f32_16x16x32_bf16 v[124:127], v[148:151], v[186:189], v[124:127]
	v_mfma_f32_16x16x32_bf16 v[120:123], v[162:165], v[186:189], v[120:123]
	v_mfma_f32_16x16x32_bf16 v[116:119], v[148:151], v[194:197], v[116:119]
	v_mfma_f32_16x16x32_bf16 v[112:115], v[162:165], v[194:197], v[112:115]
	v_mfma_f32_16x16x32_bf16 v[104:107], v[148:151], v[202:205], v[104:107]
	v_mfma_f32_16x16x32_bf16 v[96:99], v[162:165], v[202:205], v[96:99]
	v_mfma_f32_16x16x32_bf16 v[88:91], v[148:151], v[210:213], v[88:91]
	v_mfma_f32_16x16x32_bf16 v[80:83], v[162:165], v[210:213], v[80:83]
	s_setprio 0
	s_setprio 1
	v_mfma_f32_16x16x32_bf16 v[108:111], v[166:169], v[182:185], v[108:111]
	v_mfma_f32_16x16x32_bf16 v[100:103], v[174:177], v[182:185], v[100:103]
	v_mfma_f32_16x16x32_bf16 v[92:95], v[166:169], v[190:193], v[92:95]
	v_mfma_f32_16x16x32_bf16 v[84:87], v[174:177], v[190:193], v[84:87]
	v_mfma_f32_16x16x32_bf16 v[76:79], v[166:169], v[198:201], v[76:79]
	v_mfma_f32_16x16x32_bf16 v[72:75], v[174:177], v[198:201], v[72:75]
	v_mfma_f32_16x16x32_bf16 v[68:71], v[166:169], v[206:209], v[68:71]
	v_mfma_f32_16x16x32_bf16 v[64:67], v[174:177], v[206:209], v[64:67]
	v_mfma_f32_16x16x32_bf16 v[108:111], v[170:173], v[186:189], v[108:111]
	v_mfma_f32_16x16x32_bf16 v[100:103], v[178:181], v[186:189], v[100:103]
	v_mfma_f32_16x16x32_bf16 v[92:95], v[170:173], v[194:197], v[92:95]
	v_mfma_f32_16x16x32_bf16 v[84:87], v[178:181], v[194:197], v[84:87]
	v_mfma_f32_16x16x32_bf16 v[76:79], v[170:173], v[202:205], v[76:79]
	v_mfma_f32_16x16x32_bf16 v[72:75], v[178:181], v[202:205], v[72:75]
	v_mfma_f32_16x16x32_bf16 v[68:71], v[170:173], v[210:213], v[68:71]
	v_mfma_f32_16x16x32_bf16 v[64:67], v[178:181], v[210:213], v[64:67]
	s_setprio 0
	s_barrier
	s_add_i32 s20, s47, s23
	s_mov_b32 m0, s20
	ds_read_b128 v[182:185], v161 offset:49152
	ds_read_b128 v[186:189], v161 offset:50176
	ds_read_b128 v[190:193], v161 offset:51200
	ds_read_b128 v[194:197], v161 offset:52224
	ds_read_b128 v[198:201], v161 offset:53248
	ds_read_b128 v[202:205], v161 offset:54272
	ds_read_b128 v[206:209], v161 offset:55296
	ds_read_b128 v[210:213], v161 offset:56320
	global_load_lds_dwordx4 v132, s[98:99]
	s_add_i32 m0, s20, 0x2000
	s_add_u32 s18, s18, 0x160080
	s_addc_u32 s19, s19, 0
	s_add_i32 s20, s48, s23
	global_load_lds_dwordx4 v128, s[98:99]
	s_mov_b32 m0, s20
	s_nop 0
	global_load_lds_dwordx4 v132, s[18:19]
	s_add_i32 m0, s20, 0x2000
	s_nop 0
	global_load_lds_dwordx4 v128, s[18:19]
	s_mov_b32 m0, s34
	s_nop 0
	global_load_lds_dwordx4 v134, s[100:101]
	s_mov_b32 m0, s35
	s_nop 0
	global_load_lds_dwordx4 v130, s[100:101]
	s_waitcnt vmcnt(8)
	s_waitcnt lgkmcnt(0)
	s_barrier
; #define PG8_MMA(ai, bj, At, Bt) do { __builtin_amdgcn_s_setprio(1); _Pragma("unroll") for (int m = 0; m < 4; ++m) _Pragma("unroll") for (int n = 0; n < 2; ++n) _Pragma("unroll") for (int k = 0; k < 2; ++k) \
;         acc[ai][bj][m][n] = __builtin_amdgcn_mfma_f32_16x16x32_bf16(Bt[n][k], At[m][k], acc[ai][bj][m][n], 0, 0, 0); __builtin_amdgcn_s_setprio(0); } while (0)
; #define PG8_WAIT_V(n) asm volatile("s_waitcnt vmcnt(" #n ")" ::: "memory")
; #define PG8_WAIT_L(n) asm volatile("s_waitcnt lgkmcnt(" #n ")" ::: "memory")
; #define PG8_BAR __builtin_amdgcn_s_barrier()
; #define PG8_SCHED __builtin_amdgcn_sched_barrier(0)
;     ...
;             PG8_WAIT_V(8); PG8_WAIT_L(0); PG8_BAR; PG8_MMA(1, 0, At, B0); PG8_MMA(1, 1, At, B1); PG8_BAR; PG8_SCHED;
;         }
;     __device__ __forceinline__ void operator()(const Acc& acc, const Unit& u, int wr, int wc, int fr, int fq, const float (&sv8)[8]) const {
;     ...
;                     const f32x4 y0 = xr[m][bj][0] + acc[ai][bj][m][0] * scale, y1 = xr[m][bj][1] + acc[ai][bj][m][1] * scale;
	s_setprio 1
	s_waitcnt lgkmcnt(0)
	v_mfma_f32_16x16x32_bf16 v[60:63], v[144:147], v[182:185], v[60:63]
	v_mfma_f32_16x16x32_bf16 v[56:59], v[152:155], v[182:185], v[56:59]
	v_mfma_f32_16x16x32_bf16 v[52:55], v[144:147], v[190:193], v[52:55]
	v_mfma_f32_16x16x32_bf16 v[48:51], v[152:155], v[190:193], v[48:51]
	v_mfma_f32_16x16x32_bf16 v[40:43], v[144:147], v[198:201], v[40:43]
	v_mfma_f32_16x16x32_bf16 v[32:35], v[152:155], v[198:201], v[32:35]
	v_mfma_f32_16x16x32_bf16 v[24:27], v[144:147], v[206:209], v[24:27]
	v_mfma_f32_16x16x32_bf16 v[16:19], v[152:155], v[206:209], v[16:19]
	v_mfma_f32_16x16x32_bf16 v[60:63], v[148:151], v[186:189], v[60:63]
	v_mfma_f32_16x16x32_bf16 v[56:59], v[162:165], v[186:189], v[56:59]
	v_mfma_f32_16x16x32_bf16 v[52:55], v[148:151], v[194:197], v[52:55]
	v_mfma_f32_16x16x32_bf16 v[48:51], v[162:165], v[194:197], v[48:51]
	v_mfma_f32_16x16x32_bf16 v[40:43], v[148:151], v[202:205], v[40:43]
	v_mfma_f32_16x16x32_bf16 v[32:35], v[162:165], v[202:205], v[32:35]
	v_mfma_f32_16x16x32_bf16 v[24:27], v[148:151], v[210:213], v[24:27]
	v_mfma_f32_16x16x32_bf16 v[16:19], v[162:165], v[210:213], v[16:19]
	s_setprio 0
	s_setprio 1
	v_mfma_f32_16x16x32_bf16 v[44:47], v[166:169], v[182:185], v[44:47]
	v_mfma_f32_16x16x32_bf16 v[36:39], v[174:177], v[182:185], v[36:39]
	v_mfma_f32_16x16x32_bf16 v[28:31], v[166:169], v[190:193], v[28:31]
	v_mfma_f32_16x16x32_bf16 v[20:23], v[174:177], v[190:193], v[20:23]
	v_mfma_f32_16x16x32_bf16 v[12:15], v[166:169], v[198:201], v[12:15]
	v_mfma_f32_16x16x32_bf16 v[8:11], v[174:177], v[198:201], v[8:11]
	v_mfma_f32_16x16x32_bf16 v[4:7], v[166:169], v[206:209], v[4:7]
	v_mfma_f32_16x16x32_bf16 v[0:3], v[174:177], v[206:209], v[0:3]
	v_mfma_f32_16x16x32_bf16 v[44:47], v[170:173], v[186:189], v[44:47]
	v_mfma_f32_16x16x32_bf16 v[36:39], v[178:181], v[186:189], v[36:39]
	v_mfma_f32_16x16x32_bf16 v[28:31], v[170:173], v[194:197], v[28:31]
	v_mfma_f32_16x16x32_bf16 v[20:23], v[178:181], v[194:197], v[20:23]
	v_mfma_f32_16x16x32_bf16 v[12:15], v[170:173], v[202:205], v[12:15]
	v_mfma_f32_16x16x32_bf16 v[8:11], v[178:181], v[202:205], v[8:11]
	v_mfma_f32_16x16x32_bf16 v[4:7], v[170:173], v[210:213], v[4:7]
	v_mfma_f32_16x16x32_bf16 v[0:3], v[178:181], v[210:213], v[0:3]
	s_setprio 0
	s_barrier
	s_add_u32 s16, s16, 0x100
	s_addc_u32 s17, s17, 0
	s_add_u32 s44, s44, 0x100
	s_addc_u32 s45, s45, 0
	s_cmp_ge_i32 s46, s31
	s_mov_b32 s18, s46
	s_cbranch_scc0 .LBB0_1440
	v_pk_mul_f32 v[126:127], v[126:127], 0.5 op_sel_hi:[1,0]
	v_pk_mul_f32 v[146:147], v[124:125], 0.5 op_sel_hi:[1,0]
	v_pk_mul_f32 v[144:145], v[122:123], 0.5 op_sel_hi:[1,0]
	v_pk_mul_f32 v[124:125], v[120:121], 0.5 op_sel_hi:[1,0]
	v_pk_mul_f32 v[154:155], v[110:111], 0.5 op_sel_hi:[1,0]
	v_pk_mul_f32 v[152:153], v[108:109], 0.5 op_sel_hi:[1,0]
	v_pk_mul_f32 v[150:151], v[102:103], 0.5 op_sel_hi:[1,0]
	v_pk_mul_f32 v[148:149], v[100:101], 0.5 op_sel_hi:[1,0]
	v_pk_mul_f32 v[118:119], v[118:119], 0.5 op_sel_hi:[1,0]
	v_pk_mul_f32 v[116:117], v[116:117], 0.5 op_sel_hi:[1,0]
	v_pk_mul_f32 v[110:111], v[114:115], 0.5 op_sel_hi:[1,0]
	v_pk_mul_f32 v[108:109], v[112:113], 0.5 op_sel_hi:[1,0]
	v_pk_mul_f32 v[122:123], v[94:95], 0.5 op_sel_hi:[1,0]
	v_pk_mul_f32 v[120:121], v[92:93], 0.5 op_sel_hi:[1,0]
	v_pk_mul_f32 v[114:115], v[86:87], 0.5 op_sel_hi:[1,0]
	v_pk_mul_f32 v[112:113], v[84:85], 0.5 op_sel_hi:[1,0]
	v_pk_mul_f32 v[102:103], v[106:107], 0.5 op_sel_hi:[1,0]
	v_pk_mul_f32 v[100:101], v[104:105], 0.5 op_sel_hi:[1,0]
	v_pk_mul_f32 v[94:95], v[98:99], 0.5 op_sel_hi:[1,0]
	v_pk_mul_f32 v[92:93], v[96:97], 0.5 op_sel_hi:[1,0]
	v_pk_mul_f32 v[106:107], v[78:79], 0.5 op_sel_hi:[1,0]
	v_pk_mul_f32 v[104:105], v[76:77], 0.5 op_sel_hi:[1,0]
	v_pk_mul_f32 v[98:99], v[74:75], 0.5 op_sel_hi:[1,0]
	v_pk_mul_f32 v[96:97], v[72:73], 0.5 op_sel_hi:[1,0]
	v_pk_mul_f32 v[86:87], v[90:91], 0.5 op_sel_hi:[1,0]
	v_pk_mul_f32 v[84:85], v[88:89], 0.5 op_sel_hi:[1,0]
	v_pk_mul_f32 v[78:79], v[82:83], 0.5 op_sel_hi:[1,0]
	v_pk_mul_f32 v[76:77], v[80:81], 0.5 op_sel_hi:[1,0]
	v_pk_mul_f32 v[90:91], v[70:71], 0.5 op_sel_hi:[1,0]
	v_pk_mul_f32 v[88:89], v[68:69], 0.5 op_sel_hi:[1,0]
	v_pk_mul_f32 v[82:83], v[66:67], 0.5 op_sel_hi:[1,0]
	v_pk_mul_f32 v[80:81], v[64:65], 0.5 op_sel_hi:[1,0]
	v_pk_mul_f32 v[66:67], v[62:63], 0.5 op_sel_hi:[1,0]
	v_pk_mul_f32 v[64:65], v[60:61], 0.5 op_sel_hi:[1,0]
	v_pk_mul_f32 v[62:63], v[58:59], 0.5 op_sel_hi:[1,0]
	v_pk_mul_f32 v[60:61], v[56:57], 0.5 op_sel_hi:[1,0]
	v_pk_mul_f32 v[74:75], v[46:47], 0.5 op_sel_hi:[1,0]
	v_pk_mul_f32 v[72:73], v[44:45], 0.5 op_sel_hi:[1,0]
	v_pk_mul_f32 v[70:71], v[38:39], 0.5 op_sel_hi:[1,0]
	v_pk_mul_f32 v[68:69], v[36:37], 0.5 op_sel_hi:[1,0]
	v_pk_mul_f32 v[54:55], v[54:55], 0.5 op_sel_hi:[1,0]
	v_pk_mul_f32 v[52:53], v[52:53], 0.5 op_sel_hi:[1,0]
	v_pk_mul_f32 v[46:47], v[50:51], 0.5 op_sel_hi:[1,0]
	v_pk_mul_f32 v[44:45], v[48:49], 0.5 op_sel_hi:[1,0]
	v_pk_mul_f32 v[58:59], v[30:31], 0.5 op_sel_hi:[1,0]
	v_pk_mul_f32 v[56:57], v[28:29], 0.5 op_sel_hi:[1,0]
	v_pk_mul_f32 v[50:51], v[22:23], 0.5 op_sel_hi:[1,0]
	v_pk_mul_f32 v[48:49], v[20:21], 0.5 op_sel_hi:[1,0]
	v_pk_mul_f32 v[30:31], v[42:43], 0.5 op_sel_hi:[1,0]
	v_pk_mul_f32 v[28:29], v[40:41], 0.5 op_sel_hi:[1,0]
	v_pk_mul_f32 v[22:23], v[34:35], 0.5 op_sel_hi:[1,0]
	v_pk_mul_f32 v[20:21], v[32:33], 0.5 op_sel_hi:[1,0]
	v_pk_mul_f32 v[38:39], v[14:15], 0.5 op_sel_hi:[1,0]
	v_pk_mul_f32 v[36:37], v[12:13], 0.5 op_sel_hi:[1,0]
	v_pk_mul_f32 v[34:35], v[10:11], 0.5 op_sel_hi:[1,0]
	v_pk_mul_f32 v[32:33], v[8:9], 0.5 op_sel_hi:[1,0]
	v_pk_mul_f32 v[14:15], v[26:27], 0.5 op_sel_hi:[1,0]
	v_pk_mul_f32 v[12:13], v[24:25], 0.5 op_sel_hi:[1,0]
	v_pk_mul_f32 v[10:11], v[18:19], 0.5 op_sel_hi:[1,0]
	v_pk_mul_f32 v[8:9], v[16:17], 0.5 op_sel_hi:[1,0]
	v_pk_mul_f32 v[6:7], v[6:7], 0.5 op_sel_hi:[1,0]
	v_pk_mul_f32 v[4:5], v[4:5], 0.5 op_sel_hi:[1,0]
	v_pk_mul_f32 v[2:3], v[2:3], 0.5 op_sel_hi:[1,0]
	v_pk_mul_f32 v[0:1], v[0:1], 0.5 op_sel_hi:[1,0]

; __global__ void __launch_bounds__(512, 2) fwd_megakernel(Args a) {
	.amdhsa_kernel _Z14fwd_megakernel4Args
		.amdhsa_group_segment_fixed_size 0
		.amdhsa_private_segment_fixed_size 0
		.amdhsa_kernarg_size 488
		.amdhsa_user_sgpr_count 2
		.amdhsa_user_sgpr_dispatch_ptr 0
		.amdhsa_user_sgpr_queue_ptr 0
		.amdhsa_user_sgpr_kernarg_segment_ptr 1
		.amdhsa_user_sgpr_dispatch_id 0
		.amdhsa_user_sgpr_kernarg_preload_length 0
		.amdhsa_user_sgpr_kernarg_preload_offset 0
		.amdhsa_user_sgpr_private_segment_size 0
		.amdhsa_uses_dynamic_stack 0
		.amdhsa_enable_private_segment 0
		.amdhsa_system_sgpr_workgroup_id_x 1
		.amdhsa_system_sgpr_workgroup_id_y 0
		.amdhsa_system_sgpr_workgroup_id_z 0
		.amdhsa_system_sgpr_workgroup_info 0
		.amdhsa_system_vgpr_workitem_id 2
		.amdhsa_next_free_vgpr 252
		.amdhsa_next_free_sgpr 102
		.amdhsa_accum_offset 252
		.amdhsa_reserve_vcc 1
		.amdhsa_float_round_mode_32 0
		.amdhsa_float_round_mode_16_64 0
		.amdhsa_float_denorm_mode_32 3
		.amdhsa_float_denorm_mode_16_64 3
		.amdhsa_dx10_clamp 1
		.amdhsa_ieee_mode 1
		.amdhsa_fp16_overflow 0
		.amdhsa_tg_split 0
		.amdhsa_exception_fp_ieee_invalid_op 0
		.amdhsa_exception_fp_denorm_src 0
		.amdhsa_exception_fp_ieee_div_zero 0
		.amdhsa_exception_fp_ieee_overflow 0
		.amdhsa_exception_fp_ieee_underflow 0
		.amdhsa_exception_fp_ieee_inexact 0
		.amdhsa_exception_int_div_zero 0
	.end_amdhsa_kernel

; __global__ void __launch_bounds__(512, 2) fwd_megakernel(Args a) {
.Lfunc_end0:
	.size	_Z14fwd_megakernel4Args, .Lfunc_end0-_Z14fwd_megakernel4Args
	.set _Z14fwd_megakernel4Args.num_vgpr, 252
	.set _Z14fwd_megakernel4Args.num_agpr, 0
	.set _Z14fwd_megakernel4Args.numbered_sgpr, 102
	.set _Z14fwd_megakernel4Args.num_named_barrier, 0
	.set _Z14fwd_megakernel4Args.private_seg_size, 0
	.set _Z14fwd_megakernel4Args.uses_vcc, 1
	.set _Z14fwd_megakernel4Args.uses_flat_scratch, 0
	.set _Z14fwd_megakernel4Args.has_dyn_sized_stack, 0
	.set _Z14fwd_megakernel4Args.has_recursion, 0
	.set _Z14fwd_megakernel4Args.has_indirect_call, 0

; __global__ void __launch_bounds__(512, 2) fwd_megakernel(Args a) {
amdhsa.kernels:
  - .agpr_count:     0
    .args:
      - .offset:         0
        .size:           232
        .value_kind:     by_value
      - .offset:         232
        .size:           4
        .value_kind:     hidden_block_count_x
      - .offset:         236
        .size:           4
        .value_kind:     hidden_block_count_y
      - .offset:         240
        .size:           4
        .value_kind:     hidden_block_count_z
      - .offset:         244
        .size:           2
        .value_kind:     hidden_group_size_x
      - .offset:         246
        .size:           2
        .value_kind:     hidden_group_size_y
      - .offset:         248
        .size:           2
        .value_kind:     hidden_group_size_z
      - .offset:         250
        .size:           2
        .value_kind:     hidden_remainder_x
      - .offset:         252
        .size:           2
        .value_kind:     hidden_remainder_y
      - .offset:         254
        .size:           2
        .value_kind:     hidden_remainder_z
      - .offset:         272
        .size:           8
        .value_kind:     hidden_global_offset_x
      - .offset:         280
        .size:           8
        .value_kind:     hidden_global_offset_y
      - .offset:         288
        .size:           8
        .value_kind:     hidden_global_offset_z
      - .offset:         296
        .size:           2
        .value_kind:     hidden_grid_dims
      - .offset:         320
        .size:           8
        .value_kind:     hidden_multigrid_sync_arg
      - .offset:         352
        .size:           4
        .value_kind:     hidden_dynamic_lds_size
    .group_segment_fixed_size: 0
    .kernarg_segment_align: 8
    .kernarg_segment_size: 488
    .language:       OpenCL C
    .language_version:
      - 2
      - 0
    .max_flat_workgroup_size: 512
    .name:           _Z14fwd_megakernel4Args
    .private_segment_fixed_size: 0
    .sgpr_count:     108
    .sgpr_spill_count: 59
    .symbol:         _Z14fwd_megakernel4Args.kd
    .uniform_work_group_size: 1
    .uses_dynamic_stack: false
    .vgpr_count:     252
    .vgpr_spill_count: 0
    .wavefront_size: 64
